# v49 + retention state scan with 16-byte row-slice accesses + FFN-down sample-row k-loop prefetched a chunk ahead + one grid barrier dropped (M7 g0): all individually validated region rewrites stacked
# speedup vs baseline: 1.0019x; 1.0019x over previous
; __device__ __forceinline__ unsigned cvt_pk_bf16(float lo, float hi) { unsigned r; asm volatile("v_cvt_pk_bf16_f32 %0, %1, %2" : "=v"(r) : "v"(lo), "v"(hi)); return r; }
; __global__ void __launch_bounds__(512, 2) hse_fwd(Params P) {
;     ...
;                     const int u = it - n_mla - n_band, sl = u & 15, h = (u >> 4) & 7, bl = u >> 7; const int idx = sl * 512 + tid;
;                     const bf16_t* p = rets + (size_t)((bl * 8 + h) * 128) * 8192 + idx; bf16_t* pb = retb + (size_t)((bl * 8 + h) * 128) * 8192 + idx; const float g64 = __builtin_amdgcn_exp2f(64.0f * lg2_gamma(h)); float run = 0.f;
;                     float v[32];
; #pragma unroll
;                     for (int j = 0; j < 32; ++j) v[j] = __uint_as_float((unsigned)p[(size_t)j * 8192] << 16);
; #pragma unroll 1
;                     for (int c = 0; c < 128; c += 32) { float vn[32]; const int cn = c + 32 < 128 ? c + 32 : c;
; #pragma unroll
;                         for (int j = 0; j < 32; ++j) vn[j] = __uint_as_float((unsigned)p[(size_t)(cn + j) * 8192] << 16);
; #pragma unroll
;                         for (int j = 0; j < 32; j += 2) {
;                             const float r0 = run; run = g64 * run + v[j]; const float r1 = run; run = g64 * run + v[j + 1];
;                             const bool odd = lane & 1; const float mine = odd ? r1 : r0, send = odd ? r0 : r1;
;                             const float recv = __int_as_float(__builtin_amdgcn_mov_dpp(__float_as_int(send), 0xB1, 0xF, 0xF, false));
;                             const unsigned w = odd ? cvt_pk_bf16(recv, mine) : cvt_pk_bf16(mine, recv);
;                             *(unsigned*)(pb - (lane & 1) + (size_t)(c + j + (odd ? 1 : 0)) * 8192) = w; }
; #pragma unroll
;                         for (int j = 0; j < 32; ++j) v[j] = vn[j]; }
.LBB0_4959:
	s_add_i32 s0, s85, 0xfffffd00
	s_lshr_b32 s17, s0, 7
	s_lshl_b32 s0, s85, 9
	s_and_b32 s0, s0, 0x1e00
	v_add_u32_e32 v0, s0, v184
	s_lshl_b32 s0, s17, 10
	s_lshl_b32 s1, s16, 7
	s_or_b32 s26, s0, s1
	s_lshl_b64 s[0:1], s[26:27], 14
	s_add_u32 s0, s72, s0
	s_addc_u32 s1, s73, s1
	v_ashrrev_i32_e32 v1, 31, v0
	v_lshl_add_u64 v[2:3], v[0:1], 1, s[0:1]
	v_readlane_b32 s14, v253, 8
	s_cmpk_lt_u32 s14, 0x40
	s_cbranch_scc0 .Lscan_idle
	s_lshl_b32 s14, s85, 9
	s_and_b32 s14, s14, 0x1e00
	v_lshlrev_b32_e32 v0, 3, v184
	v_add_u32_e32 v0, s14, v0
	v_lshlrev_b32_e32 v1, 1, v0
	v_exp_f32_e32 v8, v4
	s_mov_b32 s14, s0
	s_mov_b32 s15, s1
	s_add_u32 s0, s0, 0x2000000
	s_addc_u32 s1, s1, 0
	global_load_dwordx4 v[40:43], v1, s[14:15]
	s_add_u32 s14, s14, 0x4000
	s_addc_u32 s15, s15, 0
	global_load_dwordx4 v[44:47], v1, s[14:15]
	s_add_u32 s14, s14, 0x4000
	s_addc_u32 s15, s15, 0
	global_load_dwordx4 v[48:51], v1, s[14:15]
	s_add_u32 s14, s14, 0x4000
	s_addc_u32 s15, s15, 0
	global_load_dwordx4 v[52:55], v1, s[14:15]
	s_add_u32 s14, s14, 0x4000
	s_addc_u32 s15, s15, 0
	global_load_dwordx4 v[56:59], v1, s[14:15]
	s_add_u32 s14, s14, 0x4000
	s_addc_u32 s15, s15, 0
	global_load_dwordx4 v[60:63], v1, s[14:15]
	s_add_u32 s14, s14, 0x4000
	s_addc_u32 s15, s15, 0
	global_load_dwordx4 v[64:67], v1, s[14:15]
	s_add_u32 s14, s14, 0x4000
	s_addc_u32 s15, s15, 0
	global_load_dwordx4 v[68:71], v1, s[14:15]
	s_add_u32 s14, s14, 0x4000
	s_addc_u32 s15, s15, 0
	global_load_dwordx4 v[72:75], v1, s[14:15]
	s_add_u32 s14, s14, 0x4000
	s_addc_u32 s15, s15, 0
	global_load_dwordx4 v[76:79], v1, s[14:15]
	s_add_u32 s14, s14, 0x4000
	s_addc_u32 s15, s15, 0
	global_load_dwordx4 v[80:83], v1, s[14:15]
	s_add_u32 s14, s14, 0x4000
	s_addc_u32 s15, s15, 0
	global_load_dwordx4 v[84:87], v1, s[14:15]
	s_add_u32 s14, s14, 0x4000
	s_addc_u32 s15, s15, 0
	global_load_dwordx4 v[88:91], v1, s[14:15]
	s_add_u32 s14, s14, 0x4000
	s_addc_u32 s15, s15, 0
	global_load_dwordx4 v[92:95], v1, s[14:15]
	s_add_u32 s14, s14, 0x4000
	s_addc_u32 s15, s15, 0
	global_load_dwordx4 v[96:99], v1, s[14:15]
	s_add_u32 s14, s14, 0x4000
	s_addc_u32 s15, s15, 0
	global_load_dwordx4 v[100:103], v1, s[14:15]
	s_add_u32 s14, s14, 0x4000
	s_addc_u32 s15, s15, 0
	global_load_dwordx4 v[104:107], v1, s[14:15]
	s_add_u32 s14, s14, 0x4000
	s_addc_u32 s15, s15, 0
	global_load_dwordx4 v[108:111], v1, s[14:15]
	s_add_u32 s14, s14, 0x4000
	s_addc_u32 s15, s15, 0
	global_load_dwordx4 v[112:115], v1, s[14:15]
	s_add_u32 s14, s14, 0x4000
	s_addc_u32 s15, s15, 0
	global_load_dwordx4 v[116:119], v1, s[14:15]
	s_add_u32 s14, s14, 0x4000
	s_addc_u32 s15, s15, 0
	global_load_dwordx4 v[120:123], v1, s[14:15]
	s_add_u32 s14, s14, 0x4000
	s_addc_u32 s15, s15, 0
	global_load_dwordx4 v[124:127], v1, s[14:15]
	s_add_u32 s14, s14, 0x4000
	s_addc_u32 s15, s15, 0
	global_load_dwordx4 v[128:131], v1, s[14:15]
	s_add_u32 s14, s14, 0x4000
	s_addc_u32 s15, s15, 0
	global_load_dwordx4 v[132:135], v1, s[14:15]
	s_add_u32 s14, s14, 0x4000
	s_addc_u32 s15, s15, 0
	global_load_dwordx4 v[136:139], v1, s[14:15]
	s_add_u32 s14, s14, 0x4000
	s_addc_u32 s15, s15, 0
	global_load_dwordx4 v[140:143], v1, s[14:15]
	s_add_u32 s14, s14, 0x4000
	s_addc_u32 s15, s15, 0
	global_load_dwordx4 v[144:147], v1, s[14:15]
	s_add_u32 s14, s14, 0x4000
	s_addc_u32 s15, s15, 0
	global_load_dwordx4 v[148:151], v1, s[14:15]
	s_add_u32 s14, s14, 0x4000
	s_addc_u32 s15, s15, 0
	global_load_dwordx4 v[152:155], v1, s[14:15]
	s_add_u32 s14, s14, 0x4000
	s_addc_u32 s15, s15, 0
	global_load_dwordx4 v[156:159], v1, s[14:15]
	s_add_u32 s14, s14, 0x4000
	s_addc_u32 s15, s15, 0
	global_load_dwordx4 v[160:163], v1, s[14:15]
	s_add_u32 s14, s14, 0x4000
	s_addc_u32 s15, s15, 0
	global_load_dwordx4 v[164:167], v1, s[14:15]
	s_add_u32 s14, s14, 0x4000
	s_addc_u32 s15, s15, 0
	v_mov_b32_e32 v10, 0
	v_mov_b32_e32 v11, 0
	v_mov_b32_e32 v12, 0
	v_mov_b32_e32 v13, 0
	v_mov_b32_e32 v14, 0
	v_mov_b32_e32 v15, 0
	v_mov_b32_e32 v16, 0
	v_mov_b32_e32 v17, 0
	v_cvt_pk_bf16_f32 v26, v10, v11
	v_cvt_pk_bf16_f32 v27, v12, v13
	v_cvt_pk_bf16_f32 v28, v14, v15
	v_cvt_pk_bf16_f32 v29, v16, v17
	global_store_dwordx4 v1, v[26:29], s[0:1]
	s_add_u32 s0, s0, 0x4000
	s_addc_u32 s1, s1, 0
	s_waitcnt vmcnt(32)
	v_lshlrev_b32_e32 v18, 16, v40
	v_and_b32_e32 v19, 0xffff0000, v40
	v_lshlrev_b32_e32 v20, 16, v41
	v_and_b32_e32 v21, 0xffff0000, v41
	v_lshlrev_b32_e32 v22, 16, v42
	v_and_b32_e32 v23, 0xffff0000, v42
	v_lshlrev_b32_e32 v24, 16, v43
	v_and_b32_e32 v25, 0xffff0000, v43
	global_load_dwordx4 v[40:43], v1, s[14:15]
	s_add_u32 s14, s14, 0x4000
	s_addc_u32 s15, s15, 0
	v_fma_f32 v10, v8, v10, v18
	v_fma_f32 v11, v8, v11, v19
	v_fma_f32 v12, v8, v12, v20
	v_fma_f32 v13, v8, v13, v21
	v_fma_f32 v14, v8, v14, v22
	v_fma_f32 v15, v8, v15, v23
	v_fma_f32 v16, v8, v16, v24
	v_fma_f32 v17, v8, v17, v25
	v_cvt_pk_bf16_f32 v34, v10, v11
	v_cvt_pk_bf16_f32 v35, v12, v13
	v_cvt_pk_bf16_f32 v36, v14, v15
	v_cvt_pk_bf16_f32 v37, v16, v17
	global_store_dwordx4 v1, v[34:37], s[0:1]
	s_add_u32 s0, s0, 0x4000
	s_addc_u32 s1, s1, 0
	s_waitcnt vmcnt(33)
	v_lshlrev_b32_e32 v18, 16, v44
	v_and_b32_e32 v19, 0xffff0000, v44
	v_lshlrev_b32_e32 v20, 16, v45
	v_and_b32_e32 v21, 0xffff0000, v45
	v_lshlrev_b32_e32 v22, 16, v46
	v_and_b32_e32 v23, 0xffff0000, v46
	v_lshlrev_b32_e32 v24, 16, v47
	v_and_b32_e32 v25, 0xffff0000, v47
	global_load_dwordx4 v[44:47], v1, s[14:15]
	s_add_u32 s14, s14, 0x4000
	s_addc_u32 s15, s15, 0
	v_fma_f32 v10, v8, v10, v18
	v_fma_f32 v11, v8, v11, v19
	v_fma_f32 v12, v8, v12, v20
	v_fma_f32 v13, v8, v13, v21
	v_fma_f32 v14, v8, v14, v22
	v_fma_f32 v15, v8, v15, v23
	v_fma_f32 v16, v8, v16, v24
	v_fma_f32 v17, v8, v17, v25
	v_cvt_pk_bf16_f32 v26, v10, v11
	v_cvt_pk_bf16_f32 v27, v12, v13
	v_cvt_pk_bf16_f32 v28, v14, v15
	v_cvt_pk_bf16_f32 v29, v16, v17
	global_store_dwordx4 v1, v[26:29], s[0:1]
	s_add_u32 s0, s0, 0x4000
	s_addc_u32 s1, s1, 0
	s_waitcnt vmcnt(34)
; __device__ __forceinline__ unsigned cvt_pk_bf16(float lo, float hi) { unsigned r; asm volatile("v_cvt_pk_bf16_f32 %0, %1, %2" : "=v"(r) : "v"(lo), "v"(hi)); return r; }
; __global__ void __launch_bounds__(512, 2) hse_fwd(Params P) {
;     ...
;                     for (int c = 0; c < 128; c += 32) { float vn[32]; const int cn = c + 32 < 128 ? c + 32 : c;
; #pragma unroll
;                         for (int j = 0; j < 32; ++j) vn[j] = __uint_as_float((unsigned)p[(size_t)(cn + j) * 8192] << 16);
; #pragma unroll
;                         for (int j = 0; j < 32; j += 2) {
;                             const float r0 = run; run = g64 * run + v[j]; const float r1 = run; run = g64 * run + v[j + 1];
;                             const bool odd = lane & 1; const float mine = odd ? r1 : r0, send = odd ? r0 : r1;
;                             const float recv = __int_as_float(__builtin_amdgcn_mov_dpp(__float_as_int(send), 0xB1, 0xF, 0xF, false));
;                             const unsigned w = odd ? cvt_pk_bf16(recv, mine) : cvt_pk_bf16(mine, recv);
;                             *(unsigned*)(pb - (lane & 1) + (size_t)(c + j + (odd ? 1 : 0)) * 8192) = w; }
; #pragma unroll
;                         for (int j = 0; j < 32; ++j) v[j] = vn[j]; }
	v_lshlrev_b32_e32 v18, 16, v48
	v_and_b32_e32 v19, 0xffff0000, v48
	v_lshlrev_b32_e32 v20, 16, v49
	v_and_b32_e32 v21, 0xffff0000, v49
	v_lshlrev_b32_e32 v22, 16, v50
	v_and_b32_e32 v23, 0xffff0000, v50
	v_lshlrev_b32_e32 v24, 16, v51
	v_and_b32_e32 v25, 0xffff0000, v51
	global_load_dwordx4 v[48:51], v1, s[14:15]
	s_add_u32 s14, s14, 0x4000
	s_addc_u32 s15, s15, 0
	v_fma_f32 v10, v8, v10, v18
	v_fma_f32 v11, v8, v11, v19
	v_fma_f32 v12, v8, v12, v20
	v_fma_f32 v13, v8, v13, v21
	v_fma_f32 v14, v8, v14, v22
	v_fma_f32 v15, v8, v15, v23
	v_fma_f32 v16, v8, v16, v24
	v_fma_f32 v17, v8, v17, v25
	v_cvt_pk_bf16_f32 v34, v10, v11
	v_cvt_pk_bf16_f32 v35, v12, v13
	v_cvt_pk_bf16_f32 v36, v14, v15
	v_cvt_pk_bf16_f32 v37, v16, v17
	global_store_dwordx4 v1, v[34:37], s[0:1]
	s_add_u32 s0, s0, 0x4000
	s_addc_u32 s1, s1, 0
	s_waitcnt vmcnt(35)
	v_lshlrev_b32_e32 v18, 16, v52
	v_and_b32_e32 v19, 0xffff0000, v52
	v_lshlrev_b32_e32 v20, 16, v53
	v_and_b32_e32 v21, 0xffff0000, v53
	v_lshlrev_b32_e32 v22, 16, v54
	v_and_b32_e32 v23, 0xffff0000, v54
	v_lshlrev_b32_e32 v24, 16, v55
	v_and_b32_e32 v25, 0xffff0000, v55
	global_load_dwordx4 v[52:55], v1, s[14:15]
	s_add_u32 s14, s14, 0x4000
	s_addc_u32 s15, s15, 0
	v_fma_f32 v10, v8, v10, v18
	v_fma_f32 v11, v8, v11, v19
	v_fma_f32 v12, v8, v12, v20
	v_fma_f32 v13, v8, v13, v21
	v_fma_f32 v14, v8, v14, v22
	v_fma_f32 v15, v8, v15, v23
	v_fma_f32 v16, v8, v16, v24
	v_fma_f32 v17, v8, v17, v25
	v_cvt_pk_bf16_f32 v26, v10, v11
	v_cvt_pk_bf16_f32 v27, v12, v13
	v_cvt_pk_bf16_f32 v28, v14, v15
	v_cvt_pk_bf16_f32 v29, v16, v17
	global_store_dwordx4 v1, v[26:29], s[0:1]
	s_add_u32 s0, s0, 0x4000
	s_addc_u32 s1, s1, 0
	s_waitcnt vmcnt(36)
	v_lshlrev_b32_e32 v18, 16, v56
	v_and_b32_e32 v19, 0xffff0000, v56
	v_lshlrev_b32_e32 v20, 16, v57
	v_and_b32_e32 v21, 0xffff0000, v57
	v_lshlrev_b32_e32 v22, 16, v58
	v_and_b32_e32 v23, 0xffff0000, v58
	v_lshlrev_b32_e32 v24, 16, v59
	v_and_b32_e32 v25, 0xffff0000, v59
	global_load_dwordx4 v[56:59], v1, s[14:15]
	s_add_u32 s14, s14, 0x4000
	s_addc_u32 s15, s15, 0
	v_fma_f32 v10, v8, v10, v18
	v_fma_f32 v11, v8, v11, v19
	v_fma_f32 v12, v8, v12, v20
	v_fma_f32 v13, v8, v13, v21
	v_fma_f32 v14, v8, v14, v22
	v_fma_f32 v15, v8, v15, v23
	v_fma_f32 v16, v8, v16, v24
	v_fma_f32 v17, v8, v17, v25
	v_cvt_pk_bf16_f32 v34, v10, v11
	v_cvt_pk_bf16_f32 v35, v12, v13
	v_cvt_pk_bf16_f32 v36, v14, v15
	v_cvt_pk_bf16_f32 v37, v16, v17
	global_store_dwordx4 v1, v[34:37], s[0:1]
	s_add_u32 s0, s0, 0x4000
	s_addc_u32 s1, s1, 0
	s_waitcnt vmcnt(37)
	v_lshlrev_b32_e32 v18, 16, v60
	v_and_b32_e32 v19, 0xffff0000, v60
	v_lshlrev_b32_e32 v20, 16, v61
	v_and_b32_e32 v21, 0xffff0000, v61
	v_lshlrev_b32_e32 v22, 16, v62
	v_and_b32_e32 v23, 0xffff0000, v62
	v_lshlrev_b32_e32 v24, 16, v63
	v_and_b32_e32 v25, 0xffff0000, v63
	global_load_dwordx4 v[60:63], v1, s[14:15]
	s_add_u32 s14, s14, 0x4000
	s_addc_u32 s15, s15, 0
	v_fma_f32 v10, v8, v10, v18
	v_fma_f32 v11, v8, v11, v19
	v_fma_f32 v12, v8, v12, v20
	v_fma_f32 v13, v8, v13, v21
	v_fma_f32 v14, v8, v14, v22
	v_fma_f32 v15, v8, v15, v23
	v_fma_f32 v16, v8, v16, v24
	v_fma_f32 v17, v8, v17, v25
	v_cvt_pk_bf16_f32 v26, v10, v11
	v_cvt_pk_bf16_f32 v27, v12, v13
	v_cvt_pk_bf16_f32 v28, v14, v15
	v_cvt_pk_bf16_f32 v29, v16, v17
	global_store_dwordx4 v1, v[26:29], s[0:1]
	s_add_u32 s0, s0, 0x4000
	s_addc_u32 s1, s1, 0
	s_waitcnt vmcnt(38)
	v_lshlrev_b32_e32 v18, 16, v64
	v_and_b32_e32 v19, 0xffff0000, v64
	v_lshlrev_b32_e32 v20, 16, v65
	v_and_b32_e32 v21, 0xffff0000, v65
	v_lshlrev_b32_e32 v22, 16, v66
	v_and_b32_e32 v23, 0xffff0000, v66
	v_lshlrev_b32_e32 v24, 16, v67
	v_and_b32_e32 v25, 0xffff0000, v67
	global_load_dwordx4 v[64:67], v1, s[14:15]
	s_add_u32 s14, s14, 0x4000
	s_addc_u32 s15, s15, 0
	v_fma_f32 v10, v8, v10, v18
	v_fma_f32 v11, v8, v11, v19
	v_fma_f32 v12, v8, v12, v20
	v_fma_f32 v13, v8, v13, v21
	v_fma_f32 v14, v8, v14, v22
	v_fma_f32 v15, v8, v15, v23
	v_fma_f32 v16, v8, v16, v24
	v_fma_f32 v17, v8, v17, v25
	v_cvt_pk_bf16_f32 v34, v10, v11
	v_cvt_pk_bf16_f32 v35, v12, v13
	v_cvt_pk_bf16_f32 v36, v14, v15
	v_cvt_pk_bf16_f32 v37, v16, v17
	global_store_dwordx4 v1, v[34:37], s[0:1]
	s_add_u32 s0, s0, 0x4000
	s_addc_u32 s1, s1, 0
	s_waitcnt vmcnt(39)
	v_lshlrev_b32_e32 v18, 16, v68
	v_and_b32_e32 v19, 0xffff0000, v68
	v_lshlrev_b32_e32 v20, 16, v69
	v_and_b32_e32 v21, 0xffff0000, v69
	v_lshlrev_b32_e32 v22, 16, v70
	v_and_b32_e32 v23, 0xffff0000, v70
	v_lshlrev_b32_e32 v24, 16, v71
	v_and_b32_e32 v25, 0xffff0000, v71
	global_load_dwordx4 v[68:71], v1, s[14:15]
	s_add_u32 s14, s14, 0x4000
	s_addc_u32 s15, s15, 0
	v_fma_f32 v10, v8, v10, v18
	v_fma_f32 v11, v8, v11, v19
	v_fma_f32 v12, v8, v12, v20
	v_fma_f32 v13, v8, v13, v21
	v_fma_f32 v14, v8, v14, v22
	v_fma_f32 v15, v8, v15, v23
	v_fma_f32 v16, v8, v16, v24
	v_fma_f32 v17, v8, v17, v25
	v_cvt_pk_bf16_f32 v26, v10, v11
	v_cvt_pk_bf16_f32 v27, v12, v13
	v_cvt_pk_bf16_f32 v28, v14, v15
	v_cvt_pk_bf16_f32 v29, v16, v17
	global_store_dwordx4 v1, v[26:29], s[0:1]
	s_add_u32 s0, s0, 0x4000
	s_addc_u32 s1, s1, 0
	s_waitcnt vmcnt(40)
	v_lshlrev_b32_e32 v18, 16, v72
	v_and_b32_e32 v19, 0xffff0000, v72
	v_lshlrev_b32_e32 v20, 16, v73
	v_and_b32_e32 v21, 0xffff0000, v73
	v_lshlrev_b32_e32 v22, 16, v74
	v_and_b32_e32 v23, 0xffff0000, v74
	v_lshlrev_b32_e32 v24, 16, v75
	v_and_b32_e32 v25, 0xffff0000, v75
	global_load_dwordx4 v[72:75], v1, s[14:15]
	s_add_u32 s14, s14, 0x4000
	s_addc_u32 s15, s15, 0
	v_fma_f32 v10, v8, v10, v18
	v_fma_f32 v11, v8, v11, v19
	v_fma_f32 v12, v8, v12, v20
	v_fma_f32 v13, v8, v13, v21
	v_fma_f32 v14, v8, v14, v22
	v_fma_f32 v15, v8, v15, v23
	v_fma_f32 v16, v8, v16, v24
	v_fma_f32 v17, v8, v17, v25
	v_cvt_pk_bf16_f32 v34, v10, v11
	v_cvt_pk_bf16_f32 v35, v12, v13
	v_cvt_pk_bf16_f32 v36, v14, v15
	v_cvt_pk_bf16_f32 v37, v16, v17
	global_store_dwordx4 v1, v[34:37], s[0:1]
	s_add_u32 s0, s0, 0x4000
	s_addc_u32 s1, s1, 0
	s_waitcnt vmcnt(41)
; __device__ __forceinline__ unsigned cvt_pk_bf16(float lo, float hi) { unsigned r; asm volatile("v_cvt_pk_bf16_f32 %0, %1, %2" : "=v"(r) : "v"(lo), "v"(hi)); return r; }
; __global__ void __launch_bounds__(512, 2) hse_fwd(Params P) {
;     ...
;                     for (int c = 0; c < 128; c += 32) { float vn[32]; const int cn = c + 32 < 128 ? c + 32 : c;
; #pragma unroll
;                         for (int j = 0; j < 32; ++j) vn[j] = __uint_as_float((unsigned)p[(size_t)(cn + j) * 8192] << 16);
; #pragma unroll
;                         for (int j = 0; j < 32; j += 2) {
;                             const float r0 = run; run = g64 * run + v[j]; const float r1 = run; run = g64 * run + v[j + 1];
;                             const bool odd = lane & 1; const float mine = odd ? r1 : r0, send = odd ? r0 : r1;
;                             const float recv = __int_as_float(__builtin_amdgcn_mov_dpp(__float_as_int(send), 0xB1, 0xF, 0xF, false));
;                             const unsigned w = odd ? cvt_pk_bf16(recv, mine) : cvt_pk_bf16(mine, recv);
;                             *(unsigned*)(pb - (lane & 1) + (size_t)(c + j + (odd ? 1 : 0)) * 8192) = w; }
; #pragma unroll
;                         for (int j = 0; j < 32; ++j) v[j] = vn[j]; }
	v_lshlrev_b32_e32 v18, 16, v76
	v_and_b32_e32 v19, 0xffff0000, v76
	v_lshlrev_b32_e32 v20, 16, v77
	v_and_b32_e32 v21, 0xffff0000, v77
	v_lshlrev_b32_e32 v22, 16, v78
	v_and_b32_e32 v23, 0xffff0000, v78
	v_lshlrev_b32_e32 v24, 16, v79
	v_and_b32_e32 v25, 0xffff0000, v79
	global_load_dwordx4 v[76:79], v1, s[14:15]
	s_add_u32 s14, s14, 0x4000
	s_addc_u32 s15, s15, 0
	v_fma_f32 v10, v8, v10, v18
	v_fma_f32 v11, v8, v11, v19
	v_fma_f32 v12, v8, v12, v20
	v_fma_f32 v13, v8, v13, v21
	v_fma_f32 v14, v8, v14, v22
	v_fma_f32 v15, v8, v15, v23
	v_fma_f32 v16, v8, v16, v24
	v_fma_f32 v17, v8, v17, v25
	v_cvt_pk_bf16_f32 v26, v10, v11
	v_cvt_pk_bf16_f32 v27, v12, v13
	v_cvt_pk_bf16_f32 v28, v14, v15
	v_cvt_pk_bf16_f32 v29, v16, v17
	global_store_dwordx4 v1, v[26:29], s[0:1]
	s_add_u32 s0, s0, 0x4000
	s_addc_u32 s1, s1, 0
	s_waitcnt vmcnt(42)
	v_lshlrev_b32_e32 v18, 16, v80
	v_and_b32_e32 v19, 0xffff0000, v80
	v_lshlrev_b32_e32 v20, 16, v81
	v_and_b32_e32 v21, 0xffff0000, v81
	v_lshlrev_b32_e32 v22, 16, v82
	v_and_b32_e32 v23, 0xffff0000, v82
	v_lshlrev_b32_e32 v24, 16, v83
	v_and_b32_e32 v25, 0xffff0000, v83
	global_load_dwordx4 v[80:83], v1, s[14:15]
	s_add_u32 s14, s14, 0x4000
	s_addc_u32 s15, s15, 0
	v_fma_f32 v10, v8, v10, v18
	v_fma_f32 v11, v8, v11, v19
	v_fma_f32 v12, v8, v12, v20
	v_fma_f32 v13, v8, v13, v21
	v_fma_f32 v14, v8, v14, v22
	v_fma_f32 v15, v8, v15, v23
	v_fma_f32 v16, v8, v16, v24
	v_fma_f32 v17, v8, v17, v25
	v_cvt_pk_bf16_f32 v34, v10, v11
	v_cvt_pk_bf16_f32 v35, v12, v13
	v_cvt_pk_bf16_f32 v36, v14, v15
	v_cvt_pk_bf16_f32 v37, v16, v17
	global_store_dwordx4 v1, v[34:37], s[0:1]
	s_add_u32 s0, s0, 0x4000
	s_addc_u32 s1, s1, 0
	s_waitcnt vmcnt(43)
	v_lshlrev_b32_e32 v18, 16, v84
	v_and_b32_e32 v19, 0xffff0000, v84
	v_lshlrev_b32_e32 v20, 16, v85
	v_and_b32_e32 v21, 0xffff0000, v85
	v_lshlrev_b32_e32 v22, 16, v86
	v_and_b32_e32 v23, 0xffff0000, v86
	v_lshlrev_b32_e32 v24, 16, v87
	v_and_b32_e32 v25, 0xffff0000, v87
	global_load_dwordx4 v[84:87], v1, s[14:15]
	s_add_u32 s14, s14, 0x4000
	s_addc_u32 s15, s15, 0
	v_fma_f32 v10, v8, v10, v18
	v_fma_f32 v11, v8, v11, v19
	v_fma_f32 v12, v8, v12, v20
	v_fma_f32 v13, v8, v13, v21
	v_fma_f32 v14, v8, v14, v22
	v_fma_f32 v15, v8, v15, v23
	v_fma_f32 v16, v8, v16, v24
	v_fma_f32 v17, v8, v17, v25
	v_cvt_pk_bf16_f32 v26, v10, v11
	v_cvt_pk_bf16_f32 v27, v12, v13
	v_cvt_pk_bf16_f32 v28, v14, v15
	v_cvt_pk_bf16_f32 v29, v16, v17
	global_store_dwordx4 v1, v[26:29], s[0:1]
	s_add_u32 s0, s0, 0x4000
	s_addc_u32 s1, s1, 0
	s_waitcnt vmcnt(44)
	v_lshlrev_b32_e32 v18, 16, v88
	v_and_b32_e32 v19, 0xffff0000, v88
	v_lshlrev_b32_e32 v20, 16, v89
	v_and_b32_e32 v21, 0xffff0000, v89
	v_lshlrev_b32_e32 v22, 16, v90
	v_and_b32_e32 v23, 0xffff0000, v90
	v_lshlrev_b32_e32 v24, 16, v91
	v_and_b32_e32 v25, 0xffff0000, v91
	global_load_dwordx4 v[88:91], v1, s[14:15]
	s_add_u32 s14, s14, 0x4000
	s_addc_u32 s15, s15, 0
	v_fma_f32 v10, v8, v10, v18
	v_fma_f32 v11, v8, v11, v19
	v_fma_f32 v12, v8, v12, v20
	v_fma_f32 v13, v8, v13, v21
	v_fma_f32 v14, v8, v14, v22
	v_fma_f32 v15, v8, v15, v23
	v_fma_f32 v16, v8, v16, v24
	v_fma_f32 v17, v8, v17, v25
	v_cvt_pk_bf16_f32 v34, v10, v11
	v_cvt_pk_bf16_f32 v35, v12, v13
	v_cvt_pk_bf16_f32 v36, v14, v15
	v_cvt_pk_bf16_f32 v37, v16, v17
	global_store_dwordx4 v1, v[34:37], s[0:1]
	s_add_u32 s0, s0, 0x4000
	s_addc_u32 s1, s1, 0
	s_waitcnt vmcnt(45)
	v_lshlrev_b32_e32 v18, 16, v92
	v_and_b32_e32 v19, 0xffff0000, v92
	v_lshlrev_b32_e32 v20, 16, v93
	v_and_b32_e32 v21, 0xffff0000, v93
	v_lshlrev_b32_e32 v22, 16, v94
	v_and_b32_e32 v23, 0xffff0000, v94
	v_lshlrev_b32_e32 v24, 16, v95
	v_and_b32_e32 v25, 0xffff0000, v95
	global_load_dwordx4 v[92:95], v1, s[14:15]
	s_add_u32 s14, s14, 0x4000
	s_addc_u32 s15, s15, 0
	v_fma_f32 v10, v8, v10, v18
	v_fma_f32 v11, v8, v11, v19
	v_fma_f32 v12, v8, v12, v20
	v_fma_f32 v13, v8, v13, v21
	v_fma_f32 v14, v8, v14, v22
	v_fma_f32 v15, v8, v15, v23
	v_fma_f32 v16, v8, v16, v24
	v_fma_f32 v17, v8, v17, v25
	v_cvt_pk_bf16_f32 v26, v10, v11
	v_cvt_pk_bf16_f32 v27, v12, v13
	v_cvt_pk_bf16_f32 v28, v14, v15
	v_cvt_pk_bf16_f32 v29, v16, v17
	global_store_dwordx4 v1, v[26:29], s[0:1]
	s_add_u32 s0, s0, 0x4000
	s_addc_u32 s1, s1, 0
	s_waitcnt vmcnt(46)
	v_lshlrev_b32_e32 v18, 16, v96
	v_and_b32_e32 v19, 0xffff0000, v96
	v_lshlrev_b32_e32 v20, 16, v97
	v_and_b32_e32 v21, 0xffff0000, v97
	v_lshlrev_b32_e32 v22, 16, v98
	v_and_b32_e32 v23, 0xffff0000, v98
	v_lshlrev_b32_e32 v24, 16, v99
	v_and_b32_e32 v25, 0xffff0000, v99
	global_load_dwordx4 v[96:99], v1, s[14:15]
	s_add_u32 s14, s14, 0x4000
	s_addc_u32 s15, s15, 0
	v_fma_f32 v10, v8, v10, v18
	v_fma_f32 v11, v8, v11, v19
	v_fma_f32 v12, v8, v12, v20
	v_fma_f32 v13, v8, v13, v21
	v_fma_f32 v14, v8, v14, v22
	v_fma_f32 v15, v8, v15, v23
	v_fma_f32 v16, v8, v16, v24
	v_fma_f32 v17, v8, v17, v25
	v_cvt_pk_bf16_f32 v34, v10, v11
	v_cvt_pk_bf16_f32 v35, v12, v13
	v_cvt_pk_bf16_f32 v36, v14, v15
	v_cvt_pk_bf16_f32 v37, v16, v17
	global_store_dwordx4 v1, v[34:37], s[0:1]
	s_add_u32 s0, s0, 0x4000
	s_addc_u32 s1, s1, 0
	s_waitcnt vmcnt(47)
	v_lshlrev_b32_e32 v18, 16, v100
	v_and_b32_e32 v19, 0xffff0000, v100
	v_lshlrev_b32_e32 v20, 16, v101
	v_and_b32_e32 v21, 0xffff0000, v101
	v_lshlrev_b32_e32 v22, 16, v102
	v_and_b32_e32 v23, 0xffff0000, v102
	v_lshlrev_b32_e32 v24, 16, v103
	v_and_b32_e32 v25, 0xffff0000, v103
	global_load_dwordx4 v[100:103], v1, s[14:15]
	s_add_u32 s14, s14, 0x4000
	s_addc_u32 s15, s15, 0
	v_fma_f32 v10, v8, v10, v18
	v_fma_f32 v11, v8, v11, v19
	v_fma_f32 v12, v8, v12, v20
	v_fma_f32 v13, v8, v13, v21
	v_fma_f32 v14, v8, v14, v22
	v_fma_f32 v15, v8, v15, v23
	v_fma_f32 v16, v8, v16, v24
	v_fma_f32 v17, v8, v17, v25
	v_cvt_pk_bf16_f32 v26, v10, v11
	v_cvt_pk_bf16_f32 v27, v12, v13
	v_cvt_pk_bf16_f32 v28, v14, v15
	v_cvt_pk_bf16_f32 v29, v16, v17
	global_store_dwordx4 v1, v[26:29], s[0:1]
	s_add_u32 s0, s0, 0x4000
	s_addc_u32 s1, s1, 0
	s_waitcnt vmcnt(48)
; __device__ __forceinline__ unsigned cvt_pk_bf16(float lo, float hi) { unsigned r; asm volatile("v_cvt_pk_bf16_f32 %0, %1, %2" : "=v"(r) : "v"(lo), "v"(hi)); return r; }
; __global__ void __launch_bounds__(512, 2) hse_fwd(Params P) {
;     ...
;                     for (int c = 0; c < 128; c += 32) { float vn[32]; const int cn = c + 32 < 128 ? c + 32 : c;
; #pragma unroll
;                         for (int j = 0; j < 32; ++j) vn[j] = __uint_as_float((unsigned)p[(size_t)(cn + j) * 8192] << 16);
; #pragma unroll
;                         for (int j = 0; j < 32; j += 2) {
;                             const float r0 = run; run = g64 * run + v[j]; const float r1 = run; run = g64 * run + v[j + 1];
;                             const bool odd = lane & 1; const float mine = odd ? r1 : r0, send = odd ? r0 : r1;
;                             const float recv = __int_as_float(__builtin_amdgcn_mov_dpp(__float_as_int(send), 0xB1, 0xF, 0xF, false));
;                             const unsigned w = odd ? cvt_pk_bf16(recv, mine) : cvt_pk_bf16(mine, recv);
;                             *(unsigned*)(pb - (lane & 1) + (size_t)(c + j + (odd ? 1 : 0)) * 8192) = w; }
; #pragma unroll
;                         for (int j = 0; j < 32; ++j) v[j] = vn[j]; }
	v_lshlrev_b32_e32 v18, 16, v104
	v_and_b32_e32 v19, 0xffff0000, v104
	v_lshlrev_b32_e32 v20, 16, v105
	v_and_b32_e32 v21, 0xffff0000, v105
	v_lshlrev_b32_e32 v22, 16, v106
	v_and_b32_e32 v23, 0xffff0000, v106
	v_lshlrev_b32_e32 v24, 16, v107
	v_and_b32_e32 v25, 0xffff0000, v107
	global_load_dwordx4 v[104:107], v1, s[14:15]
	s_add_u32 s14, s14, 0x4000
	s_addc_u32 s15, s15, 0
	v_fma_f32 v10, v8, v10, v18
	v_fma_f32 v11, v8, v11, v19
	v_fma_f32 v12, v8, v12, v20
	v_fma_f32 v13, v8, v13, v21
	v_fma_f32 v14, v8, v14, v22
	v_fma_f32 v15, v8, v15, v23
	v_fma_f32 v16, v8, v16, v24
	v_fma_f32 v17, v8, v17, v25
	v_cvt_pk_bf16_f32 v34, v10, v11
	v_cvt_pk_bf16_f32 v35, v12, v13
	v_cvt_pk_bf16_f32 v36, v14, v15
	v_cvt_pk_bf16_f32 v37, v16, v17
	global_store_dwordx4 v1, v[34:37], s[0:1]
	s_add_u32 s0, s0, 0x4000
	s_addc_u32 s1, s1, 0
	s_waitcnt vmcnt(49)
	v_lshlrev_b32_e32 v18, 16, v108
	v_and_b32_e32 v19, 0xffff0000, v108
	v_lshlrev_b32_e32 v20, 16, v109
	v_and_b32_e32 v21, 0xffff0000, v109
	v_lshlrev_b32_e32 v22, 16, v110
	v_and_b32_e32 v23, 0xffff0000, v110
	v_lshlrev_b32_e32 v24, 16, v111
	v_and_b32_e32 v25, 0xffff0000, v111
	global_load_dwordx4 v[108:111], v1, s[14:15]
	s_add_u32 s14, s14, 0x4000
	s_addc_u32 s15, s15, 0
	v_fma_f32 v10, v8, v10, v18
	v_fma_f32 v11, v8, v11, v19
	v_fma_f32 v12, v8, v12, v20
	v_fma_f32 v13, v8, v13, v21
	v_fma_f32 v14, v8, v14, v22
	v_fma_f32 v15, v8, v15, v23
	v_fma_f32 v16, v8, v16, v24
	v_fma_f32 v17, v8, v17, v25
	v_cvt_pk_bf16_f32 v26, v10, v11
	v_cvt_pk_bf16_f32 v27, v12, v13
	v_cvt_pk_bf16_f32 v28, v14, v15
	v_cvt_pk_bf16_f32 v29, v16, v17
	global_store_dwordx4 v1, v[26:29], s[0:1]
	s_add_u32 s0, s0, 0x4000
	s_addc_u32 s1, s1, 0
	s_waitcnt vmcnt(50)
	v_lshlrev_b32_e32 v18, 16, v112
	v_and_b32_e32 v19, 0xffff0000, v112
	v_lshlrev_b32_e32 v20, 16, v113
	v_and_b32_e32 v21, 0xffff0000, v113
	v_lshlrev_b32_e32 v22, 16, v114
	v_and_b32_e32 v23, 0xffff0000, v114
	v_lshlrev_b32_e32 v24, 16, v115
	v_and_b32_e32 v25, 0xffff0000, v115
	global_load_dwordx4 v[112:115], v1, s[14:15]
	s_add_u32 s14, s14, 0x4000
	s_addc_u32 s15, s15, 0
	v_fma_f32 v10, v8, v10, v18
	v_fma_f32 v11, v8, v11, v19
	v_fma_f32 v12, v8, v12, v20
	v_fma_f32 v13, v8, v13, v21
	v_fma_f32 v14, v8, v14, v22
	v_fma_f32 v15, v8, v15, v23
	v_fma_f32 v16, v8, v16, v24
	v_fma_f32 v17, v8, v17, v25
	v_cvt_pk_bf16_f32 v34, v10, v11
	v_cvt_pk_bf16_f32 v35, v12, v13
	v_cvt_pk_bf16_f32 v36, v14, v15
	v_cvt_pk_bf16_f32 v37, v16, v17
	global_store_dwordx4 v1, v[34:37], s[0:1]
	s_add_u32 s0, s0, 0x4000
	s_addc_u32 s1, s1, 0
	s_waitcnt vmcnt(51)
	v_lshlrev_b32_e32 v18, 16, v116
	v_and_b32_e32 v19, 0xffff0000, v116
	v_lshlrev_b32_e32 v20, 16, v117
	v_and_b32_e32 v21, 0xffff0000, v117
	v_lshlrev_b32_e32 v22, 16, v118
	v_and_b32_e32 v23, 0xffff0000, v118
	v_lshlrev_b32_e32 v24, 16, v119
	v_and_b32_e32 v25, 0xffff0000, v119
	global_load_dwordx4 v[116:119], v1, s[14:15]
	s_add_u32 s14, s14, 0x4000
	s_addc_u32 s15, s15, 0
	v_fma_f32 v10, v8, v10, v18
	v_fma_f32 v11, v8, v11, v19
	v_fma_f32 v12, v8, v12, v20
	v_fma_f32 v13, v8, v13, v21
	v_fma_f32 v14, v8, v14, v22
	v_fma_f32 v15, v8, v15, v23
	v_fma_f32 v16, v8, v16, v24
	v_fma_f32 v17, v8, v17, v25
	v_cvt_pk_bf16_f32 v26, v10, v11
	v_cvt_pk_bf16_f32 v27, v12, v13
	v_cvt_pk_bf16_f32 v28, v14, v15
	v_cvt_pk_bf16_f32 v29, v16, v17
	global_store_dwordx4 v1, v[26:29], s[0:1]
	s_add_u32 s0, s0, 0x4000
	s_addc_u32 s1, s1, 0
	s_waitcnt vmcnt(52)
	v_lshlrev_b32_e32 v18, 16, v120
	v_and_b32_e32 v19, 0xffff0000, v120
	v_lshlrev_b32_e32 v20, 16, v121
	v_and_b32_e32 v21, 0xffff0000, v121
	v_lshlrev_b32_e32 v22, 16, v122
	v_and_b32_e32 v23, 0xffff0000, v122
	v_lshlrev_b32_e32 v24, 16, v123
	v_and_b32_e32 v25, 0xffff0000, v123
	global_load_dwordx4 v[120:123], v1, s[14:15]
	s_add_u32 s14, s14, 0x4000
	s_addc_u32 s15, s15, 0
	v_fma_f32 v10, v8, v10, v18
	v_fma_f32 v11, v8, v11, v19
	v_fma_f32 v12, v8, v12, v20
	v_fma_f32 v13, v8, v13, v21
	v_fma_f32 v14, v8, v14, v22
	v_fma_f32 v15, v8, v15, v23
	v_fma_f32 v16, v8, v16, v24
	v_fma_f32 v17, v8, v17, v25
	v_cvt_pk_bf16_f32 v34, v10, v11
	v_cvt_pk_bf16_f32 v35, v12, v13
	v_cvt_pk_bf16_f32 v36, v14, v15
	v_cvt_pk_bf16_f32 v37, v16, v17
	global_store_dwordx4 v1, v[34:37], s[0:1]
	s_add_u32 s0, s0, 0x4000
	s_addc_u32 s1, s1, 0
	s_waitcnt vmcnt(53)
	v_lshlrev_b32_e32 v18, 16, v124
	v_and_b32_e32 v19, 0xffff0000, v124
	v_lshlrev_b32_e32 v20, 16, v125
	v_and_b32_e32 v21, 0xffff0000, v125
	v_lshlrev_b32_e32 v22, 16, v126
	v_and_b32_e32 v23, 0xffff0000, v126
	v_lshlrev_b32_e32 v24, 16, v127
	v_and_b32_e32 v25, 0xffff0000, v127
	global_load_dwordx4 v[124:127], v1, s[14:15]
	s_add_u32 s14, s14, 0x4000
	s_addc_u32 s15, s15, 0
	v_fma_f32 v10, v8, v10, v18
	v_fma_f32 v11, v8, v11, v19
	v_fma_f32 v12, v8, v12, v20
	v_fma_f32 v13, v8, v13, v21
	v_fma_f32 v14, v8, v14, v22
	v_fma_f32 v15, v8, v15, v23
	v_fma_f32 v16, v8, v16, v24
	v_fma_f32 v17, v8, v17, v25
	v_cvt_pk_bf16_f32 v26, v10, v11
	v_cvt_pk_bf16_f32 v27, v12, v13
	v_cvt_pk_bf16_f32 v28, v14, v15
	v_cvt_pk_bf16_f32 v29, v16, v17
	global_store_dwordx4 v1, v[26:29], s[0:1]
	s_add_u32 s0, s0, 0x4000
	s_addc_u32 s1, s1, 0
	s_waitcnt vmcnt(54)
	v_lshlrev_b32_e32 v18, 16, v128
	v_and_b32_e32 v19, 0xffff0000, v128
	v_lshlrev_b32_e32 v20, 16, v129
	v_and_b32_e32 v21, 0xffff0000, v129
	v_lshlrev_b32_e32 v22, 16, v130
	v_and_b32_e32 v23, 0xffff0000, v130
	v_lshlrev_b32_e32 v24, 16, v131
	v_and_b32_e32 v25, 0xffff0000, v131
	global_load_dwordx4 v[128:131], v1, s[14:15]
	s_add_u32 s14, s14, 0x4000
	s_addc_u32 s15, s15, 0
	v_fma_f32 v10, v8, v10, v18
	v_fma_f32 v11, v8, v11, v19
	v_fma_f32 v12, v8, v12, v20
	v_fma_f32 v13, v8, v13, v21
	v_fma_f32 v14, v8, v14, v22
	v_fma_f32 v15, v8, v15, v23
	v_fma_f32 v16, v8, v16, v24
	v_fma_f32 v17, v8, v17, v25
	v_cvt_pk_bf16_f32 v34, v10, v11
	v_cvt_pk_bf16_f32 v35, v12, v13
	v_cvt_pk_bf16_f32 v36, v14, v15
	v_cvt_pk_bf16_f32 v37, v16, v17
	global_store_dwordx4 v1, v[34:37], s[0:1]
	s_add_u32 s0, s0, 0x4000
	s_addc_u32 s1, s1, 0
	s_waitcnt vmcnt(55)
; __device__ __forceinline__ unsigned cvt_pk_bf16(float lo, float hi) { unsigned r; asm volatile("v_cvt_pk_bf16_f32 %0, %1, %2" : "=v"(r) : "v"(lo), "v"(hi)); return r; }
; __global__ void __launch_bounds__(512, 2) hse_fwd(Params P) {
;     ...
;                     for (int c = 0; c < 128; c += 32) { float vn[32]; const int cn = c + 32 < 128 ? c + 32 : c;
; #pragma unroll
;                         for (int j = 0; j < 32; ++j) vn[j] = __uint_as_float((unsigned)p[(size_t)(cn + j) * 8192] << 16);
; #pragma unroll
;                         for (int j = 0; j < 32; j += 2) {
;                             const float r0 = run; run = g64 * run + v[j]; const float r1 = run; run = g64 * run + v[j + 1];
;                             const bool odd = lane & 1; const float mine = odd ? r1 : r0, send = odd ? r0 : r1;
;                             const float recv = __int_as_float(__builtin_amdgcn_mov_dpp(__float_as_int(send), 0xB1, 0xF, 0xF, false));
;                             const unsigned w = odd ? cvt_pk_bf16(recv, mine) : cvt_pk_bf16(mine, recv);
;                             *(unsigned*)(pb - (lane & 1) + (size_t)(c + j + (odd ? 1 : 0)) * 8192) = w; }
; #pragma unroll
;                         for (int j = 0; j < 32; ++j) v[j] = vn[j]; }
	v_lshlrev_b32_e32 v18, 16, v132
	v_and_b32_e32 v19, 0xffff0000, v132
	v_lshlrev_b32_e32 v20, 16, v133
	v_and_b32_e32 v21, 0xffff0000, v133
	v_lshlrev_b32_e32 v22, 16, v134
	v_and_b32_e32 v23, 0xffff0000, v134
	v_lshlrev_b32_e32 v24, 16, v135
	v_and_b32_e32 v25, 0xffff0000, v135
	global_load_dwordx4 v[132:135], v1, s[14:15]
	s_add_u32 s14, s14, 0x4000
	s_addc_u32 s15, s15, 0
	v_fma_f32 v10, v8, v10, v18
	v_fma_f32 v11, v8, v11, v19
	v_fma_f32 v12, v8, v12, v20
	v_fma_f32 v13, v8, v13, v21
	v_fma_f32 v14, v8, v14, v22
	v_fma_f32 v15, v8, v15, v23
	v_fma_f32 v16, v8, v16, v24
	v_fma_f32 v17, v8, v17, v25
	v_cvt_pk_bf16_f32 v26, v10, v11
	v_cvt_pk_bf16_f32 v27, v12, v13
	v_cvt_pk_bf16_f32 v28, v14, v15
	v_cvt_pk_bf16_f32 v29, v16, v17
	global_store_dwordx4 v1, v[26:29], s[0:1]
	s_add_u32 s0, s0, 0x4000
	s_addc_u32 s1, s1, 0
	s_waitcnt vmcnt(56)
	v_lshlrev_b32_e32 v18, 16, v136
	v_and_b32_e32 v19, 0xffff0000, v136
	v_lshlrev_b32_e32 v20, 16, v137
	v_and_b32_e32 v21, 0xffff0000, v137
	v_lshlrev_b32_e32 v22, 16, v138
	v_and_b32_e32 v23, 0xffff0000, v138
	v_lshlrev_b32_e32 v24, 16, v139
	v_and_b32_e32 v25, 0xffff0000, v139
	global_load_dwordx4 v[136:139], v1, s[14:15]
	s_add_u32 s14, s14, 0x4000
	s_addc_u32 s15, s15, 0
	v_fma_f32 v10, v8, v10, v18
	v_fma_f32 v11, v8, v11, v19
	v_fma_f32 v12, v8, v12, v20
	v_fma_f32 v13, v8, v13, v21
	v_fma_f32 v14, v8, v14, v22
	v_fma_f32 v15, v8, v15, v23
	v_fma_f32 v16, v8, v16, v24
	v_fma_f32 v17, v8, v17, v25
	v_cvt_pk_bf16_f32 v34, v10, v11
	v_cvt_pk_bf16_f32 v35, v12, v13
	v_cvt_pk_bf16_f32 v36, v14, v15
	v_cvt_pk_bf16_f32 v37, v16, v17
	global_store_dwordx4 v1, v[34:37], s[0:1]
	s_add_u32 s0, s0, 0x4000
	s_addc_u32 s1, s1, 0
	s_waitcnt vmcnt(57)
	v_lshlrev_b32_e32 v18, 16, v140
	v_and_b32_e32 v19, 0xffff0000, v140
	v_lshlrev_b32_e32 v20, 16, v141
	v_and_b32_e32 v21, 0xffff0000, v141
	v_lshlrev_b32_e32 v22, 16, v142
	v_and_b32_e32 v23, 0xffff0000, v142
	v_lshlrev_b32_e32 v24, 16, v143
	v_and_b32_e32 v25, 0xffff0000, v143
	global_load_dwordx4 v[140:143], v1, s[14:15]
	s_add_u32 s14, s14, 0x4000
	s_addc_u32 s15, s15, 0
	v_fma_f32 v10, v8, v10, v18
	v_fma_f32 v11, v8, v11, v19
	v_fma_f32 v12, v8, v12, v20
	v_fma_f32 v13, v8, v13, v21
	v_fma_f32 v14, v8, v14, v22
	v_fma_f32 v15, v8, v15, v23
	v_fma_f32 v16, v8, v16, v24
	v_fma_f32 v17, v8, v17, v25
	v_cvt_pk_bf16_f32 v26, v10, v11
	v_cvt_pk_bf16_f32 v27, v12, v13
	v_cvt_pk_bf16_f32 v28, v14, v15
	v_cvt_pk_bf16_f32 v29, v16, v17
	global_store_dwordx4 v1, v[26:29], s[0:1]
	s_add_u32 s0, s0, 0x4000
	s_addc_u32 s1, s1, 0
	s_waitcnt vmcnt(58)
	v_lshlrev_b32_e32 v18, 16, v144
	v_and_b32_e32 v19, 0xffff0000, v144
	v_lshlrev_b32_e32 v20, 16, v145
	v_and_b32_e32 v21, 0xffff0000, v145
	v_lshlrev_b32_e32 v22, 16, v146
	v_and_b32_e32 v23, 0xffff0000, v146
	v_lshlrev_b32_e32 v24, 16, v147
	v_and_b32_e32 v25, 0xffff0000, v147
	global_load_dwordx4 v[144:147], v1, s[14:15]
	s_add_u32 s14, s14, 0x4000
	s_addc_u32 s15, s15, 0
	v_fma_f32 v10, v8, v10, v18
	v_fma_f32 v11, v8, v11, v19
	v_fma_f32 v12, v8, v12, v20
	v_fma_f32 v13, v8, v13, v21
	v_fma_f32 v14, v8, v14, v22
	v_fma_f32 v15, v8, v15, v23
	v_fma_f32 v16, v8, v16, v24
	v_fma_f32 v17, v8, v17, v25
	v_cvt_pk_bf16_f32 v34, v10, v11
	v_cvt_pk_bf16_f32 v35, v12, v13
	v_cvt_pk_bf16_f32 v36, v14, v15
	v_cvt_pk_bf16_f32 v37, v16, v17
	global_store_dwordx4 v1, v[34:37], s[0:1]
	s_add_u32 s0, s0, 0x4000
	s_addc_u32 s1, s1, 0
	s_waitcnt vmcnt(59)
	v_lshlrev_b32_e32 v18, 16, v148
	v_and_b32_e32 v19, 0xffff0000, v148
	v_lshlrev_b32_e32 v20, 16, v149
	v_and_b32_e32 v21, 0xffff0000, v149
	v_lshlrev_b32_e32 v22, 16, v150
	v_and_b32_e32 v23, 0xffff0000, v150
	v_lshlrev_b32_e32 v24, 16, v151
	v_and_b32_e32 v25, 0xffff0000, v151
	global_load_dwordx4 v[148:151], v1, s[14:15]
	s_add_u32 s14, s14, 0x4000
	s_addc_u32 s15, s15, 0
	v_fma_f32 v10, v8, v10, v18
	v_fma_f32 v11, v8, v11, v19
	v_fma_f32 v12, v8, v12, v20
	v_fma_f32 v13, v8, v13, v21
	v_fma_f32 v14, v8, v14, v22
	v_fma_f32 v15, v8, v15, v23
	v_fma_f32 v16, v8, v16, v24
	v_fma_f32 v17, v8, v17, v25
	v_cvt_pk_bf16_f32 v26, v10, v11
	v_cvt_pk_bf16_f32 v27, v12, v13
	v_cvt_pk_bf16_f32 v28, v14, v15
	v_cvt_pk_bf16_f32 v29, v16, v17
	global_store_dwordx4 v1, v[26:29], s[0:1]
	s_add_u32 s0, s0, 0x4000
	s_addc_u32 s1, s1, 0
	s_waitcnt vmcnt(60)
	v_lshlrev_b32_e32 v18, 16, v152
	v_and_b32_e32 v19, 0xffff0000, v152
	v_lshlrev_b32_e32 v20, 16, v153
	v_and_b32_e32 v21, 0xffff0000, v153
	v_lshlrev_b32_e32 v22, 16, v154
	v_and_b32_e32 v23, 0xffff0000, v154
	v_lshlrev_b32_e32 v24, 16, v155
	v_and_b32_e32 v25, 0xffff0000, v155
	global_load_dwordx4 v[152:155], v1, s[14:15]
	s_add_u32 s14, s14, 0x4000
	s_addc_u32 s15, s15, 0
	v_fma_f32 v10, v8, v10, v18
	v_fma_f32 v11, v8, v11, v19
	v_fma_f32 v12, v8, v12, v20
	v_fma_f32 v13, v8, v13, v21
	v_fma_f32 v14, v8, v14, v22
	v_fma_f32 v15, v8, v15, v23
	v_fma_f32 v16, v8, v16, v24
	v_fma_f32 v17, v8, v17, v25
	v_cvt_pk_bf16_f32 v34, v10, v11
	v_cvt_pk_bf16_f32 v35, v12, v13
	v_cvt_pk_bf16_f32 v36, v14, v15
	v_cvt_pk_bf16_f32 v37, v16, v17
	global_store_dwordx4 v1, v[34:37], s[0:1]
	s_add_u32 s0, s0, 0x4000
	s_addc_u32 s1, s1, 0
	s_waitcnt vmcnt(61)
	v_lshlrev_b32_e32 v18, 16, v156
	v_and_b32_e32 v19, 0xffff0000, v156
	v_lshlrev_b32_e32 v20, 16, v157
	v_and_b32_e32 v21, 0xffff0000, v157
	v_lshlrev_b32_e32 v22, 16, v158
	v_and_b32_e32 v23, 0xffff0000, v158
	v_lshlrev_b32_e32 v24, 16, v159
	v_and_b32_e32 v25, 0xffff0000, v159
	global_load_dwordx4 v[156:159], v1, s[14:15]
	s_add_u32 s14, s14, 0x4000
	s_addc_u32 s15, s15, 0
	v_fma_f32 v10, v8, v10, v18
	v_fma_f32 v11, v8, v11, v19
	v_fma_f32 v12, v8, v12, v20
	v_fma_f32 v13, v8, v13, v21
	v_fma_f32 v14, v8, v14, v22
	v_fma_f32 v15, v8, v15, v23
	v_fma_f32 v16, v8, v16, v24
	v_fma_f32 v17, v8, v17, v25
	v_cvt_pk_bf16_f32 v26, v10, v11
	v_cvt_pk_bf16_f32 v27, v12, v13
	v_cvt_pk_bf16_f32 v28, v14, v15
	v_cvt_pk_bf16_f32 v29, v16, v17
	global_store_dwordx4 v1, v[26:29], s[0:1]
	s_add_u32 s0, s0, 0x4000
	s_addc_u32 s1, s1, 0
	s_waitcnt vmcnt(62)
; __device__ __forceinline__ unsigned cvt_pk_bf16(float lo, float hi) { unsigned r; asm volatile("v_cvt_pk_bf16_f32 %0, %1, %2" : "=v"(r) : "v"(lo), "v"(hi)); return r; }
; __global__ void __launch_bounds__(512, 2) hse_fwd(Params P) {
;     ...
;                     for (int c = 0; c < 128; c += 32) { float vn[32]; const int cn = c + 32 < 128 ? c + 32 : c;
; #pragma unroll
;                         for (int j = 0; j < 32; ++j) vn[j] = __uint_as_float((unsigned)p[(size_t)(cn + j) * 8192] << 16);
; #pragma unroll
;                         for (int j = 0; j < 32; j += 2) {
;                             const float r0 = run; run = g64 * run + v[j]; const float r1 = run; run = g64 * run + v[j + 1];
;                             const bool odd = lane & 1; const float mine = odd ? r1 : r0, send = odd ? r0 : r1;
;                             const float recv = __int_as_float(__builtin_amdgcn_mov_dpp(__float_as_int(send), 0xB1, 0xF, 0xF, false));
;                             const unsigned w = odd ? cvt_pk_bf16(recv, mine) : cvt_pk_bf16(mine, recv);
;                             *(unsigned*)(pb - (lane & 1) + (size_t)(c + j + (odd ? 1 : 0)) * 8192) = w; }
; #pragma unroll
;                         for (int j = 0; j < 32; ++j) v[j] = vn[j]; }
	v_lshlrev_b32_e32 v18, 16, v160
	v_and_b32_e32 v19, 0xffff0000, v160
	v_lshlrev_b32_e32 v20, 16, v161
	v_and_b32_e32 v21, 0xffff0000, v161
	v_lshlrev_b32_e32 v22, 16, v162
	v_and_b32_e32 v23, 0xffff0000, v162
	v_lshlrev_b32_e32 v24, 16, v163
	v_and_b32_e32 v25, 0xffff0000, v163
	global_load_dwordx4 v[160:163], v1, s[14:15]
	s_add_u32 s14, s14, 0x4000
	s_addc_u32 s15, s15, 0
	v_fma_f32 v10, v8, v10, v18
	v_fma_f32 v11, v8, v11, v19
	v_fma_f32 v12, v8, v12, v20
	v_fma_f32 v13, v8, v13, v21
	v_fma_f32 v14, v8, v14, v22
	v_fma_f32 v15, v8, v15, v23
	v_fma_f32 v16, v8, v16, v24
	v_fma_f32 v17, v8, v17, v25
	v_cvt_pk_bf16_f32 v34, v10, v11
	v_cvt_pk_bf16_f32 v35, v12, v13
	v_cvt_pk_bf16_f32 v36, v14, v15
	v_cvt_pk_bf16_f32 v37, v16, v17
	global_store_dwordx4 v1, v[34:37], s[0:1]
	s_add_u32 s0, s0, 0x4000
	s_addc_u32 s1, s1, 0
	s_waitcnt vmcnt(63)
	v_lshlrev_b32_e32 v18, 16, v164
	v_and_b32_e32 v19, 0xffff0000, v164
	v_lshlrev_b32_e32 v20, 16, v165
	v_and_b32_e32 v21, 0xffff0000, v165
	v_lshlrev_b32_e32 v22, 16, v166
	v_and_b32_e32 v23, 0xffff0000, v166
	v_lshlrev_b32_e32 v24, 16, v167
	v_and_b32_e32 v25, 0xffff0000, v167
	global_load_dwordx4 v[164:167], v1, s[14:15]
	s_add_u32 s14, s14, 0x4000
	s_addc_u32 s15, s15, 0
	v_fma_f32 v10, v8, v10, v18
	v_fma_f32 v11, v8, v11, v19
	v_fma_f32 v12, v8, v12, v20
	v_fma_f32 v13, v8, v13, v21
	v_fma_f32 v14, v8, v14, v22
	v_fma_f32 v15, v8, v15, v23
	v_fma_f32 v16, v8, v16, v24
	v_fma_f32 v17, v8, v17, v25
	v_cvt_pk_bf16_f32 v26, v10, v11
	v_cvt_pk_bf16_f32 v27, v12, v13
	v_cvt_pk_bf16_f32 v28, v14, v15
	v_cvt_pk_bf16_f32 v29, v16, v17
	global_store_dwordx4 v1, v[26:29], s[0:1]
	s_add_u32 s0, s0, 0x4000
	s_addc_u32 s1, s1, 0
	s_waitcnt vmcnt(63)
	v_lshlrev_b32_e32 v18, 16, v40
	v_and_b32_e32 v19, 0xffff0000, v40
	v_lshlrev_b32_e32 v20, 16, v41
	v_and_b32_e32 v21, 0xffff0000, v41
	v_lshlrev_b32_e32 v22, 16, v42
	v_and_b32_e32 v23, 0xffff0000, v42
	v_lshlrev_b32_e32 v24, 16, v43
	v_and_b32_e32 v25, 0xffff0000, v43
	global_load_dwordx4 v[40:43], v1, s[14:15]
	s_add_u32 s14, s14, 0x4000
	s_addc_u32 s15, s15, 0
	v_fma_f32 v10, v8, v10, v18
	v_fma_f32 v11, v8, v11, v19
	v_fma_f32 v12, v8, v12, v20
	v_fma_f32 v13, v8, v13, v21
	v_fma_f32 v14, v8, v14, v22
	v_fma_f32 v15, v8, v15, v23
	v_fma_f32 v16, v8, v16, v24
	v_fma_f32 v17, v8, v17, v25
	v_cvt_pk_bf16_f32 v34, v10, v11
	v_cvt_pk_bf16_f32 v35, v12, v13
	v_cvt_pk_bf16_f32 v36, v14, v15
	v_cvt_pk_bf16_f32 v37, v16, v17
	global_store_dwordx4 v1, v[34:37], s[0:1]
	s_add_u32 s0, s0, 0x4000
	s_addc_u32 s1, s1, 0
	s_waitcnt vmcnt(63)
	v_lshlrev_b32_e32 v18, 16, v44
	v_and_b32_e32 v19, 0xffff0000, v44
	v_lshlrev_b32_e32 v20, 16, v45
	v_and_b32_e32 v21, 0xffff0000, v45
	v_lshlrev_b32_e32 v22, 16, v46
	v_and_b32_e32 v23, 0xffff0000, v46
	v_lshlrev_b32_e32 v24, 16, v47
	v_and_b32_e32 v25, 0xffff0000, v47
	global_load_dwordx4 v[44:47], v1, s[14:15]
	s_add_u32 s14, s14, 0x4000
	s_addc_u32 s15, s15, 0
	v_fma_f32 v10, v8, v10, v18
	v_fma_f32 v11, v8, v11, v19
	v_fma_f32 v12, v8, v12, v20
	v_fma_f32 v13, v8, v13, v21
	v_fma_f32 v14, v8, v14, v22
	v_fma_f32 v15, v8, v15, v23
	v_fma_f32 v16, v8, v16, v24
	v_fma_f32 v17, v8, v17, v25
	v_cvt_pk_bf16_f32 v26, v10, v11
	v_cvt_pk_bf16_f32 v27, v12, v13
	v_cvt_pk_bf16_f32 v28, v14, v15
	v_cvt_pk_bf16_f32 v29, v16, v17
	global_store_dwordx4 v1, v[26:29], s[0:1]
	s_add_u32 s0, s0, 0x4000
	s_addc_u32 s1, s1, 0
	s_waitcnt vmcnt(63)
	v_lshlrev_b32_e32 v18, 16, v48
	v_and_b32_e32 v19, 0xffff0000, v48
	v_lshlrev_b32_e32 v20, 16, v49
	v_and_b32_e32 v21, 0xffff0000, v49
	v_lshlrev_b32_e32 v22, 16, v50
	v_and_b32_e32 v23, 0xffff0000, v50
	v_lshlrev_b32_e32 v24, 16, v51
	v_and_b32_e32 v25, 0xffff0000, v51
	global_load_dwordx4 v[48:51], v1, s[14:15]
	s_add_u32 s14, s14, 0x4000
	s_addc_u32 s15, s15, 0
	v_fma_f32 v10, v8, v10, v18
	v_fma_f32 v11, v8, v11, v19
	v_fma_f32 v12, v8, v12, v20
	v_fma_f32 v13, v8, v13, v21
	v_fma_f32 v14, v8, v14, v22
	v_fma_f32 v15, v8, v15, v23
	v_fma_f32 v16, v8, v16, v24
	v_fma_f32 v17, v8, v17, v25
	v_cvt_pk_bf16_f32 v34, v10, v11
	v_cvt_pk_bf16_f32 v35, v12, v13
	v_cvt_pk_bf16_f32 v36, v14, v15
	v_cvt_pk_bf16_f32 v37, v16, v17
	global_store_dwordx4 v1, v[34:37], s[0:1]
	s_add_u32 s0, s0, 0x4000
	s_addc_u32 s1, s1, 0
	s_waitcnt vmcnt(63)
	v_lshlrev_b32_e32 v18, 16, v52
	v_and_b32_e32 v19, 0xffff0000, v52
	v_lshlrev_b32_e32 v20, 16, v53
	v_and_b32_e32 v21, 0xffff0000, v53
	v_lshlrev_b32_e32 v22, 16, v54
	v_and_b32_e32 v23, 0xffff0000, v54
	v_lshlrev_b32_e32 v24, 16, v55
	v_and_b32_e32 v25, 0xffff0000, v55
	global_load_dwordx4 v[52:55], v1, s[14:15]
	s_add_u32 s14, s14, 0x4000
	s_addc_u32 s15, s15, 0
	v_fma_f32 v10, v8, v10, v18
	v_fma_f32 v11, v8, v11, v19
	v_fma_f32 v12, v8, v12, v20
	v_fma_f32 v13, v8, v13, v21
	v_fma_f32 v14, v8, v14, v22
	v_fma_f32 v15, v8, v15, v23
	v_fma_f32 v16, v8, v16, v24
	v_fma_f32 v17, v8, v17, v25
	v_cvt_pk_bf16_f32 v26, v10, v11
	v_cvt_pk_bf16_f32 v27, v12, v13
	v_cvt_pk_bf16_f32 v28, v14, v15
	v_cvt_pk_bf16_f32 v29, v16, v17
	global_store_dwordx4 v1, v[26:29], s[0:1]
	s_add_u32 s0, s0, 0x4000
	s_addc_u32 s1, s1, 0
	s_waitcnt vmcnt(63)
	v_lshlrev_b32_e32 v18, 16, v56
	v_and_b32_e32 v19, 0xffff0000, v56
	v_lshlrev_b32_e32 v20, 16, v57
	v_and_b32_e32 v21, 0xffff0000, v57
	v_lshlrev_b32_e32 v22, 16, v58
	v_and_b32_e32 v23, 0xffff0000, v58
	v_lshlrev_b32_e32 v24, 16, v59
	v_and_b32_e32 v25, 0xffff0000, v59
	global_load_dwordx4 v[56:59], v1, s[14:15]
	s_add_u32 s14, s14, 0x4000
	s_addc_u32 s15, s15, 0
	v_fma_f32 v10, v8, v10, v18
	v_fma_f32 v11, v8, v11, v19
	v_fma_f32 v12, v8, v12, v20
	v_fma_f32 v13, v8, v13, v21
	v_fma_f32 v14, v8, v14, v22
	v_fma_f32 v15, v8, v15, v23
	v_fma_f32 v16, v8, v16, v24
	v_fma_f32 v17, v8, v17, v25
	v_cvt_pk_bf16_f32 v34, v10, v11
	v_cvt_pk_bf16_f32 v35, v12, v13
	v_cvt_pk_bf16_f32 v36, v14, v15
	v_cvt_pk_bf16_f32 v37, v16, v17
	global_store_dwordx4 v1, v[34:37], s[0:1]
	s_add_u32 s0, s0, 0x4000
	s_addc_u32 s1, s1, 0
	s_waitcnt vmcnt(63)
; __device__ __forceinline__ unsigned cvt_pk_bf16(float lo, float hi) { unsigned r; asm volatile("v_cvt_pk_bf16_f32 %0, %1, %2" : "=v"(r) : "v"(lo), "v"(hi)); return r; }
; __global__ void __launch_bounds__(512, 2) hse_fwd(Params P) {
;     ...
;                     for (int c = 0; c < 128; c += 32) { float vn[32]; const int cn = c + 32 < 128 ? c + 32 : c;
; #pragma unroll
;                         for (int j = 0; j < 32; ++j) vn[j] = __uint_as_float((unsigned)p[(size_t)(cn + j) * 8192] << 16);
; #pragma unroll
;                         for (int j = 0; j < 32; j += 2) {
;                             const float r0 = run; run = g64 * run + v[j]; const float r1 = run; run = g64 * run + v[j + 1];
;                             const bool odd = lane & 1; const float mine = odd ? r1 : r0, send = odd ? r0 : r1;
;                             const float recv = __int_as_float(__builtin_amdgcn_mov_dpp(__float_as_int(send), 0xB1, 0xF, 0xF, false));
;                             const unsigned w = odd ? cvt_pk_bf16(recv, mine) : cvt_pk_bf16(mine, recv);
;                             *(unsigned*)(pb - (lane & 1) + (size_t)(c + j + (odd ? 1 : 0)) * 8192) = w; }
; #pragma unroll
;                         for (int j = 0; j < 32; ++j) v[j] = vn[j]; }
	v_lshlrev_b32_e32 v18, 16, v60
	v_and_b32_e32 v19, 0xffff0000, v60
	v_lshlrev_b32_e32 v20, 16, v61
	v_and_b32_e32 v21, 0xffff0000, v61
	v_lshlrev_b32_e32 v22, 16, v62
	v_and_b32_e32 v23, 0xffff0000, v62
	v_lshlrev_b32_e32 v24, 16, v63
	v_and_b32_e32 v25, 0xffff0000, v63
	global_load_dwordx4 v[60:63], v1, s[14:15]
	s_add_u32 s14, s14, 0x4000
	s_addc_u32 s15, s15, 0
	v_fma_f32 v10, v8, v10, v18
	v_fma_f32 v11, v8, v11, v19
	v_fma_f32 v12, v8, v12, v20
	v_fma_f32 v13, v8, v13, v21
	v_fma_f32 v14, v8, v14, v22
	v_fma_f32 v15, v8, v15, v23
	v_fma_f32 v16, v8, v16, v24
	v_fma_f32 v17, v8, v17, v25
	v_cvt_pk_bf16_f32 v26, v10, v11
	v_cvt_pk_bf16_f32 v27, v12, v13
	v_cvt_pk_bf16_f32 v28, v14, v15
	v_cvt_pk_bf16_f32 v29, v16, v17
	global_store_dwordx4 v1, v[26:29], s[0:1]
	s_add_u32 s0, s0, 0x4000
	s_addc_u32 s1, s1, 0
	s_waitcnt vmcnt(63)
	v_lshlrev_b32_e32 v18, 16, v64
	v_and_b32_e32 v19, 0xffff0000, v64
	v_lshlrev_b32_e32 v20, 16, v65
	v_and_b32_e32 v21, 0xffff0000, v65
	v_lshlrev_b32_e32 v22, 16, v66
	v_and_b32_e32 v23, 0xffff0000, v66
	v_lshlrev_b32_e32 v24, 16, v67
	v_and_b32_e32 v25, 0xffff0000, v67
	global_load_dwordx4 v[64:67], v1, s[14:15]
	s_add_u32 s14, s14, 0x4000
	s_addc_u32 s15, s15, 0
	v_fma_f32 v10, v8, v10, v18
	v_fma_f32 v11, v8, v11, v19
	v_fma_f32 v12, v8, v12, v20
	v_fma_f32 v13, v8, v13, v21
	v_fma_f32 v14, v8, v14, v22
	v_fma_f32 v15, v8, v15, v23
	v_fma_f32 v16, v8, v16, v24
	v_fma_f32 v17, v8, v17, v25
	v_cvt_pk_bf16_f32 v34, v10, v11
	v_cvt_pk_bf16_f32 v35, v12, v13
	v_cvt_pk_bf16_f32 v36, v14, v15
	v_cvt_pk_bf16_f32 v37, v16, v17
	global_store_dwordx4 v1, v[34:37], s[0:1]
	s_add_u32 s0, s0, 0x4000
	s_addc_u32 s1, s1, 0
	s_waitcnt vmcnt(63)
	v_lshlrev_b32_e32 v18, 16, v68
	v_and_b32_e32 v19, 0xffff0000, v68
	v_lshlrev_b32_e32 v20, 16, v69
	v_and_b32_e32 v21, 0xffff0000, v69
	v_lshlrev_b32_e32 v22, 16, v70
	v_and_b32_e32 v23, 0xffff0000, v70
	v_lshlrev_b32_e32 v24, 16, v71
	v_and_b32_e32 v25, 0xffff0000, v71
	global_load_dwordx4 v[68:71], v1, s[14:15]
	s_add_u32 s14, s14, 0x4000
	s_addc_u32 s15, s15, 0
	v_fma_f32 v10, v8, v10, v18
	v_fma_f32 v11, v8, v11, v19
	v_fma_f32 v12, v8, v12, v20
	v_fma_f32 v13, v8, v13, v21
	v_fma_f32 v14, v8, v14, v22
	v_fma_f32 v15, v8, v15, v23
	v_fma_f32 v16, v8, v16, v24
	v_fma_f32 v17, v8, v17, v25
	v_cvt_pk_bf16_f32 v26, v10, v11
	v_cvt_pk_bf16_f32 v27, v12, v13
	v_cvt_pk_bf16_f32 v28, v14, v15
	v_cvt_pk_bf16_f32 v29, v16, v17
	global_store_dwordx4 v1, v[26:29], s[0:1]
	s_add_u32 s0, s0, 0x4000
	s_addc_u32 s1, s1, 0
	s_waitcnt vmcnt(63)
	v_lshlrev_b32_e32 v18, 16, v72
	v_and_b32_e32 v19, 0xffff0000, v72
	v_lshlrev_b32_e32 v20, 16, v73
	v_and_b32_e32 v21, 0xffff0000, v73
	v_lshlrev_b32_e32 v22, 16, v74
	v_and_b32_e32 v23, 0xffff0000, v74
	v_lshlrev_b32_e32 v24, 16, v75
	v_and_b32_e32 v25, 0xffff0000, v75
	global_load_dwordx4 v[72:75], v1, s[14:15]
	s_add_u32 s14, s14, 0x4000
	s_addc_u32 s15, s15, 0
	v_fma_f32 v10, v8, v10, v18
	v_fma_f32 v11, v8, v11, v19
	v_fma_f32 v12, v8, v12, v20
	v_fma_f32 v13, v8, v13, v21
	v_fma_f32 v14, v8, v14, v22
	v_fma_f32 v15, v8, v15, v23
	v_fma_f32 v16, v8, v16, v24
	v_fma_f32 v17, v8, v17, v25
	v_cvt_pk_bf16_f32 v34, v10, v11
	v_cvt_pk_bf16_f32 v35, v12, v13
	v_cvt_pk_bf16_f32 v36, v14, v15
	v_cvt_pk_bf16_f32 v37, v16, v17
	global_store_dwordx4 v1, v[34:37], s[0:1]
	s_add_u32 s0, s0, 0x4000
	s_addc_u32 s1, s1, 0
	s_waitcnt vmcnt(63)
	v_lshlrev_b32_e32 v18, 16, v76
	v_and_b32_e32 v19, 0xffff0000, v76
	v_lshlrev_b32_e32 v20, 16, v77
	v_and_b32_e32 v21, 0xffff0000, v77
	v_lshlrev_b32_e32 v22, 16, v78
	v_and_b32_e32 v23, 0xffff0000, v78
	v_lshlrev_b32_e32 v24, 16, v79
	v_and_b32_e32 v25, 0xffff0000, v79
	global_load_dwordx4 v[76:79], v1, s[14:15]
	s_add_u32 s14, s14, 0x4000
	s_addc_u32 s15, s15, 0
	v_fma_f32 v10, v8, v10, v18
	v_fma_f32 v11, v8, v11, v19
	v_fma_f32 v12, v8, v12, v20
	v_fma_f32 v13, v8, v13, v21
	v_fma_f32 v14, v8, v14, v22
	v_fma_f32 v15, v8, v15, v23
	v_fma_f32 v16, v8, v16, v24
	v_fma_f32 v17, v8, v17, v25
	v_cvt_pk_bf16_f32 v26, v10, v11
	v_cvt_pk_bf16_f32 v27, v12, v13
	v_cvt_pk_bf16_f32 v28, v14, v15
	v_cvt_pk_bf16_f32 v29, v16, v17
	global_store_dwordx4 v1, v[26:29], s[0:1]
	s_add_u32 s0, s0, 0x4000
	s_addc_u32 s1, s1, 0
	s_waitcnt vmcnt(63)
	v_lshlrev_b32_e32 v18, 16, v80
	v_and_b32_e32 v19, 0xffff0000, v80
	v_lshlrev_b32_e32 v20, 16, v81
	v_and_b32_e32 v21, 0xffff0000, v81
	v_lshlrev_b32_e32 v22, 16, v82
	v_and_b32_e32 v23, 0xffff0000, v82
	v_lshlrev_b32_e32 v24, 16, v83
	v_and_b32_e32 v25, 0xffff0000, v83
	global_load_dwordx4 v[80:83], v1, s[14:15]
	s_add_u32 s14, s14, 0x4000
	s_addc_u32 s15, s15, 0
	v_fma_f32 v10, v8, v10, v18
	v_fma_f32 v11, v8, v11, v19
	v_fma_f32 v12, v8, v12, v20
	v_fma_f32 v13, v8, v13, v21
	v_fma_f32 v14, v8, v14, v22
	v_fma_f32 v15, v8, v15, v23
	v_fma_f32 v16, v8, v16, v24
	v_fma_f32 v17, v8, v17, v25
	v_cvt_pk_bf16_f32 v34, v10, v11
	v_cvt_pk_bf16_f32 v35, v12, v13
	v_cvt_pk_bf16_f32 v36, v14, v15
	v_cvt_pk_bf16_f32 v37, v16, v17
	global_store_dwordx4 v1, v[34:37], s[0:1]
	s_add_u32 s0, s0, 0x4000
	s_addc_u32 s1, s1, 0
	s_waitcnt vmcnt(63)
	v_lshlrev_b32_e32 v18, 16, v84
	v_and_b32_e32 v19, 0xffff0000, v84
	v_lshlrev_b32_e32 v20, 16, v85
	v_and_b32_e32 v21, 0xffff0000, v85
	v_lshlrev_b32_e32 v22, 16, v86
	v_and_b32_e32 v23, 0xffff0000, v86
	v_lshlrev_b32_e32 v24, 16, v87
	v_and_b32_e32 v25, 0xffff0000, v87
	global_load_dwordx4 v[84:87], v1, s[14:15]
	s_add_u32 s14, s14, 0x4000
	s_addc_u32 s15, s15, 0
	v_fma_f32 v10, v8, v10, v18
	v_fma_f32 v11, v8, v11, v19
	v_fma_f32 v12, v8, v12, v20
	v_fma_f32 v13, v8, v13, v21
	v_fma_f32 v14, v8, v14, v22
	v_fma_f32 v15, v8, v15, v23
	v_fma_f32 v16, v8, v16, v24
	v_fma_f32 v17, v8, v17, v25
	v_cvt_pk_bf16_f32 v26, v10, v11
	v_cvt_pk_bf16_f32 v27, v12, v13
	v_cvt_pk_bf16_f32 v28, v14, v15
	v_cvt_pk_bf16_f32 v29, v16, v17
	global_store_dwordx4 v1, v[26:29], s[0:1]
	s_add_u32 s0, s0, 0x4000
	s_addc_u32 s1, s1, 0
	s_waitcnt vmcnt(63)
; __device__ __forceinline__ unsigned cvt_pk_bf16(float lo, float hi) { unsigned r; asm volatile("v_cvt_pk_bf16_f32 %0, %1, %2" : "=v"(r) : "v"(lo), "v"(hi)); return r; }
; __global__ void __launch_bounds__(512, 2) hse_fwd(Params P) {
;     ...
;                     for (int c = 0; c < 128; c += 32) { float vn[32]; const int cn = c + 32 < 128 ? c + 32 : c;
; #pragma unroll
;                         for (int j = 0; j < 32; ++j) vn[j] = __uint_as_float((unsigned)p[(size_t)(cn + j) * 8192] << 16);
; #pragma unroll
;                         for (int j = 0; j < 32; j += 2) {
;                             const float r0 = run; run = g64 * run + v[j]; const float r1 = run; run = g64 * run + v[j + 1];
;                             const bool odd = lane & 1; const float mine = odd ? r1 : r0, send = odd ? r0 : r1;
;                             const float recv = __int_as_float(__builtin_amdgcn_mov_dpp(__float_as_int(send), 0xB1, 0xF, 0xF, false));
;                             const unsigned w = odd ? cvt_pk_bf16(recv, mine) : cvt_pk_bf16(mine, recv);
;                             *(unsigned*)(pb - (lane & 1) + (size_t)(c + j + (odd ? 1 : 0)) * 8192) = w; }
; #pragma unroll
;                         for (int j = 0; j < 32; ++j) v[j] = vn[j]; }
	v_lshlrev_b32_e32 v18, 16, v88
	v_and_b32_e32 v19, 0xffff0000, v88
	v_lshlrev_b32_e32 v20, 16, v89
	v_and_b32_e32 v21, 0xffff0000, v89
	v_lshlrev_b32_e32 v22, 16, v90
	v_and_b32_e32 v23, 0xffff0000, v90
	v_lshlrev_b32_e32 v24, 16, v91
	v_and_b32_e32 v25, 0xffff0000, v91
	global_load_dwordx4 v[88:91], v1, s[14:15]
	s_add_u32 s14, s14, 0x4000
	s_addc_u32 s15, s15, 0
	v_fma_f32 v10, v8, v10, v18
	v_fma_f32 v11, v8, v11, v19
	v_fma_f32 v12, v8, v12, v20
	v_fma_f32 v13, v8, v13, v21
	v_fma_f32 v14, v8, v14, v22
	v_fma_f32 v15, v8, v15, v23
	v_fma_f32 v16, v8, v16, v24
	v_fma_f32 v17, v8, v17, v25
	v_cvt_pk_bf16_f32 v34, v10, v11
	v_cvt_pk_bf16_f32 v35, v12, v13
	v_cvt_pk_bf16_f32 v36, v14, v15
	v_cvt_pk_bf16_f32 v37, v16, v17
	global_store_dwordx4 v1, v[34:37], s[0:1]
	s_add_u32 s0, s0, 0x4000
	s_addc_u32 s1, s1, 0
	s_waitcnt vmcnt(63)
	v_lshlrev_b32_e32 v18, 16, v92
	v_and_b32_e32 v19, 0xffff0000, v92
	v_lshlrev_b32_e32 v20, 16, v93
	v_and_b32_e32 v21, 0xffff0000, v93
	v_lshlrev_b32_e32 v22, 16, v94
	v_and_b32_e32 v23, 0xffff0000, v94
	v_lshlrev_b32_e32 v24, 16, v95
	v_and_b32_e32 v25, 0xffff0000, v95
	global_load_dwordx4 v[92:95], v1, s[14:15]
	s_add_u32 s14, s14, 0x4000
	s_addc_u32 s15, s15, 0
	v_fma_f32 v10, v8, v10, v18
	v_fma_f32 v11, v8, v11, v19
	v_fma_f32 v12, v8, v12, v20
	v_fma_f32 v13, v8, v13, v21
	v_fma_f32 v14, v8, v14, v22
	v_fma_f32 v15, v8, v15, v23
	v_fma_f32 v16, v8, v16, v24
	v_fma_f32 v17, v8, v17, v25
	v_cvt_pk_bf16_f32 v26, v10, v11
	v_cvt_pk_bf16_f32 v27, v12, v13
	v_cvt_pk_bf16_f32 v28, v14, v15
	v_cvt_pk_bf16_f32 v29, v16, v17
	global_store_dwordx4 v1, v[26:29], s[0:1]
	s_add_u32 s0, s0, 0x4000
	s_addc_u32 s1, s1, 0
	s_waitcnt vmcnt(63)
	v_lshlrev_b32_e32 v18, 16, v96
	v_and_b32_e32 v19, 0xffff0000, v96
	v_lshlrev_b32_e32 v20, 16, v97
	v_and_b32_e32 v21, 0xffff0000, v97
	v_lshlrev_b32_e32 v22, 16, v98
	v_and_b32_e32 v23, 0xffff0000, v98
	v_lshlrev_b32_e32 v24, 16, v99
	v_and_b32_e32 v25, 0xffff0000, v99
	global_load_dwordx4 v[96:99], v1, s[14:15]
	s_add_u32 s14, s14, 0x4000
	s_addc_u32 s15, s15, 0
	v_fma_f32 v10, v8, v10, v18
	v_fma_f32 v11, v8, v11, v19
	v_fma_f32 v12, v8, v12, v20
	v_fma_f32 v13, v8, v13, v21
	v_fma_f32 v14, v8, v14, v22
	v_fma_f32 v15, v8, v15, v23
	v_fma_f32 v16, v8, v16, v24
	v_fma_f32 v17, v8, v17, v25
	v_cvt_pk_bf16_f32 v34, v10, v11
	v_cvt_pk_bf16_f32 v35, v12, v13
	v_cvt_pk_bf16_f32 v36, v14, v15
	v_cvt_pk_bf16_f32 v37, v16, v17
	global_store_dwordx4 v1, v[34:37], s[0:1]
	s_add_u32 s0, s0, 0x4000
	s_addc_u32 s1, s1, 0
	s_waitcnt vmcnt(63)
	v_lshlrev_b32_e32 v18, 16, v100
	v_and_b32_e32 v19, 0xffff0000, v100
	v_lshlrev_b32_e32 v20, 16, v101
	v_and_b32_e32 v21, 0xffff0000, v101
	v_lshlrev_b32_e32 v22, 16, v102
	v_and_b32_e32 v23, 0xffff0000, v102
	v_lshlrev_b32_e32 v24, 16, v103
	v_and_b32_e32 v25, 0xffff0000, v103
	global_load_dwordx4 v[100:103], v1, s[14:15]
	s_add_u32 s14, s14, 0x4000
	s_addc_u32 s15, s15, 0
	v_fma_f32 v10, v8, v10, v18
	v_fma_f32 v11, v8, v11, v19
	v_fma_f32 v12, v8, v12, v20
	v_fma_f32 v13, v8, v13, v21
	v_fma_f32 v14, v8, v14, v22
	v_fma_f32 v15, v8, v15, v23
	v_fma_f32 v16, v8, v16, v24
	v_fma_f32 v17, v8, v17, v25
	v_cvt_pk_bf16_f32 v26, v10, v11
	v_cvt_pk_bf16_f32 v27, v12, v13
	v_cvt_pk_bf16_f32 v28, v14, v15
	v_cvt_pk_bf16_f32 v29, v16, v17
	global_store_dwordx4 v1, v[26:29], s[0:1]
	s_add_u32 s0, s0, 0x4000
	s_addc_u32 s1, s1, 0
	s_waitcnt vmcnt(63)
	v_lshlrev_b32_e32 v18, 16, v104
	v_and_b32_e32 v19, 0xffff0000, v104
	v_lshlrev_b32_e32 v20, 16, v105
	v_and_b32_e32 v21, 0xffff0000, v105
	v_lshlrev_b32_e32 v22, 16, v106
	v_and_b32_e32 v23, 0xffff0000, v106
	v_lshlrev_b32_e32 v24, 16, v107
	v_and_b32_e32 v25, 0xffff0000, v107
	global_load_dwordx4 v[104:107], v1, s[14:15]
	s_add_u32 s14, s14, 0x4000
	s_addc_u32 s15, s15, 0
	v_fma_f32 v10, v8, v10, v18
	v_fma_f32 v11, v8, v11, v19
	v_fma_f32 v12, v8, v12, v20
	v_fma_f32 v13, v8, v13, v21
	v_fma_f32 v14, v8, v14, v22
	v_fma_f32 v15, v8, v15, v23
	v_fma_f32 v16, v8, v16, v24
	v_fma_f32 v17, v8, v17, v25
	v_cvt_pk_bf16_f32 v34, v10, v11
	v_cvt_pk_bf16_f32 v35, v12, v13
	v_cvt_pk_bf16_f32 v36, v14, v15
	v_cvt_pk_bf16_f32 v37, v16, v17
	global_store_dwordx4 v1, v[34:37], s[0:1]
	s_add_u32 s0, s0, 0x4000
	s_addc_u32 s1, s1, 0
	s_waitcnt vmcnt(63)
	v_lshlrev_b32_e32 v18, 16, v108
	v_and_b32_e32 v19, 0xffff0000, v108
	v_lshlrev_b32_e32 v20, 16, v109
	v_and_b32_e32 v21, 0xffff0000, v109
	v_lshlrev_b32_e32 v22, 16, v110
	v_and_b32_e32 v23, 0xffff0000, v110
	v_lshlrev_b32_e32 v24, 16, v111
	v_and_b32_e32 v25, 0xffff0000, v111
	global_load_dwordx4 v[108:111], v1, s[14:15]
	s_add_u32 s14, s14, 0x4000
	s_addc_u32 s15, s15, 0
	v_fma_f32 v10, v8, v10, v18
	v_fma_f32 v11, v8, v11, v19
	v_fma_f32 v12, v8, v12, v20
	v_fma_f32 v13, v8, v13, v21
	v_fma_f32 v14, v8, v14, v22
	v_fma_f32 v15, v8, v15, v23
	v_fma_f32 v16, v8, v16, v24
	v_fma_f32 v17, v8, v17, v25
	v_cvt_pk_bf16_f32 v26, v10, v11
	v_cvt_pk_bf16_f32 v27, v12, v13
	v_cvt_pk_bf16_f32 v28, v14, v15
	v_cvt_pk_bf16_f32 v29, v16, v17
	global_store_dwordx4 v1, v[26:29], s[0:1]
	s_add_u32 s0, s0, 0x4000
	s_addc_u32 s1, s1, 0
	s_waitcnt vmcnt(63)
	v_lshlrev_b32_e32 v18, 16, v112
	v_and_b32_e32 v19, 0xffff0000, v112
	v_lshlrev_b32_e32 v20, 16, v113
	v_and_b32_e32 v21, 0xffff0000, v113
	v_lshlrev_b32_e32 v22, 16, v114
	v_and_b32_e32 v23, 0xffff0000, v114
	v_lshlrev_b32_e32 v24, 16, v115
	v_and_b32_e32 v25, 0xffff0000, v115
	global_load_dwordx4 v[112:115], v1, s[14:15]
	s_add_u32 s14, s14, 0x4000
	s_addc_u32 s15, s15, 0
	v_fma_f32 v10, v8, v10, v18
	v_fma_f32 v11, v8, v11, v19
	v_fma_f32 v12, v8, v12, v20
	v_fma_f32 v13, v8, v13, v21
	v_fma_f32 v14, v8, v14, v22
	v_fma_f32 v15, v8, v15, v23
	v_fma_f32 v16, v8, v16, v24
	v_fma_f32 v17, v8, v17, v25
	v_cvt_pk_bf16_f32 v34, v10, v11
	v_cvt_pk_bf16_f32 v35, v12, v13
	v_cvt_pk_bf16_f32 v36, v14, v15
	v_cvt_pk_bf16_f32 v37, v16, v17
	global_store_dwordx4 v1, v[34:37], s[0:1]
	s_add_u32 s0, s0, 0x4000
	s_addc_u32 s1, s1, 0
	s_waitcnt vmcnt(63)
; __device__ __forceinline__ unsigned cvt_pk_bf16(float lo, float hi) { unsigned r; asm volatile("v_cvt_pk_bf16_f32 %0, %1, %2" : "=v"(r) : "v"(lo), "v"(hi)); return r; }
; __global__ void __launch_bounds__(512, 2) hse_fwd(Params P) {
;     ...
;                     for (int c = 0; c < 128; c += 32) { float vn[32]; const int cn = c + 32 < 128 ? c + 32 : c;
; #pragma unroll
;                         for (int j = 0; j < 32; ++j) vn[j] = __uint_as_float((unsigned)p[(size_t)(cn + j) * 8192] << 16);
; #pragma unroll
;                         for (int j = 0; j < 32; j += 2) {
;                             const float r0 = run; run = g64 * run + v[j]; const float r1 = run; run = g64 * run + v[j + 1];
;                             const bool odd = lane & 1; const float mine = odd ? r1 : r0, send = odd ? r0 : r1;
;                             const float recv = __int_as_float(__builtin_amdgcn_mov_dpp(__float_as_int(send), 0xB1, 0xF, 0xF, false));
;                             const unsigned w = odd ? cvt_pk_bf16(recv, mine) : cvt_pk_bf16(mine, recv);
;                             *(unsigned*)(pb - (lane & 1) + (size_t)(c + j + (odd ? 1 : 0)) * 8192) = w; }
; #pragma unroll
;                         for (int j = 0; j < 32; ++j) v[j] = vn[j]; }
	v_lshlrev_b32_e32 v18, 16, v116
	v_and_b32_e32 v19, 0xffff0000, v116
	v_lshlrev_b32_e32 v20, 16, v117
	v_and_b32_e32 v21, 0xffff0000, v117
	v_lshlrev_b32_e32 v22, 16, v118
	v_and_b32_e32 v23, 0xffff0000, v118
	v_lshlrev_b32_e32 v24, 16, v119
	v_and_b32_e32 v25, 0xffff0000, v119
	global_load_dwordx4 v[116:119], v1, s[14:15]
	s_add_u32 s14, s14, 0x4000
	s_addc_u32 s15, s15, 0
	v_fma_f32 v10, v8, v10, v18
	v_fma_f32 v11, v8, v11, v19
	v_fma_f32 v12, v8, v12, v20
	v_fma_f32 v13, v8, v13, v21
	v_fma_f32 v14, v8, v14, v22
	v_fma_f32 v15, v8, v15, v23
	v_fma_f32 v16, v8, v16, v24
	v_fma_f32 v17, v8, v17, v25
	v_cvt_pk_bf16_f32 v26, v10, v11
	v_cvt_pk_bf16_f32 v27, v12, v13
	v_cvt_pk_bf16_f32 v28, v14, v15
	v_cvt_pk_bf16_f32 v29, v16, v17
	global_store_dwordx4 v1, v[26:29], s[0:1]
	s_add_u32 s0, s0, 0x4000
	s_addc_u32 s1, s1, 0
	s_waitcnt vmcnt(63)
	v_lshlrev_b32_e32 v18, 16, v120
	v_and_b32_e32 v19, 0xffff0000, v120
	v_lshlrev_b32_e32 v20, 16, v121
	v_and_b32_e32 v21, 0xffff0000, v121
	v_lshlrev_b32_e32 v22, 16, v122
	v_and_b32_e32 v23, 0xffff0000, v122
	v_lshlrev_b32_e32 v24, 16, v123
	v_and_b32_e32 v25, 0xffff0000, v123
	global_load_dwordx4 v[120:123], v1, s[14:15]
	s_add_u32 s14, s14, 0x4000
	s_addc_u32 s15, s15, 0
	v_fma_f32 v10, v8, v10, v18
	v_fma_f32 v11, v8, v11, v19
	v_fma_f32 v12, v8, v12, v20
	v_fma_f32 v13, v8, v13, v21
	v_fma_f32 v14, v8, v14, v22
	v_fma_f32 v15, v8, v15, v23
	v_fma_f32 v16, v8, v16, v24
	v_fma_f32 v17, v8, v17, v25
	v_cvt_pk_bf16_f32 v34, v10, v11
	v_cvt_pk_bf16_f32 v35, v12, v13
	v_cvt_pk_bf16_f32 v36, v14, v15
	v_cvt_pk_bf16_f32 v37, v16, v17
	global_store_dwordx4 v1, v[34:37], s[0:1]
	s_add_u32 s0, s0, 0x4000
	s_addc_u32 s1, s1, 0
	s_waitcnt vmcnt(63)
	v_lshlrev_b32_e32 v18, 16, v124
	v_and_b32_e32 v19, 0xffff0000, v124
	v_lshlrev_b32_e32 v20, 16, v125
	v_and_b32_e32 v21, 0xffff0000, v125
	v_lshlrev_b32_e32 v22, 16, v126
	v_and_b32_e32 v23, 0xffff0000, v126
	v_lshlrev_b32_e32 v24, 16, v127
	v_and_b32_e32 v25, 0xffff0000, v127
	global_load_dwordx4 v[124:127], v1, s[14:15]
	s_add_u32 s14, s14, 0x4000
	s_addc_u32 s15, s15, 0
	v_fma_f32 v10, v8, v10, v18
	v_fma_f32 v11, v8, v11, v19
	v_fma_f32 v12, v8, v12, v20
	v_fma_f32 v13, v8, v13, v21
	v_fma_f32 v14, v8, v14, v22
	v_fma_f32 v15, v8, v15, v23
	v_fma_f32 v16, v8, v16, v24
	v_fma_f32 v17, v8, v17, v25
	v_cvt_pk_bf16_f32 v26, v10, v11
	v_cvt_pk_bf16_f32 v27, v12, v13
	v_cvt_pk_bf16_f32 v28, v14, v15
	v_cvt_pk_bf16_f32 v29, v16, v17
	global_store_dwordx4 v1, v[26:29], s[0:1]
	s_add_u32 s0, s0, 0x4000
	s_addc_u32 s1, s1, 0
	s_waitcnt vmcnt(63)
	v_lshlrev_b32_e32 v18, 16, v128
	v_and_b32_e32 v19, 0xffff0000, v128
	v_lshlrev_b32_e32 v20, 16, v129
	v_and_b32_e32 v21, 0xffff0000, v129
	v_lshlrev_b32_e32 v22, 16, v130
	v_and_b32_e32 v23, 0xffff0000, v130
	v_lshlrev_b32_e32 v24, 16, v131
	v_and_b32_e32 v25, 0xffff0000, v131
	global_load_dwordx4 v[128:131], v1, s[14:15]
	s_add_u32 s14, s14, 0x4000
	s_addc_u32 s15, s15, 0
	v_fma_f32 v10, v8, v10, v18
	v_fma_f32 v11, v8, v11, v19
	v_fma_f32 v12, v8, v12, v20
	v_fma_f32 v13, v8, v13, v21
	v_fma_f32 v14, v8, v14, v22
	v_fma_f32 v15, v8, v15, v23
	v_fma_f32 v16, v8, v16, v24
	v_fma_f32 v17, v8, v17, v25
	v_cvt_pk_bf16_f32 v34, v10, v11
	v_cvt_pk_bf16_f32 v35, v12, v13
	v_cvt_pk_bf16_f32 v36, v14, v15
	v_cvt_pk_bf16_f32 v37, v16, v17
	global_store_dwordx4 v1, v[34:37], s[0:1]
	s_add_u32 s0, s0, 0x4000
	s_addc_u32 s1, s1, 0
	s_waitcnt vmcnt(63)
	v_lshlrev_b32_e32 v18, 16, v132
	v_and_b32_e32 v19, 0xffff0000, v132
	v_lshlrev_b32_e32 v20, 16, v133
	v_and_b32_e32 v21, 0xffff0000, v133
	v_lshlrev_b32_e32 v22, 16, v134
	v_and_b32_e32 v23, 0xffff0000, v134
	v_lshlrev_b32_e32 v24, 16, v135
	v_and_b32_e32 v25, 0xffff0000, v135
	global_load_dwordx4 v[132:135], v1, s[14:15]
	s_add_u32 s14, s14, 0x4000
	s_addc_u32 s15, s15, 0
	v_fma_f32 v10, v8, v10, v18
	v_fma_f32 v11, v8, v11, v19
	v_fma_f32 v12, v8, v12, v20
	v_fma_f32 v13, v8, v13, v21
	v_fma_f32 v14, v8, v14, v22
	v_fma_f32 v15, v8, v15, v23
	v_fma_f32 v16, v8, v16, v24
	v_fma_f32 v17, v8, v17, v25
	v_cvt_pk_bf16_f32 v26, v10, v11
	v_cvt_pk_bf16_f32 v27, v12, v13
	v_cvt_pk_bf16_f32 v28, v14, v15
	v_cvt_pk_bf16_f32 v29, v16, v17
	global_store_dwordx4 v1, v[26:29], s[0:1]
	s_add_u32 s0, s0, 0x4000
	s_addc_u32 s1, s1, 0
	s_waitcnt vmcnt(63)
	v_lshlrev_b32_e32 v18, 16, v136
	v_and_b32_e32 v19, 0xffff0000, v136
	v_lshlrev_b32_e32 v20, 16, v137
	v_and_b32_e32 v21, 0xffff0000, v137
	v_lshlrev_b32_e32 v22, 16, v138
	v_and_b32_e32 v23, 0xffff0000, v138
	v_lshlrev_b32_e32 v24, 16, v139
	v_and_b32_e32 v25, 0xffff0000, v139
	global_load_dwordx4 v[136:139], v1, s[14:15]
	s_add_u32 s14, s14, 0x4000
	s_addc_u32 s15, s15, 0
	v_fma_f32 v10, v8, v10, v18
	v_fma_f32 v11, v8, v11, v19
	v_fma_f32 v12, v8, v12, v20
	v_fma_f32 v13, v8, v13, v21
	v_fma_f32 v14, v8, v14, v22
	v_fma_f32 v15, v8, v15, v23
	v_fma_f32 v16, v8, v16, v24
	v_fma_f32 v17, v8, v17, v25
	v_cvt_pk_bf16_f32 v34, v10, v11
	v_cvt_pk_bf16_f32 v35, v12, v13
	v_cvt_pk_bf16_f32 v36, v14, v15
	v_cvt_pk_bf16_f32 v37, v16, v17
	global_store_dwordx4 v1, v[34:37], s[0:1]
	s_add_u32 s0, s0, 0x4000
	s_addc_u32 s1, s1, 0
	s_waitcnt vmcnt(63)
	v_lshlrev_b32_e32 v18, 16, v140
	v_and_b32_e32 v19, 0xffff0000, v140
	v_lshlrev_b32_e32 v20, 16, v141
	v_and_b32_e32 v21, 0xffff0000, v141
	v_lshlrev_b32_e32 v22, 16, v142
	v_and_b32_e32 v23, 0xffff0000, v142
	v_lshlrev_b32_e32 v24, 16, v143
	v_and_b32_e32 v25, 0xffff0000, v143
	global_load_dwordx4 v[140:143], v1, s[14:15]
	s_add_u32 s14, s14, 0x4000
	s_addc_u32 s15, s15, 0
	v_fma_f32 v10, v8, v10, v18
	v_fma_f32 v11, v8, v11, v19
	v_fma_f32 v12, v8, v12, v20
	v_fma_f32 v13, v8, v13, v21
	v_fma_f32 v14, v8, v14, v22
	v_fma_f32 v15, v8, v15, v23
	v_fma_f32 v16, v8, v16, v24
	v_fma_f32 v17, v8, v17, v25
	v_cvt_pk_bf16_f32 v26, v10, v11
	v_cvt_pk_bf16_f32 v27, v12, v13
	v_cvt_pk_bf16_f32 v28, v14, v15
	v_cvt_pk_bf16_f32 v29, v16, v17
	global_store_dwordx4 v1, v[26:29], s[0:1]
	s_add_u32 s0, s0, 0x4000
	s_addc_u32 s1, s1, 0
	s_waitcnt vmcnt(63)
; __device__ __forceinline__ unsigned cvt_pk_bf16(float lo, float hi) { unsigned r; asm volatile("v_cvt_pk_bf16_f32 %0, %1, %2" : "=v"(r) : "v"(lo), "v"(hi)); return r; }
; __global__ void __launch_bounds__(512, 2) hse_fwd(Params P) {
;     ...
;                     for (int c = 0; c < 128; c += 32) { float vn[32]; const int cn = c + 32 < 128 ? c + 32 : c;
; #pragma unroll
;                         for (int j = 0; j < 32; ++j) vn[j] = __uint_as_float((unsigned)p[(size_t)(cn + j) * 8192] << 16);
; #pragma unroll
;                         for (int j = 0; j < 32; j += 2) {
;                             const float r0 = run; run = g64 * run + v[j]; const float r1 = run; run = g64 * run + v[j + 1];
;                             const bool odd = lane & 1; const float mine = odd ? r1 : r0, send = odd ? r0 : r1;
;                             const float recv = __int_as_float(__builtin_amdgcn_mov_dpp(__float_as_int(send), 0xB1, 0xF, 0xF, false));
;                             const unsigned w = odd ? cvt_pk_bf16(recv, mine) : cvt_pk_bf16(mine, recv);
;                             *(unsigned*)(pb - (lane & 1) + (size_t)(c + j + (odd ? 1 : 0)) * 8192) = w; }
; #pragma unroll
;                         for (int j = 0; j < 32; ++j) v[j] = vn[j]; }
	v_lshlrev_b32_e32 v18, 16, v144
	v_and_b32_e32 v19, 0xffff0000, v144
	v_lshlrev_b32_e32 v20, 16, v145
	v_and_b32_e32 v21, 0xffff0000, v145
	v_lshlrev_b32_e32 v22, 16, v146
	v_and_b32_e32 v23, 0xffff0000, v146
	v_lshlrev_b32_e32 v24, 16, v147
	v_and_b32_e32 v25, 0xffff0000, v147
	global_load_dwordx4 v[144:147], v1, s[14:15]
	s_add_u32 s14, s14, 0x4000
	s_addc_u32 s15, s15, 0
	v_fma_f32 v10, v8, v10, v18
	v_fma_f32 v11, v8, v11, v19
	v_fma_f32 v12, v8, v12, v20
	v_fma_f32 v13, v8, v13, v21
	v_fma_f32 v14, v8, v14, v22
	v_fma_f32 v15, v8, v15, v23
	v_fma_f32 v16, v8, v16, v24
	v_fma_f32 v17, v8, v17, v25
	v_cvt_pk_bf16_f32 v34, v10, v11
	v_cvt_pk_bf16_f32 v35, v12, v13
	v_cvt_pk_bf16_f32 v36, v14, v15
	v_cvt_pk_bf16_f32 v37, v16, v17
	global_store_dwordx4 v1, v[34:37], s[0:1]
	s_add_u32 s0, s0, 0x4000
	s_addc_u32 s1, s1, 0
	s_waitcnt vmcnt(63)
	v_lshlrev_b32_e32 v18, 16, v148
	v_and_b32_e32 v19, 0xffff0000, v148
	v_lshlrev_b32_e32 v20, 16, v149
	v_and_b32_e32 v21, 0xffff0000, v149
	v_lshlrev_b32_e32 v22, 16, v150
	v_and_b32_e32 v23, 0xffff0000, v150
	v_lshlrev_b32_e32 v24, 16, v151
	v_and_b32_e32 v25, 0xffff0000, v151
	global_load_dwordx4 v[148:151], v1, s[14:15]
	s_add_u32 s14, s14, 0x4000
	s_addc_u32 s15, s15, 0
	v_fma_f32 v10, v8, v10, v18
	v_fma_f32 v11, v8, v11, v19
	v_fma_f32 v12, v8, v12, v20
	v_fma_f32 v13, v8, v13, v21
	v_fma_f32 v14, v8, v14, v22
	v_fma_f32 v15, v8, v15, v23
	v_fma_f32 v16, v8, v16, v24
	v_fma_f32 v17, v8, v17, v25
	v_cvt_pk_bf16_f32 v26, v10, v11
	v_cvt_pk_bf16_f32 v27, v12, v13
	v_cvt_pk_bf16_f32 v28, v14, v15
	v_cvt_pk_bf16_f32 v29, v16, v17
	global_store_dwordx4 v1, v[26:29], s[0:1]
	s_add_u32 s0, s0, 0x4000
	s_addc_u32 s1, s1, 0
	s_waitcnt vmcnt(63)
	v_lshlrev_b32_e32 v18, 16, v152
	v_and_b32_e32 v19, 0xffff0000, v152
	v_lshlrev_b32_e32 v20, 16, v153
	v_and_b32_e32 v21, 0xffff0000, v153
	v_lshlrev_b32_e32 v22, 16, v154
	v_and_b32_e32 v23, 0xffff0000, v154
	v_lshlrev_b32_e32 v24, 16, v155
	v_and_b32_e32 v25, 0xffff0000, v155
	global_load_dwordx4 v[152:155], v1, s[14:15]
	s_add_u32 s14, s14, 0x4000
	s_addc_u32 s15, s15, 0
	v_fma_f32 v10, v8, v10, v18
	v_fma_f32 v11, v8, v11, v19
	v_fma_f32 v12, v8, v12, v20
	v_fma_f32 v13, v8, v13, v21
	v_fma_f32 v14, v8, v14, v22
	v_fma_f32 v15, v8, v15, v23
	v_fma_f32 v16, v8, v16, v24
	v_fma_f32 v17, v8, v17, v25
	v_cvt_pk_bf16_f32 v34, v10, v11
	v_cvt_pk_bf16_f32 v35, v12, v13
	v_cvt_pk_bf16_f32 v36, v14, v15
	v_cvt_pk_bf16_f32 v37, v16, v17
	global_store_dwordx4 v1, v[34:37], s[0:1]
	s_add_u32 s0, s0, 0x4000
	s_addc_u32 s1, s1, 0
	s_waitcnt vmcnt(63)
	v_lshlrev_b32_e32 v18, 16, v156
	v_and_b32_e32 v19, 0xffff0000, v156
	v_lshlrev_b32_e32 v20, 16, v157
	v_and_b32_e32 v21, 0xffff0000, v157
	v_lshlrev_b32_e32 v22, 16, v158
	v_and_b32_e32 v23, 0xffff0000, v158
	v_lshlrev_b32_e32 v24, 16, v159
	v_and_b32_e32 v25, 0xffff0000, v159
	global_load_dwordx4 v[156:159], v1, s[14:15]
	s_add_u32 s14, s14, 0x4000
	s_addc_u32 s15, s15, 0
	v_fma_f32 v10, v8, v10, v18
	v_fma_f32 v11, v8, v11, v19
	v_fma_f32 v12, v8, v12, v20
	v_fma_f32 v13, v8, v13, v21
	v_fma_f32 v14, v8, v14, v22
	v_fma_f32 v15, v8, v15, v23
	v_fma_f32 v16, v8, v16, v24
	v_fma_f32 v17, v8, v17, v25
	v_cvt_pk_bf16_f32 v26, v10, v11
	v_cvt_pk_bf16_f32 v27, v12, v13
	v_cvt_pk_bf16_f32 v28, v14, v15
	v_cvt_pk_bf16_f32 v29, v16, v17
	global_store_dwordx4 v1, v[26:29], s[0:1]
	s_add_u32 s0, s0, 0x4000
	s_addc_u32 s1, s1, 0
	s_waitcnt vmcnt(63)
	v_lshlrev_b32_e32 v18, 16, v160
	v_and_b32_e32 v19, 0xffff0000, v160
	v_lshlrev_b32_e32 v20, 16, v161
	v_and_b32_e32 v21, 0xffff0000, v161
	v_lshlrev_b32_e32 v22, 16, v162
	v_and_b32_e32 v23, 0xffff0000, v162
	v_lshlrev_b32_e32 v24, 16, v163
	v_and_b32_e32 v25, 0xffff0000, v163
	global_load_dwordx4 v[160:163], v1, s[14:15]
	s_add_u32 s14, s14, 0x4000
	s_addc_u32 s15, s15, 0
	v_fma_f32 v10, v8, v10, v18
	v_fma_f32 v11, v8, v11, v19
	v_fma_f32 v12, v8, v12, v20
	v_fma_f32 v13, v8, v13, v21
	v_fma_f32 v14, v8, v14, v22
	v_fma_f32 v15, v8, v15, v23
	v_fma_f32 v16, v8, v16, v24
	v_fma_f32 v17, v8, v17, v25
	v_cvt_pk_bf16_f32 v34, v10, v11
	v_cvt_pk_bf16_f32 v35, v12, v13
	v_cvt_pk_bf16_f32 v36, v14, v15
	v_cvt_pk_bf16_f32 v37, v16, v17
	global_store_dwordx4 v1, v[34:37], s[0:1]
	s_add_u32 s0, s0, 0x4000
	s_addc_u32 s1, s1, 0
	s_waitcnt vmcnt(63)
	v_lshlrev_b32_e32 v18, 16, v164
	v_and_b32_e32 v19, 0xffff0000, v164
	v_lshlrev_b32_e32 v20, 16, v165
	v_and_b32_e32 v21, 0xffff0000, v165
	v_lshlrev_b32_e32 v22, 16, v166
	v_and_b32_e32 v23, 0xffff0000, v166
	v_lshlrev_b32_e32 v24, 16, v167
	v_and_b32_e32 v25, 0xffff0000, v167
	global_load_dwordx4 v[164:167], v1, s[14:15]
	s_add_u32 s14, s14, 0x4000
	s_addc_u32 s15, s15, 0
	v_fma_f32 v10, v8, v10, v18
	v_fma_f32 v11, v8, v11, v19
	v_fma_f32 v12, v8, v12, v20
	v_fma_f32 v13, v8, v13, v21
	v_fma_f32 v14, v8, v14, v22
	v_fma_f32 v15, v8, v15, v23
	v_fma_f32 v16, v8, v16, v24
	v_fma_f32 v17, v8, v17, v25
	v_cvt_pk_bf16_f32 v26, v10, v11
	v_cvt_pk_bf16_f32 v27, v12, v13
	v_cvt_pk_bf16_f32 v28, v14, v15
	v_cvt_pk_bf16_f32 v29, v16, v17
	global_store_dwordx4 v1, v[26:29], s[0:1]
	s_add_u32 s0, s0, 0x4000
	s_addc_u32 s1, s1, 0
	s_waitcnt vmcnt(63)
	v_lshlrev_b32_e32 v18, 16, v40
	v_and_b32_e32 v19, 0xffff0000, v40
	v_lshlrev_b32_e32 v20, 16, v41
	v_and_b32_e32 v21, 0xffff0000, v41
	v_lshlrev_b32_e32 v22, 16, v42
	v_and_b32_e32 v23, 0xffff0000, v42
	v_lshlrev_b32_e32 v24, 16, v43
	v_and_b32_e32 v25, 0xffff0000, v43
	global_load_dwordx4 v[40:43], v1, s[14:15]
	s_add_u32 s14, s14, 0x4000
	s_addc_u32 s15, s15, 0
	v_fma_f32 v10, v8, v10, v18
	v_fma_f32 v11, v8, v11, v19
	v_fma_f32 v12, v8, v12, v20
	v_fma_f32 v13, v8, v13, v21
	v_fma_f32 v14, v8, v14, v22
	v_fma_f32 v15, v8, v15, v23
	v_fma_f32 v16, v8, v16, v24
	v_fma_f32 v17, v8, v17, v25
	v_cvt_pk_bf16_f32 v34, v10, v11
	v_cvt_pk_bf16_f32 v35, v12, v13
	v_cvt_pk_bf16_f32 v36, v14, v15
	v_cvt_pk_bf16_f32 v37, v16, v17
	global_store_dwordx4 v1, v[34:37], s[0:1]
	s_add_u32 s0, s0, 0x4000
	s_addc_u32 s1, s1, 0
	s_waitcnt vmcnt(63)
; __device__ __forceinline__ unsigned cvt_pk_bf16(float lo, float hi) { unsigned r; asm volatile("v_cvt_pk_bf16_f32 %0, %1, %2" : "=v"(r) : "v"(lo), "v"(hi)); return r; }
; __global__ void __launch_bounds__(512, 2) hse_fwd(Params P) {
;     ...
;                     for (int c = 0; c < 128; c += 32) { float vn[32]; const int cn = c + 32 < 128 ? c + 32 : c;
; #pragma unroll
;                         for (int j = 0; j < 32; ++j) vn[j] = __uint_as_float((unsigned)p[(size_t)(cn + j) * 8192] << 16);
; #pragma unroll
;                         for (int j = 0; j < 32; j += 2) {
;                             const float r0 = run; run = g64 * run + v[j]; const float r1 = run; run = g64 * run + v[j + 1];
;                             const bool odd = lane & 1; const float mine = odd ? r1 : r0, send = odd ? r0 : r1;
;                             const float recv = __int_as_float(__builtin_amdgcn_mov_dpp(__float_as_int(send), 0xB1, 0xF, 0xF, false));
;                             const unsigned w = odd ? cvt_pk_bf16(recv, mine) : cvt_pk_bf16(mine, recv);
;                             *(unsigned*)(pb - (lane & 1) + (size_t)(c + j + (odd ? 1 : 0)) * 8192) = w; }
; #pragma unroll
;                         for (int j = 0; j < 32; ++j) v[j] = vn[j]; }
	v_lshlrev_b32_e32 v18, 16, v44
	v_and_b32_e32 v19, 0xffff0000, v44
	v_lshlrev_b32_e32 v20, 16, v45
	v_and_b32_e32 v21, 0xffff0000, v45
	v_lshlrev_b32_e32 v22, 16, v46
	v_and_b32_e32 v23, 0xffff0000, v46
	v_lshlrev_b32_e32 v24, 16, v47
	v_and_b32_e32 v25, 0xffff0000, v47
	global_load_dwordx4 v[44:47], v1, s[14:15]
	s_add_u32 s14, s14, 0x4000
	s_addc_u32 s15, s15, 0
	v_fma_f32 v10, v8, v10, v18
	v_fma_f32 v11, v8, v11, v19
	v_fma_f32 v12, v8, v12, v20
	v_fma_f32 v13, v8, v13, v21
	v_fma_f32 v14, v8, v14, v22
	v_fma_f32 v15, v8, v15, v23
	v_fma_f32 v16, v8, v16, v24
	v_fma_f32 v17, v8, v17, v25
	v_cvt_pk_bf16_f32 v26, v10, v11
	v_cvt_pk_bf16_f32 v27, v12, v13
	v_cvt_pk_bf16_f32 v28, v14, v15
	v_cvt_pk_bf16_f32 v29, v16, v17
	global_store_dwordx4 v1, v[26:29], s[0:1]
	s_add_u32 s0, s0, 0x4000
	s_addc_u32 s1, s1, 0
	s_waitcnt vmcnt(63)
	v_lshlrev_b32_e32 v18, 16, v48
	v_and_b32_e32 v19, 0xffff0000, v48
	v_lshlrev_b32_e32 v20, 16, v49
	v_and_b32_e32 v21, 0xffff0000, v49
	v_lshlrev_b32_e32 v22, 16, v50
	v_and_b32_e32 v23, 0xffff0000, v50
	v_lshlrev_b32_e32 v24, 16, v51
	v_and_b32_e32 v25, 0xffff0000, v51
	global_load_dwordx4 v[48:51], v1, s[14:15]
	s_add_u32 s14, s14, 0x4000
	s_addc_u32 s15, s15, 0
	v_fma_f32 v10, v8, v10, v18
	v_fma_f32 v11, v8, v11, v19
	v_fma_f32 v12, v8, v12, v20
	v_fma_f32 v13, v8, v13, v21
	v_fma_f32 v14, v8, v14, v22
	v_fma_f32 v15, v8, v15, v23
	v_fma_f32 v16, v8, v16, v24
	v_fma_f32 v17, v8, v17, v25
	v_cvt_pk_bf16_f32 v34, v10, v11
	v_cvt_pk_bf16_f32 v35, v12, v13
	v_cvt_pk_bf16_f32 v36, v14, v15
	v_cvt_pk_bf16_f32 v37, v16, v17
	global_store_dwordx4 v1, v[34:37], s[0:1]
	s_add_u32 s0, s0, 0x4000
	s_addc_u32 s1, s1, 0
	s_waitcnt vmcnt(63)
	v_lshlrev_b32_e32 v18, 16, v52
	v_and_b32_e32 v19, 0xffff0000, v52
	v_lshlrev_b32_e32 v20, 16, v53
	v_and_b32_e32 v21, 0xffff0000, v53
	v_lshlrev_b32_e32 v22, 16, v54
	v_and_b32_e32 v23, 0xffff0000, v54
	v_lshlrev_b32_e32 v24, 16, v55
	v_and_b32_e32 v25, 0xffff0000, v55
	global_load_dwordx4 v[52:55], v1, s[14:15]
	s_add_u32 s14, s14, 0x4000
	s_addc_u32 s15, s15, 0
	v_fma_f32 v10, v8, v10, v18
	v_fma_f32 v11, v8, v11, v19
	v_fma_f32 v12, v8, v12, v20
	v_fma_f32 v13, v8, v13, v21
	v_fma_f32 v14, v8, v14, v22
	v_fma_f32 v15, v8, v15, v23
	v_fma_f32 v16, v8, v16, v24
	v_fma_f32 v17, v8, v17, v25
	v_cvt_pk_bf16_f32 v26, v10, v11
	v_cvt_pk_bf16_f32 v27, v12, v13
	v_cvt_pk_bf16_f32 v28, v14, v15
	v_cvt_pk_bf16_f32 v29, v16, v17
	global_store_dwordx4 v1, v[26:29], s[0:1]
	s_add_u32 s0, s0, 0x4000
	s_addc_u32 s1, s1, 0
	s_waitcnt vmcnt(63)
	v_lshlrev_b32_e32 v18, 16, v56
	v_and_b32_e32 v19, 0xffff0000, v56
	v_lshlrev_b32_e32 v20, 16, v57
	v_and_b32_e32 v21, 0xffff0000, v57
	v_lshlrev_b32_e32 v22, 16, v58
	v_and_b32_e32 v23, 0xffff0000, v58
	v_lshlrev_b32_e32 v24, 16, v59
	v_and_b32_e32 v25, 0xffff0000, v59
	global_load_dwordx4 v[56:59], v1, s[14:15]
	s_add_u32 s14, s14, 0x4000
	s_addc_u32 s15, s15, 0
	v_fma_f32 v10, v8, v10, v18
	v_fma_f32 v11, v8, v11, v19
	v_fma_f32 v12, v8, v12, v20
	v_fma_f32 v13, v8, v13, v21
	v_fma_f32 v14, v8, v14, v22
	v_fma_f32 v15, v8, v15, v23
	v_fma_f32 v16, v8, v16, v24
	v_fma_f32 v17, v8, v17, v25
	v_cvt_pk_bf16_f32 v34, v10, v11
	v_cvt_pk_bf16_f32 v35, v12, v13
	v_cvt_pk_bf16_f32 v36, v14, v15
	v_cvt_pk_bf16_f32 v37, v16, v17
	global_store_dwordx4 v1, v[34:37], s[0:1]
	s_add_u32 s0, s0, 0x4000
	s_addc_u32 s1, s1, 0
	s_waitcnt vmcnt(63)
	v_lshlrev_b32_e32 v18, 16, v60
	v_and_b32_e32 v19, 0xffff0000, v60
	v_lshlrev_b32_e32 v20, 16, v61
	v_and_b32_e32 v21, 0xffff0000, v61
	v_lshlrev_b32_e32 v22, 16, v62
	v_and_b32_e32 v23, 0xffff0000, v62
	v_lshlrev_b32_e32 v24, 16, v63
	v_and_b32_e32 v25, 0xffff0000, v63
	global_load_dwordx4 v[60:63], v1, s[14:15]
	s_add_u32 s14, s14, 0x4000
	s_addc_u32 s15, s15, 0
	v_fma_f32 v10, v8, v10, v18
	v_fma_f32 v11, v8, v11, v19
	v_fma_f32 v12, v8, v12, v20
	v_fma_f32 v13, v8, v13, v21
	v_fma_f32 v14, v8, v14, v22
	v_fma_f32 v15, v8, v15, v23
	v_fma_f32 v16, v8, v16, v24
	v_fma_f32 v17, v8, v17, v25
	v_cvt_pk_bf16_f32 v26, v10, v11
	v_cvt_pk_bf16_f32 v27, v12, v13
	v_cvt_pk_bf16_f32 v28, v14, v15
	v_cvt_pk_bf16_f32 v29, v16, v17
	global_store_dwordx4 v1, v[26:29], s[0:1]
	s_add_u32 s0, s0, 0x4000
	s_addc_u32 s1, s1, 0
	s_waitcnt vmcnt(63)
	v_lshlrev_b32_e32 v18, 16, v64
	v_and_b32_e32 v19, 0xffff0000, v64
	v_lshlrev_b32_e32 v20, 16, v65
	v_and_b32_e32 v21, 0xffff0000, v65
	v_lshlrev_b32_e32 v22, 16, v66
	v_and_b32_e32 v23, 0xffff0000, v66
	v_lshlrev_b32_e32 v24, 16, v67
	v_and_b32_e32 v25, 0xffff0000, v67
	global_load_dwordx4 v[64:67], v1, s[14:15]
	s_add_u32 s14, s14, 0x4000
	s_addc_u32 s15, s15, 0
	v_fma_f32 v10, v8, v10, v18
	v_fma_f32 v11, v8, v11, v19
	v_fma_f32 v12, v8, v12, v20
	v_fma_f32 v13, v8, v13, v21
	v_fma_f32 v14, v8, v14, v22
	v_fma_f32 v15, v8, v15, v23
	v_fma_f32 v16, v8, v16, v24
	v_fma_f32 v17, v8, v17, v25
	v_cvt_pk_bf16_f32 v34, v10, v11
	v_cvt_pk_bf16_f32 v35, v12, v13
	v_cvt_pk_bf16_f32 v36, v14, v15
	v_cvt_pk_bf16_f32 v37, v16, v17
	global_store_dwordx4 v1, v[34:37], s[0:1]
	s_add_u32 s0, s0, 0x4000
	s_addc_u32 s1, s1, 0
	s_waitcnt vmcnt(63)
	v_lshlrev_b32_e32 v18, 16, v68
	v_and_b32_e32 v19, 0xffff0000, v68
	v_lshlrev_b32_e32 v20, 16, v69
	v_and_b32_e32 v21, 0xffff0000, v69
	v_lshlrev_b32_e32 v22, 16, v70
	v_and_b32_e32 v23, 0xffff0000, v70
	v_lshlrev_b32_e32 v24, 16, v71
	v_and_b32_e32 v25, 0xffff0000, v71
	global_load_dwordx4 v[68:71], v1, s[14:15]
	s_add_u32 s14, s14, 0x4000
	s_addc_u32 s15, s15, 0
	v_fma_f32 v10, v8, v10, v18
	v_fma_f32 v11, v8, v11, v19
	v_fma_f32 v12, v8, v12, v20
	v_fma_f32 v13, v8, v13, v21
	v_fma_f32 v14, v8, v14, v22
	v_fma_f32 v15, v8, v15, v23
	v_fma_f32 v16, v8, v16, v24
	v_fma_f32 v17, v8, v17, v25
	v_cvt_pk_bf16_f32 v26, v10, v11
	v_cvt_pk_bf16_f32 v27, v12, v13
	v_cvt_pk_bf16_f32 v28, v14, v15
	v_cvt_pk_bf16_f32 v29, v16, v17
	global_store_dwordx4 v1, v[26:29], s[0:1]
	s_add_u32 s0, s0, 0x4000
	s_addc_u32 s1, s1, 0
	s_waitcnt vmcnt(63)
; __device__ __forceinline__ unsigned cvt_pk_bf16(float lo, float hi) { unsigned r; asm volatile("v_cvt_pk_bf16_f32 %0, %1, %2" : "=v"(r) : "v"(lo), "v"(hi)); return r; }
; __global__ void __launch_bounds__(512, 2) hse_fwd(Params P) {
;     ...
;                     for (int c = 0; c < 128; c += 32) { float vn[32]; const int cn = c + 32 < 128 ? c + 32 : c;
; #pragma unroll
;                         for (int j = 0; j < 32; ++j) vn[j] = __uint_as_float((unsigned)p[(size_t)(cn + j) * 8192] << 16);
; #pragma unroll
;                         for (int j = 0; j < 32; j += 2) {
;                             const float r0 = run; run = g64 * run + v[j]; const float r1 = run; run = g64 * run + v[j + 1];
;                             const bool odd = lane & 1; const float mine = odd ? r1 : r0, send = odd ? r0 : r1;
;                             const float recv = __int_as_float(__builtin_amdgcn_mov_dpp(__float_as_int(send), 0xB1, 0xF, 0xF, false));
;                             const unsigned w = odd ? cvt_pk_bf16(recv, mine) : cvt_pk_bf16(mine, recv);
;                             *(unsigned*)(pb - (lane & 1) + (size_t)(c + j + (odd ? 1 : 0)) * 8192) = w; }
; #pragma unroll
;                         for (int j = 0; j < 32; ++j) v[j] = vn[j]; }
	v_lshlrev_b32_e32 v18, 16, v72
	v_and_b32_e32 v19, 0xffff0000, v72
	v_lshlrev_b32_e32 v20, 16, v73
	v_and_b32_e32 v21, 0xffff0000, v73
	v_lshlrev_b32_e32 v22, 16, v74
	v_and_b32_e32 v23, 0xffff0000, v74
	v_lshlrev_b32_e32 v24, 16, v75
	v_and_b32_e32 v25, 0xffff0000, v75
	global_load_dwordx4 v[72:75], v1, s[14:15]
	s_add_u32 s14, s14, 0x4000
	s_addc_u32 s15, s15, 0
	v_fma_f32 v10, v8, v10, v18
	v_fma_f32 v11, v8, v11, v19
	v_fma_f32 v12, v8, v12, v20
	v_fma_f32 v13, v8, v13, v21
	v_fma_f32 v14, v8, v14, v22
	v_fma_f32 v15, v8, v15, v23
	v_fma_f32 v16, v8, v16, v24
	v_fma_f32 v17, v8, v17, v25
	v_cvt_pk_bf16_f32 v34, v10, v11
	v_cvt_pk_bf16_f32 v35, v12, v13
	v_cvt_pk_bf16_f32 v36, v14, v15
	v_cvt_pk_bf16_f32 v37, v16, v17
	global_store_dwordx4 v1, v[34:37], s[0:1]
	s_add_u32 s0, s0, 0x4000
	s_addc_u32 s1, s1, 0
	s_waitcnt vmcnt(63)
	v_lshlrev_b32_e32 v18, 16, v76
	v_and_b32_e32 v19, 0xffff0000, v76
	v_lshlrev_b32_e32 v20, 16, v77
	v_and_b32_e32 v21, 0xffff0000, v77
	v_lshlrev_b32_e32 v22, 16, v78
	v_and_b32_e32 v23, 0xffff0000, v78
	v_lshlrev_b32_e32 v24, 16, v79
	v_and_b32_e32 v25, 0xffff0000, v79
	global_load_dwordx4 v[76:79], v1, s[14:15]
	s_add_u32 s14, s14, 0x4000
	s_addc_u32 s15, s15, 0
	v_fma_f32 v10, v8, v10, v18
	v_fma_f32 v11, v8, v11, v19
	v_fma_f32 v12, v8, v12, v20
	v_fma_f32 v13, v8, v13, v21
	v_fma_f32 v14, v8, v14, v22
	v_fma_f32 v15, v8, v15, v23
	v_fma_f32 v16, v8, v16, v24
	v_fma_f32 v17, v8, v17, v25
	v_cvt_pk_bf16_f32 v26, v10, v11
	v_cvt_pk_bf16_f32 v27, v12, v13
	v_cvt_pk_bf16_f32 v28, v14, v15
	v_cvt_pk_bf16_f32 v29, v16, v17
	global_store_dwordx4 v1, v[26:29], s[0:1]
	s_add_u32 s0, s0, 0x4000
	s_addc_u32 s1, s1, 0
	s_waitcnt vmcnt(63)
	v_lshlrev_b32_e32 v18, 16, v80
	v_and_b32_e32 v19, 0xffff0000, v80
	v_lshlrev_b32_e32 v20, 16, v81
	v_and_b32_e32 v21, 0xffff0000, v81
	v_lshlrev_b32_e32 v22, 16, v82
	v_and_b32_e32 v23, 0xffff0000, v82
	v_lshlrev_b32_e32 v24, 16, v83
	v_and_b32_e32 v25, 0xffff0000, v83
	global_load_dwordx4 v[80:83], v1, s[14:15]
	s_add_u32 s14, s14, 0x4000
	s_addc_u32 s15, s15, 0
	v_fma_f32 v10, v8, v10, v18
	v_fma_f32 v11, v8, v11, v19
	v_fma_f32 v12, v8, v12, v20
	v_fma_f32 v13, v8, v13, v21
	v_fma_f32 v14, v8, v14, v22
	v_fma_f32 v15, v8, v15, v23
	v_fma_f32 v16, v8, v16, v24
	v_fma_f32 v17, v8, v17, v25
	v_cvt_pk_bf16_f32 v34, v10, v11
	v_cvt_pk_bf16_f32 v35, v12, v13
	v_cvt_pk_bf16_f32 v36, v14, v15
	v_cvt_pk_bf16_f32 v37, v16, v17
	global_store_dwordx4 v1, v[34:37], s[0:1]
	s_add_u32 s0, s0, 0x4000
	s_addc_u32 s1, s1, 0
	s_waitcnt vmcnt(63)
	v_lshlrev_b32_e32 v18, 16, v84
	v_and_b32_e32 v19, 0xffff0000, v84
	v_lshlrev_b32_e32 v20, 16, v85
	v_and_b32_e32 v21, 0xffff0000, v85
	v_lshlrev_b32_e32 v22, 16, v86
	v_and_b32_e32 v23, 0xffff0000, v86
	v_lshlrev_b32_e32 v24, 16, v87
	v_and_b32_e32 v25, 0xffff0000, v87
	global_load_dwordx4 v[84:87], v1, s[14:15]
	s_add_u32 s14, s14, 0x4000
	s_addc_u32 s15, s15, 0
	v_fma_f32 v10, v8, v10, v18
	v_fma_f32 v11, v8, v11, v19
	v_fma_f32 v12, v8, v12, v20
	v_fma_f32 v13, v8, v13, v21
	v_fma_f32 v14, v8, v14, v22
	v_fma_f32 v15, v8, v15, v23
	v_fma_f32 v16, v8, v16, v24
	v_fma_f32 v17, v8, v17, v25
	v_cvt_pk_bf16_f32 v26, v10, v11
	v_cvt_pk_bf16_f32 v27, v12, v13
	v_cvt_pk_bf16_f32 v28, v14, v15
	v_cvt_pk_bf16_f32 v29, v16, v17
	global_store_dwordx4 v1, v[26:29], s[0:1]
	s_add_u32 s0, s0, 0x4000
	s_addc_u32 s1, s1, 0
	s_waitcnt vmcnt(63)
	v_lshlrev_b32_e32 v18, 16, v88
	v_and_b32_e32 v19, 0xffff0000, v88
	v_lshlrev_b32_e32 v20, 16, v89
	v_and_b32_e32 v21, 0xffff0000, v89
	v_lshlrev_b32_e32 v22, 16, v90
	v_and_b32_e32 v23, 0xffff0000, v90
	v_lshlrev_b32_e32 v24, 16, v91
	v_and_b32_e32 v25, 0xffff0000, v91
	global_load_dwordx4 v[88:91], v1, s[14:15]
	s_add_u32 s14, s14, 0x4000
	s_addc_u32 s15, s15, 0
	v_fma_f32 v10, v8, v10, v18
	v_fma_f32 v11, v8, v11, v19
	v_fma_f32 v12, v8, v12, v20
	v_fma_f32 v13, v8, v13, v21
	v_fma_f32 v14, v8, v14, v22
	v_fma_f32 v15, v8, v15, v23
	v_fma_f32 v16, v8, v16, v24
	v_fma_f32 v17, v8, v17, v25
	v_cvt_pk_bf16_f32 v34, v10, v11
	v_cvt_pk_bf16_f32 v35, v12, v13
	v_cvt_pk_bf16_f32 v36, v14, v15
	v_cvt_pk_bf16_f32 v37, v16, v17
	global_store_dwordx4 v1, v[34:37], s[0:1]
	s_add_u32 s0, s0, 0x4000
	s_addc_u32 s1, s1, 0
	s_waitcnt vmcnt(63)
	v_lshlrev_b32_e32 v18, 16, v92
	v_and_b32_e32 v19, 0xffff0000, v92
	v_lshlrev_b32_e32 v20, 16, v93
	v_and_b32_e32 v21, 0xffff0000, v93
	v_lshlrev_b32_e32 v22, 16, v94
	v_and_b32_e32 v23, 0xffff0000, v94
	v_lshlrev_b32_e32 v24, 16, v95
	v_and_b32_e32 v25, 0xffff0000, v95
	global_load_dwordx4 v[92:95], v1, s[14:15]
	s_add_u32 s14, s14, 0x4000
	s_addc_u32 s15, s15, 0
	v_fma_f32 v10, v8, v10, v18
	v_fma_f32 v11, v8, v11, v19
	v_fma_f32 v12, v8, v12, v20
	v_fma_f32 v13, v8, v13, v21
	v_fma_f32 v14, v8, v14, v22
	v_fma_f32 v15, v8, v15, v23
	v_fma_f32 v16, v8, v16, v24
	v_fma_f32 v17, v8, v17, v25
	v_cvt_pk_bf16_f32 v26, v10, v11
	v_cvt_pk_bf16_f32 v27, v12, v13
	v_cvt_pk_bf16_f32 v28, v14, v15
	v_cvt_pk_bf16_f32 v29, v16, v17
	global_store_dwordx4 v1, v[26:29], s[0:1]
	s_add_u32 s0, s0, 0x4000
	s_addc_u32 s1, s1, 0
	s_waitcnt vmcnt(63)
	v_lshlrev_b32_e32 v18, 16, v96
	v_and_b32_e32 v19, 0xffff0000, v96
	v_lshlrev_b32_e32 v20, 16, v97
	v_and_b32_e32 v21, 0xffff0000, v97
	v_lshlrev_b32_e32 v22, 16, v98
	v_and_b32_e32 v23, 0xffff0000, v98
	v_lshlrev_b32_e32 v24, 16, v99
	v_and_b32_e32 v25, 0xffff0000, v99
	global_load_dwordx4 v[96:99], v1, s[14:15]
	s_add_u32 s14, s14, 0x4000
	s_addc_u32 s15, s15, 0
	v_fma_f32 v10, v8, v10, v18
	v_fma_f32 v11, v8, v11, v19
	v_fma_f32 v12, v8, v12, v20
	v_fma_f32 v13, v8, v13, v21
	v_fma_f32 v14, v8, v14, v22
	v_fma_f32 v15, v8, v15, v23
	v_fma_f32 v16, v8, v16, v24
	v_fma_f32 v17, v8, v17, v25
	v_cvt_pk_bf16_f32 v34, v10, v11
	v_cvt_pk_bf16_f32 v35, v12, v13
	v_cvt_pk_bf16_f32 v36, v14, v15
	v_cvt_pk_bf16_f32 v37, v16, v17
	global_store_dwordx4 v1, v[34:37], s[0:1]
	s_add_u32 s0, s0, 0x4000
	s_addc_u32 s1, s1, 0
	s_waitcnt vmcnt(63)
; __device__ __forceinline__ unsigned cvt_pk_bf16(float lo, float hi) { unsigned r; asm volatile("v_cvt_pk_bf16_f32 %0, %1, %2" : "=v"(r) : "v"(lo), "v"(hi)); return r; }
; __global__ void __launch_bounds__(512, 2) hse_fwd(Params P) {
;     ...
;                     for (int c = 0; c < 128; c += 32) { float vn[32]; const int cn = c + 32 < 128 ? c + 32 : c;
; #pragma unroll
;                         for (int j = 0; j < 32; ++j) vn[j] = __uint_as_float((unsigned)p[(size_t)(cn + j) * 8192] << 16);
; #pragma unroll
;                         for (int j = 0; j < 32; j += 2) {
;                             const float r0 = run; run = g64 * run + v[j]; const float r1 = run; run = g64 * run + v[j + 1];
;                             const bool odd = lane & 1; const float mine = odd ? r1 : r0, send = odd ? r0 : r1;
;                             const float recv = __int_as_float(__builtin_amdgcn_mov_dpp(__float_as_int(send), 0xB1, 0xF, 0xF, false));
;                             const unsigned w = odd ? cvt_pk_bf16(recv, mine) : cvt_pk_bf16(mine, recv);
;                             *(unsigned*)(pb - (lane & 1) + (size_t)(c + j + (odd ? 1 : 0)) * 8192) = w; }
; #pragma unroll
;                         for (int j = 0; j < 32; ++j) v[j] = vn[j]; }
	v_lshlrev_b32_e32 v18, 16, v100
	v_and_b32_e32 v19, 0xffff0000, v100
	v_lshlrev_b32_e32 v20, 16, v101
	v_and_b32_e32 v21, 0xffff0000, v101
	v_lshlrev_b32_e32 v22, 16, v102
	v_and_b32_e32 v23, 0xffff0000, v102
	v_lshlrev_b32_e32 v24, 16, v103
	v_and_b32_e32 v25, 0xffff0000, v103
	global_load_dwordx4 v[100:103], v1, s[14:15]
	s_add_u32 s14, s14, 0x4000
	s_addc_u32 s15, s15, 0
	v_fma_f32 v10, v8, v10, v18
	v_fma_f32 v11, v8, v11, v19
	v_fma_f32 v12, v8, v12, v20
	v_fma_f32 v13, v8, v13, v21
	v_fma_f32 v14, v8, v14, v22
	v_fma_f32 v15, v8, v15, v23
	v_fma_f32 v16, v8, v16, v24
	v_fma_f32 v17, v8, v17, v25
	v_cvt_pk_bf16_f32 v26, v10, v11
	v_cvt_pk_bf16_f32 v27, v12, v13
	v_cvt_pk_bf16_f32 v28, v14, v15
	v_cvt_pk_bf16_f32 v29, v16, v17
	global_store_dwordx4 v1, v[26:29], s[0:1]
	s_add_u32 s0, s0, 0x4000
	s_addc_u32 s1, s1, 0
	s_waitcnt vmcnt(63)
	v_lshlrev_b32_e32 v18, 16, v104
	v_and_b32_e32 v19, 0xffff0000, v104
	v_lshlrev_b32_e32 v20, 16, v105
	v_and_b32_e32 v21, 0xffff0000, v105
	v_lshlrev_b32_e32 v22, 16, v106
	v_and_b32_e32 v23, 0xffff0000, v106
	v_lshlrev_b32_e32 v24, 16, v107
	v_and_b32_e32 v25, 0xffff0000, v107
	global_load_dwordx4 v[104:107], v1, s[14:15]
	s_add_u32 s14, s14, 0x4000
	s_addc_u32 s15, s15, 0
	v_fma_f32 v10, v8, v10, v18
	v_fma_f32 v11, v8, v11, v19
	v_fma_f32 v12, v8, v12, v20
	v_fma_f32 v13, v8, v13, v21
	v_fma_f32 v14, v8, v14, v22
	v_fma_f32 v15, v8, v15, v23
	v_fma_f32 v16, v8, v16, v24
	v_fma_f32 v17, v8, v17, v25
	v_cvt_pk_bf16_f32 v34, v10, v11
	v_cvt_pk_bf16_f32 v35, v12, v13
	v_cvt_pk_bf16_f32 v36, v14, v15
	v_cvt_pk_bf16_f32 v37, v16, v17
	global_store_dwordx4 v1, v[34:37], s[0:1]
	s_add_u32 s0, s0, 0x4000
	s_addc_u32 s1, s1, 0
	s_waitcnt vmcnt(63)
	v_lshlrev_b32_e32 v18, 16, v108
	v_and_b32_e32 v19, 0xffff0000, v108
	v_lshlrev_b32_e32 v20, 16, v109
	v_and_b32_e32 v21, 0xffff0000, v109
	v_lshlrev_b32_e32 v22, 16, v110
	v_and_b32_e32 v23, 0xffff0000, v110
	v_lshlrev_b32_e32 v24, 16, v111
	v_and_b32_e32 v25, 0xffff0000, v111
	global_load_dwordx4 v[108:111], v1, s[14:15]
	s_add_u32 s14, s14, 0x4000
	s_addc_u32 s15, s15, 0
	v_fma_f32 v10, v8, v10, v18
	v_fma_f32 v11, v8, v11, v19
	v_fma_f32 v12, v8, v12, v20
	v_fma_f32 v13, v8, v13, v21
	v_fma_f32 v14, v8, v14, v22
	v_fma_f32 v15, v8, v15, v23
	v_fma_f32 v16, v8, v16, v24
	v_fma_f32 v17, v8, v17, v25
	v_cvt_pk_bf16_f32 v26, v10, v11
	v_cvt_pk_bf16_f32 v27, v12, v13
	v_cvt_pk_bf16_f32 v28, v14, v15
	v_cvt_pk_bf16_f32 v29, v16, v17
	global_store_dwordx4 v1, v[26:29], s[0:1]
	s_add_u32 s0, s0, 0x4000
	s_addc_u32 s1, s1, 0
	s_waitcnt vmcnt(63)
	v_lshlrev_b32_e32 v18, 16, v112
	v_and_b32_e32 v19, 0xffff0000, v112
	v_lshlrev_b32_e32 v20, 16, v113
	v_and_b32_e32 v21, 0xffff0000, v113
	v_lshlrev_b32_e32 v22, 16, v114
	v_and_b32_e32 v23, 0xffff0000, v114
	v_lshlrev_b32_e32 v24, 16, v115
	v_and_b32_e32 v25, 0xffff0000, v115
	global_load_dwordx4 v[112:115], v1, s[14:15]
	s_add_u32 s14, s14, 0x4000
	s_addc_u32 s15, s15, 0
	v_fma_f32 v10, v8, v10, v18
	v_fma_f32 v11, v8, v11, v19
	v_fma_f32 v12, v8, v12, v20
	v_fma_f32 v13, v8, v13, v21
	v_fma_f32 v14, v8, v14, v22
	v_fma_f32 v15, v8, v15, v23
	v_fma_f32 v16, v8, v16, v24
	v_fma_f32 v17, v8, v17, v25
	v_cvt_pk_bf16_f32 v34, v10, v11
	v_cvt_pk_bf16_f32 v35, v12, v13
	v_cvt_pk_bf16_f32 v36, v14, v15
	v_cvt_pk_bf16_f32 v37, v16, v17
	global_store_dwordx4 v1, v[34:37], s[0:1]
	s_add_u32 s0, s0, 0x4000
	s_addc_u32 s1, s1, 0
	s_waitcnt vmcnt(63)
	v_lshlrev_b32_e32 v18, 16, v116
	v_and_b32_e32 v19, 0xffff0000, v116
	v_lshlrev_b32_e32 v20, 16, v117
	v_and_b32_e32 v21, 0xffff0000, v117
	v_lshlrev_b32_e32 v22, 16, v118
	v_and_b32_e32 v23, 0xffff0000, v118
	v_lshlrev_b32_e32 v24, 16, v119
	v_and_b32_e32 v25, 0xffff0000, v119
	global_load_dwordx4 v[116:119], v1, s[14:15]
	s_add_u32 s14, s14, 0x4000
	s_addc_u32 s15, s15, 0
	v_fma_f32 v10, v8, v10, v18
	v_fma_f32 v11, v8, v11, v19
	v_fma_f32 v12, v8, v12, v20
	v_fma_f32 v13, v8, v13, v21
	v_fma_f32 v14, v8, v14, v22
	v_fma_f32 v15, v8, v15, v23
	v_fma_f32 v16, v8, v16, v24
	v_fma_f32 v17, v8, v17, v25
	v_cvt_pk_bf16_f32 v26, v10, v11
	v_cvt_pk_bf16_f32 v27, v12, v13
	v_cvt_pk_bf16_f32 v28, v14, v15
	v_cvt_pk_bf16_f32 v29, v16, v17
	global_store_dwordx4 v1, v[26:29], s[0:1]
	s_add_u32 s0, s0, 0x4000
	s_addc_u32 s1, s1, 0
	s_waitcnt vmcnt(63)
	v_lshlrev_b32_e32 v18, 16, v120
	v_and_b32_e32 v19, 0xffff0000, v120
	v_lshlrev_b32_e32 v20, 16, v121
	v_and_b32_e32 v21, 0xffff0000, v121
	v_lshlrev_b32_e32 v22, 16, v122
	v_and_b32_e32 v23, 0xffff0000, v122
	v_lshlrev_b32_e32 v24, 16, v123
	v_and_b32_e32 v25, 0xffff0000, v123
	global_load_dwordx4 v[120:123], v1, s[14:15]
	s_add_u32 s14, s14, 0x4000
	s_addc_u32 s15, s15, 0
	v_fma_f32 v10, v8, v10, v18
	v_fma_f32 v11, v8, v11, v19
	v_fma_f32 v12, v8, v12, v20
	v_fma_f32 v13, v8, v13, v21
	v_fma_f32 v14, v8, v14, v22
	v_fma_f32 v15, v8, v15, v23
	v_fma_f32 v16, v8, v16, v24
	v_fma_f32 v17, v8, v17, v25
	v_cvt_pk_bf16_f32 v34, v10, v11
	v_cvt_pk_bf16_f32 v35, v12, v13
	v_cvt_pk_bf16_f32 v36, v14, v15
	v_cvt_pk_bf16_f32 v37, v16, v17
	global_store_dwordx4 v1, v[34:37], s[0:1]
	s_add_u32 s0, s0, 0x4000
	s_addc_u32 s1, s1, 0
	s_waitcnt vmcnt(63)
	v_lshlrev_b32_e32 v18, 16, v124
	v_and_b32_e32 v19, 0xffff0000, v124
	v_lshlrev_b32_e32 v20, 16, v125
	v_and_b32_e32 v21, 0xffff0000, v125
	v_lshlrev_b32_e32 v22, 16, v126
	v_and_b32_e32 v23, 0xffff0000, v126
	v_lshlrev_b32_e32 v24, 16, v127
	v_and_b32_e32 v25, 0xffff0000, v127
	global_load_dwordx4 v[124:127], v1, s[14:15]
	s_add_u32 s14, s14, 0x4000
	s_addc_u32 s15, s15, 0
	v_fma_f32 v10, v8, v10, v18
	v_fma_f32 v11, v8, v11, v19
	v_fma_f32 v12, v8, v12, v20
	v_fma_f32 v13, v8, v13, v21
	v_fma_f32 v14, v8, v14, v22
	v_fma_f32 v15, v8, v15, v23
	v_fma_f32 v16, v8, v16, v24
	v_fma_f32 v17, v8, v17, v25
	v_cvt_pk_bf16_f32 v26, v10, v11
	v_cvt_pk_bf16_f32 v27, v12, v13
	v_cvt_pk_bf16_f32 v28, v14, v15
	v_cvt_pk_bf16_f32 v29, v16, v17
	global_store_dwordx4 v1, v[26:29], s[0:1]
	s_add_u32 s0, s0, 0x4000
	s_addc_u32 s1, s1, 0
	s_waitcnt vmcnt(63)
; __device__ __forceinline__ unsigned cvt_pk_bf16(float lo, float hi) { unsigned r; asm volatile("v_cvt_pk_bf16_f32 %0, %1, %2" : "=v"(r) : "v"(lo), "v"(hi)); return r; }
; __global__ void __launch_bounds__(512, 2) hse_fwd(Params P) {
;     ...
;                     for (int c = 0; c < 128; c += 32) { float vn[32]; const int cn = c + 32 < 128 ? c + 32 : c;
; #pragma unroll
;                         for (int j = 0; j < 32; ++j) vn[j] = __uint_as_float((unsigned)p[(size_t)(cn + j) * 8192] << 16);
; #pragma unroll
;                         for (int j = 0; j < 32; j += 2) {
;                             const float r0 = run; run = g64 * run + v[j]; const float r1 = run; run = g64 * run + v[j + 1];
;                             const bool odd = lane & 1; const float mine = odd ? r1 : r0, send = odd ? r0 : r1;
;                             const float recv = __int_as_float(__builtin_amdgcn_mov_dpp(__float_as_int(send), 0xB1, 0xF, 0xF, false));
;                             const unsigned w = odd ? cvt_pk_bf16(recv, mine) : cvt_pk_bf16(mine, recv);
;                             *(unsigned*)(pb - (lane & 1) + (size_t)(c + j + (odd ? 1 : 0)) * 8192) = w; }
; #pragma unroll
;                         for (int j = 0; j < 32; ++j) v[j] = vn[j]; }
	v_lshlrev_b32_e32 v18, 16, v128
	v_and_b32_e32 v19, 0xffff0000, v128
	v_lshlrev_b32_e32 v20, 16, v129
	v_and_b32_e32 v21, 0xffff0000, v129
	v_lshlrev_b32_e32 v22, 16, v130
	v_and_b32_e32 v23, 0xffff0000, v130
	v_lshlrev_b32_e32 v24, 16, v131
	v_and_b32_e32 v25, 0xffff0000, v131
	global_load_dwordx4 v[128:131], v1, s[14:15]
	s_add_u32 s14, s14, 0x4000
	s_addc_u32 s15, s15, 0
	v_fma_f32 v10, v8, v10, v18
	v_fma_f32 v11, v8, v11, v19
	v_fma_f32 v12, v8, v12, v20
	v_fma_f32 v13, v8, v13, v21
	v_fma_f32 v14, v8, v14, v22
	v_fma_f32 v15, v8, v15, v23
	v_fma_f32 v16, v8, v16, v24
	v_fma_f32 v17, v8, v17, v25
	v_cvt_pk_bf16_f32 v34, v10, v11
	v_cvt_pk_bf16_f32 v35, v12, v13
	v_cvt_pk_bf16_f32 v36, v14, v15
	v_cvt_pk_bf16_f32 v37, v16, v17
	global_store_dwordx4 v1, v[34:37], s[0:1]
	s_add_u32 s0, s0, 0x4000
	s_addc_u32 s1, s1, 0
	s_waitcnt vmcnt(63)
	v_lshlrev_b32_e32 v18, 16, v132
	v_and_b32_e32 v19, 0xffff0000, v132
	v_lshlrev_b32_e32 v20, 16, v133
	v_and_b32_e32 v21, 0xffff0000, v133
	v_lshlrev_b32_e32 v22, 16, v134
	v_and_b32_e32 v23, 0xffff0000, v134
	v_lshlrev_b32_e32 v24, 16, v135
	v_and_b32_e32 v25, 0xffff0000, v135
	global_load_dwordx4 v[132:135], v1, s[14:15]
	s_add_u32 s14, s14, 0x4000
	s_addc_u32 s15, s15, 0
	v_fma_f32 v10, v8, v10, v18
	v_fma_f32 v11, v8, v11, v19
	v_fma_f32 v12, v8, v12, v20
	v_fma_f32 v13, v8, v13, v21
	v_fma_f32 v14, v8, v14, v22
	v_fma_f32 v15, v8, v15, v23
	v_fma_f32 v16, v8, v16, v24
	v_fma_f32 v17, v8, v17, v25
	v_cvt_pk_bf16_f32 v26, v10, v11
	v_cvt_pk_bf16_f32 v27, v12, v13
	v_cvt_pk_bf16_f32 v28, v14, v15
	v_cvt_pk_bf16_f32 v29, v16, v17
	global_store_dwordx4 v1, v[26:29], s[0:1]
	s_add_u32 s0, s0, 0x4000
	s_addc_u32 s1, s1, 0
	s_waitcnt vmcnt(63)
	v_lshlrev_b32_e32 v18, 16, v136
	v_and_b32_e32 v19, 0xffff0000, v136
	v_lshlrev_b32_e32 v20, 16, v137
	v_and_b32_e32 v21, 0xffff0000, v137
	v_lshlrev_b32_e32 v22, 16, v138
	v_and_b32_e32 v23, 0xffff0000, v138
	v_lshlrev_b32_e32 v24, 16, v139
	v_and_b32_e32 v25, 0xffff0000, v139
	global_load_dwordx4 v[136:139], v1, s[14:15]
	s_add_u32 s14, s14, 0x4000
	s_addc_u32 s15, s15, 0
	v_fma_f32 v10, v8, v10, v18
	v_fma_f32 v11, v8, v11, v19
	v_fma_f32 v12, v8, v12, v20
	v_fma_f32 v13, v8, v13, v21
	v_fma_f32 v14, v8, v14, v22
	v_fma_f32 v15, v8, v15, v23
	v_fma_f32 v16, v8, v16, v24
	v_fma_f32 v17, v8, v17, v25
	v_cvt_pk_bf16_f32 v34, v10, v11
	v_cvt_pk_bf16_f32 v35, v12, v13
	v_cvt_pk_bf16_f32 v36, v14, v15
	v_cvt_pk_bf16_f32 v37, v16, v17
	global_store_dwordx4 v1, v[34:37], s[0:1]
	s_add_u32 s0, s0, 0x4000
	s_addc_u32 s1, s1, 0
	s_waitcnt vmcnt(63)
	v_lshlrev_b32_e32 v18, 16, v140
	v_and_b32_e32 v19, 0xffff0000, v140
	v_lshlrev_b32_e32 v20, 16, v141
	v_and_b32_e32 v21, 0xffff0000, v141
	v_lshlrev_b32_e32 v22, 16, v142
	v_and_b32_e32 v23, 0xffff0000, v142
	v_lshlrev_b32_e32 v24, 16, v143
	v_and_b32_e32 v25, 0xffff0000, v143
	global_load_dwordx4 v[140:143], v1, s[14:15]
	s_add_u32 s14, s14, 0x4000
	s_addc_u32 s15, s15, 0
	v_fma_f32 v10, v8, v10, v18
	v_fma_f32 v11, v8, v11, v19
	v_fma_f32 v12, v8, v12, v20
	v_fma_f32 v13, v8, v13, v21
	v_fma_f32 v14, v8, v14, v22
	v_fma_f32 v15, v8, v15, v23
	v_fma_f32 v16, v8, v16, v24
	v_fma_f32 v17, v8, v17, v25
	v_cvt_pk_bf16_f32 v26, v10, v11
	v_cvt_pk_bf16_f32 v27, v12, v13
	v_cvt_pk_bf16_f32 v28, v14, v15
	v_cvt_pk_bf16_f32 v29, v16, v17
	global_store_dwordx4 v1, v[26:29], s[0:1]
	s_add_u32 s0, s0, 0x4000
	s_addc_u32 s1, s1, 0
	s_waitcnt vmcnt(63)
	v_lshlrev_b32_e32 v18, 16, v144
	v_and_b32_e32 v19, 0xffff0000, v144
	v_lshlrev_b32_e32 v20, 16, v145
	v_and_b32_e32 v21, 0xffff0000, v145
	v_lshlrev_b32_e32 v22, 16, v146
	v_and_b32_e32 v23, 0xffff0000, v146
	v_lshlrev_b32_e32 v24, 16, v147
	v_and_b32_e32 v25, 0xffff0000, v147
	global_load_dwordx4 v[144:147], v1, s[14:15]
	s_add_u32 s14, s14, 0x4000
	s_addc_u32 s15, s15, 0
	v_fma_f32 v10, v8, v10, v18
	v_fma_f32 v11, v8, v11, v19
	v_fma_f32 v12, v8, v12, v20
	v_fma_f32 v13, v8, v13, v21
	v_fma_f32 v14, v8, v14, v22
	v_fma_f32 v15, v8, v15, v23
	v_fma_f32 v16, v8, v16, v24
	v_fma_f32 v17, v8, v17, v25
	v_cvt_pk_bf16_f32 v34, v10, v11
	v_cvt_pk_bf16_f32 v35, v12, v13
	v_cvt_pk_bf16_f32 v36, v14, v15
	v_cvt_pk_bf16_f32 v37, v16, v17
	global_store_dwordx4 v1, v[34:37], s[0:1]
	s_add_u32 s0, s0, 0x4000
	s_addc_u32 s1, s1, 0
	s_waitcnt vmcnt(63)
	v_lshlrev_b32_e32 v18, 16, v148
	v_and_b32_e32 v19, 0xffff0000, v148
	v_lshlrev_b32_e32 v20, 16, v149
	v_and_b32_e32 v21, 0xffff0000, v149
	v_lshlrev_b32_e32 v22, 16, v150
	v_and_b32_e32 v23, 0xffff0000, v150
	v_lshlrev_b32_e32 v24, 16, v151
	v_and_b32_e32 v25, 0xffff0000, v151
	global_load_dwordx4 v[148:151], v1, s[14:15]
	s_add_u32 s14, s14, 0x4000
	s_addc_u32 s15, s15, 0
	v_fma_f32 v10, v8, v10, v18
	v_fma_f32 v11, v8, v11, v19
	v_fma_f32 v12, v8, v12, v20
	v_fma_f32 v13, v8, v13, v21
	v_fma_f32 v14, v8, v14, v22
	v_fma_f32 v15, v8, v15, v23
	v_fma_f32 v16, v8, v16, v24
	v_fma_f32 v17, v8, v17, v25
	v_cvt_pk_bf16_f32 v26, v10, v11
	v_cvt_pk_bf16_f32 v27, v12, v13
	v_cvt_pk_bf16_f32 v28, v14, v15
	v_cvt_pk_bf16_f32 v29, v16, v17
	global_store_dwordx4 v1, v[26:29], s[0:1]
	s_add_u32 s0, s0, 0x4000
	s_addc_u32 s1, s1, 0
	s_waitcnt vmcnt(63)
	v_lshlrev_b32_e32 v18, 16, v152
	v_and_b32_e32 v19, 0xffff0000, v152
	v_lshlrev_b32_e32 v20, 16, v153
	v_and_b32_e32 v21, 0xffff0000, v153
	v_lshlrev_b32_e32 v22, 16, v154
	v_and_b32_e32 v23, 0xffff0000, v154
	v_lshlrev_b32_e32 v24, 16, v155
	v_and_b32_e32 v25, 0xffff0000, v155
	global_load_dwordx4 v[152:155], v1, s[14:15]
	s_add_u32 s14, s14, 0x4000
	s_addc_u32 s15, s15, 0
	v_fma_f32 v10, v8, v10, v18
	v_fma_f32 v11, v8, v11, v19
	v_fma_f32 v12, v8, v12, v20
	v_fma_f32 v13, v8, v13, v21
	v_fma_f32 v14, v8, v14, v22
	v_fma_f32 v15, v8, v15, v23
	v_fma_f32 v16, v8, v16, v24
	v_fma_f32 v17, v8, v17, v25
	v_cvt_pk_bf16_f32 v34, v10, v11
	v_cvt_pk_bf16_f32 v35, v12, v13
	v_cvt_pk_bf16_f32 v36, v14, v15
	v_cvt_pk_bf16_f32 v37, v16, v17
	global_store_dwordx4 v1, v[34:37], s[0:1]
	s_add_u32 s0, s0, 0x4000
	s_addc_u32 s1, s1, 0
	s_waitcnt vmcnt(63)
; __device__ __forceinline__ unsigned cvt_pk_bf16(float lo, float hi) { unsigned r; asm volatile("v_cvt_pk_bf16_f32 %0, %1, %2" : "=v"(r) : "v"(lo), "v"(hi)); return r; }
; __global__ void __launch_bounds__(512, 2) hse_fwd(Params P) {
;     ...
;                     for (int c = 0; c < 128; c += 32) { float vn[32]; const int cn = c + 32 < 128 ? c + 32 : c;
; #pragma unroll
;                         for (int j = 0; j < 32; ++j) vn[j] = __uint_as_float((unsigned)p[(size_t)(cn + j) * 8192] << 16);
; #pragma unroll
;                         for (int j = 0; j < 32; j += 2) {
;                             const float r0 = run; run = g64 * run + v[j]; const float r1 = run; run = g64 * run + v[j + 1];
;                             const bool odd = lane & 1; const float mine = odd ? r1 : r0, send = odd ? r0 : r1;
;                             const float recv = __int_as_float(__builtin_amdgcn_mov_dpp(__float_as_int(send), 0xB1, 0xF, 0xF, false));
;                             const unsigned w = odd ? cvt_pk_bf16(recv, mine) : cvt_pk_bf16(mine, recv);
;                             *(unsigned*)(pb - (lane & 1) + (size_t)(c + j + (odd ? 1 : 0)) * 8192) = w; }
; #pragma unroll
;                         for (int j = 0; j < 32; ++j) v[j] = vn[j]; }
	v_lshlrev_b32_e32 v18, 16, v156
	v_and_b32_e32 v19, 0xffff0000, v156
	v_lshlrev_b32_e32 v20, 16, v157
	v_and_b32_e32 v21, 0xffff0000, v157
	v_lshlrev_b32_e32 v22, 16, v158
	v_and_b32_e32 v23, 0xffff0000, v158
	v_lshlrev_b32_e32 v24, 16, v159
	v_and_b32_e32 v25, 0xffff0000, v159
	global_load_dwordx4 v[156:159], v1, s[14:15]
	s_add_u32 s14, s14, 0x4000
	s_addc_u32 s15, s15, 0
	v_fma_f32 v10, v8, v10, v18
	v_fma_f32 v11, v8, v11, v19
	v_fma_f32 v12, v8, v12, v20
	v_fma_f32 v13, v8, v13, v21
	v_fma_f32 v14, v8, v14, v22
	v_fma_f32 v15, v8, v15, v23
	v_fma_f32 v16, v8, v16, v24
	v_fma_f32 v17, v8, v17, v25
	v_cvt_pk_bf16_f32 v26, v10, v11
	v_cvt_pk_bf16_f32 v27, v12, v13
	v_cvt_pk_bf16_f32 v28, v14, v15
	v_cvt_pk_bf16_f32 v29, v16, v17
	global_store_dwordx4 v1, v[26:29], s[0:1]
	s_add_u32 s0, s0, 0x4000
	s_addc_u32 s1, s1, 0
	s_waitcnt vmcnt(63)
	v_lshlrev_b32_e32 v18, 16, v160
	v_and_b32_e32 v19, 0xffff0000, v160
	v_lshlrev_b32_e32 v20, 16, v161
	v_and_b32_e32 v21, 0xffff0000, v161
	v_lshlrev_b32_e32 v22, 16, v162
	v_and_b32_e32 v23, 0xffff0000, v162
	v_lshlrev_b32_e32 v24, 16, v163
	v_and_b32_e32 v25, 0xffff0000, v163
	global_load_dwordx4 v[160:163], v1, s[14:15]
	s_add_u32 s14, s14, 0x4000
	s_addc_u32 s15, s15, 0
	v_fma_f32 v10, v8, v10, v18
	v_fma_f32 v11, v8, v11, v19
	v_fma_f32 v12, v8, v12, v20
	v_fma_f32 v13, v8, v13, v21
	v_fma_f32 v14, v8, v14, v22
	v_fma_f32 v15, v8, v15, v23
	v_fma_f32 v16, v8, v16, v24
	v_fma_f32 v17, v8, v17, v25
	v_cvt_pk_bf16_f32 v34, v10, v11
	v_cvt_pk_bf16_f32 v35, v12, v13
	v_cvt_pk_bf16_f32 v36, v14, v15
	v_cvt_pk_bf16_f32 v37, v16, v17
	global_store_dwordx4 v1, v[34:37], s[0:1]
	s_add_u32 s0, s0, 0x4000
	s_addc_u32 s1, s1, 0
	s_waitcnt vmcnt(63)
	v_lshlrev_b32_e32 v18, 16, v164
	v_and_b32_e32 v19, 0xffff0000, v164
	v_lshlrev_b32_e32 v20, 16, v165
	v_and_b32_e32 v21, 0xffff0000, v165
	v_lshlrev_b32_e32 v22, 16, v166
	v_and_b32_e32 v23, 0xffff0000, v166
	v_lshlrev_b32_e32 v24, 16, v167
	v_and_b32_e32 v25, 0xffff0000, v167
	global_load_dwordx4 v[164:167], v1, s[14:15]
	s_add_u32 s14, s14, 0x4000
	s_addc_u32 s15, s15, 0
	v_fma_f32 v10, v8, v10, v18
	v_fma_f32 v11, v8, v11, v19
	v_fma_f32 v12, v8, v12, v20
	v_fma_f32 v13, v8, v13, v21
	v_fma_f32 v14, v8, v14, v22
	v_fma_f32 v15, v8, v15, v23
	v_fma_f32 v16, v8, v16, v24
	v_fma_f32 v17, v8, v17, v25
	v_cvt_pk_bf16_f32 v26, v10, v11
	v_cvt_pk_bf16_f32 v27, v12, v13
	v_cvt_pk_bf16_f32 v28, v14, v15
	v_cvt_pk_bf16_f32 v29, v16, v17
	global_store_dwordx4 v1, v[26:29], s[0:1]
	s_add_u32 s0, s0, 0x4000
	s_addc_u32 s1, s1, 0
	s_waitcnt vmcnt(63)
	v_lshlrev_b32_e32 v18, 16, v40
	v_and_b32_e32 v19, 0xffff0000, v40
	v_lshlrev_b32_e32 v20, 16, v41
	v_and_b32_e32 v21, 0xffff0000, v41
	v_lshlrev_b32_e32 v22, 16, v42
	v_and_b32_e32 v23, 0xffff0000, v42
	v_lshlrev_b32_e32 v24, 16, v43
	v_and_b32_e32 v25, 0xffff0000, v43
	v_fma_f32 v10, v8, v10, v18
	v_fma_f32 v11, v8, v11, v19
	v_fma_f32 v12, v8, v12, v20
	v_fma_f32 v13, v8, v13, v21
	v_fma_f32 v14, v8, v14, v22
	v_fma_f32 v15, v8, v15, v23
	v_fma_f32 v16, v8, v16, v24
	v_fma_f32 v17, v8, v17, v25
	v_cvt_pk_bf16_f32 v34, v10, v11
	v_cvt_pk_bf16_f32 v35, v12, v13
	v_cvt_pk_bf16_f32 v36, v14, v15
	v_cvt_pk_bf16_f32 v37, v16, v17
	global_store_dwordx4 v1, v[34:37], s[0:1]
	s_add_u32 s0, s0, 0x4000
	s_addc_u32 s1, s1, 0
	s_waitcnt vmcnt(62)
	v_lshlrev_b32_e32 v18, 16, v44
	v_and_b32_e32 v19, 0xffff0000, v44
	v_lshlrev_b32_e32 v20, 16, v45
	v_and_b32_e32 v21, 0xffff0000, v45
	v_lshlrev_b32_e32 v22, 16, v46
	v_and_b32_e32 v23, 0xffff0000, v46
	v_lshlrev_b32_e32 v24, 16, v47
	v_and_b32_e32 v25, 0xffff0000, v47
	v_fma_f32 v10, v8, v10, v18
	v_fma_f32 v11, v8, v11, v19
	v_fma_f32 v12, v8, v12, v20
	v_fma_f32 v13, v8, v13, v21
	v_fma_f32 v14, v8, v14, v22
	v_fma_f32 v15, v8, v15, v23
	v_fma_f32 v16, v8, v16, v24
	v_fma_f32 v17, v8, v17, v25
	v_cvt_pk_bf16_f32 v26, v10, v11
	v_cvt_pk_bf16_f32 v27, v12, v13
	v_cvt_pk_bf16_f32 v28, v14, v15
	v_cvt_pk_bf16_f32 v29, v16, v17
	global_store_dwordx4 v1, v[26:29], s[0:1]
	s_add_u32 s0, s0, 0x4000
	s_addc_u32 s1, s1, 0
	s_waitcnt vmcnt(61)
	v_lshlrev_b32_e32 v18, 16, v48
	v_and_b32_e32 v19, 0xffff0000, v48
	v_lshlrev_b32_e32 v20, 16, v49
	v_and_b32_e32 v21, 0xffff0000, v49
	v_lshlrev_b32_e32 v22, 16, v50
	v_and_b32_e32 v23, 0xffff0000, v50
	v_lshlrev_b32_e32 v24, 16, v51
	v_and_b32_e32 v25, 0xffff0000, v51
	v_fma_f32 v10, v8, v10, v18
	v_fma_f32 v11, v8, v11, v19
	v_fma_f32 v12, v8, v12, v20
	v_fma_f32 v13, v8, v13, v21
	v_fma_f32 v14, v8, v14, v22
	v_fma_f32 v15, v8, v15, v23
	v_fma_f32 v16, v8, v16, v24
	v_fma_f32 v17, v8, v17, v25
	v_cvt_pk_bf16_f32 v34, v10, v11
	v_cvt_pk_bf16_f32 v35, v12, v13
	v_cvt_pk_bf16_f32 v36, v14, v15
	v_cvt_pk_bf16_f32 v37, v16, v17
	global_store_dwordx4 v1, v[34:37], s[0:1]
	s_add_u32 s0, s0, 0x4000
	s_addc_u32 s1, s1, 0
	s_waitcnt vmcnt(60)
	v_lshlrev_b32_e32 v18, 16, v52
	v_and_b32_e32 v19, 0xffff0000, v52
	v_lshlrev_b32_e32 v20, 16, v53
	v_and_b32_e32 v21, 0xffff0000, v53
	v_lshlrev_b32_e32 v22, 16, v54
	v_and_b32_e32 v23, 0xffff0000, v54
	v_lshlrev_b32_e32 v24, 16, v55
	v_and_b32_e32 v25, 0xffff0000, v55
	v_fma_f32 v10, v8, v10, v18
	v_fma_f32 v11, v8, v11, v19
	v_fma_f32 v12, v8, v12, v20
	v_fma_f32 v13, v8, v13, v21
	v_fma_f32 v14, v8, v14, v22
	v_fma_f32 v15, v8, v15, v23
	v_fma_f32 v16, v8, v16, v24
	v_fma_f32 v17, v8, v17, v25
	v_cvt_pk_bf16_f32 v26, v10, v11
	v_cvt_pk_bf16_f32 v27, v12, v13
	v_cvt_pk_bf16_f32 v28, v14, v15
	v_cvt_pk_bf16_f32 v29, v16, v17
	global_store_dwordx4 v1, v[26:29], s[0:1]
	s_add_u32 s0, s0, 0x4000
	s_addc_u32 s1, s1, 0
	s_waitcnt vmcnt(59)
; __device__ __forceinline__ unsigned cvt_pk_bf16(float lo, float hi) { unsigned r; asm volatile("v_cvt_pk_bf16_f32 %0, %1, %2" : "=v"(r) : "v"(lo), "v"(hi)); return r; }
; __global__ void __launch_bounds__(512, 2) hse_fwd(Params P) {
;     ...
;                     for (int c = 0; c < 128; c += 32) { float vn[32]; const int cn = c + 32 < 128 ? c + 32 : c;
; #pragma unroll
;                         for (int j = 0; j < 32; ++j) vn[j] = __uint_as_float((unsigned)p[(size_t)(cn + j) * 8192] << 16);
; #pragma unroll
;                         for (int j = 0; j < 32; j += 2) {
;                             const float r0 = run; run = g64 * run + v[j]; const float r1 = run; run = g64 * run + v[j + 1];
;                             const bool odd = lane & 1; const float mine = odd ? r1 : r0, send = odd ? r0 : r1;
;                             const float recv = __int_as_float(__builtin_amdgcn_mov_dpp(__float_as_int(send), 0xB1, 0xF, 0xF, false));
;                             const unsigned w = odd ? cvt_pk_bf16(recv, mine) : cvt_pk_bf16(mine, recv);
;                             *(unsigned*)(pb - (lane & 1) + (size_t)(c + j + (odd ? 1 : 0)) * 8192) = w; }
; #pragma unroll
;                         for (int j = 0; j < 32; ++j) v[j] = vn[j]; }
	v_lshlrev_b32_e32 v18, 16, v56
	v_and_b32_e32 v19, 0xffff0000, v56
	v_lshlrev_b32_e32 v20, 16, v57
	v_and_b32_e32 v21, 0xffff0000, v57
	v_lshlrev_b32_e32 v22, 16, v58
	v_and_b32_e32 v23, 0xffff0000, v58
	v_lshlrev_b32_e32 v24, 16, v59
	v_and_b32_e32 v25, 0xffff0000, v59
	v_fma_f32 v10, v8, v10, v18
	v_fma_f32 v11, v8, v11, v19
	v_fma_f32 v12, v8, v12, v20
	v_fma_f32 v13, v8, v13, v21
	v_fma_f32 v14, v8, v14, v22
	v_fma_f32 v15, v8, v15, v23
	v_fma_f32 v16, v8, v16, v24
	v_fma_f32 v17, v8, v17, v25
	v_cvt_pk_bf16_f32 v34, v10, v11
	v_cvt_pk_bf16_f32 v35, v12, v13
	v_cvt_pk_bf16_f32 v36, v14, v15
	v_cvt_pk_bf16_f32 v37, v16, v17
	global_store_dwordx4 v1, v[34:37], s[0:1]
	s_add_u32 s0, s0, 0x4000
	s_addc_u32 s1, s1, 0
	s_waitcnt vmcnt(58)
	v_lshlrev_b32_e32 v18, 16, v60
	v_and_b32_e32 v19, 0xffff0000, v60
	v_lshlrev_b32_e32 v20, 16, v61
	v_and_b32_e32 v21, 0xffff0000, v61
	v_lshlrev_b32_e32 v22, 16, v62
	v_and_b32_e32 v23, 0xffff0000, v62
	v_lshlrev_b32_e32 v24, 16, v63
	v_and_b32_e32 v25, 0xffff0000, v63
	v_fma_f32 v10, v8, v10, v18
	v_fma_f32 v11, v8, v11, v19
	v_fma_f32 v12, v8, v12, v20
	v_fma_f32 v13, v8, v13, v21
	v_fma_f32 v14, v8, v14, v22
	v_fma_f32 v15, v8, v15, v23
	v_fma_f32 v16, v8, v16, v24
	v_fma_f32 v17, v8, v17, v25
	v_cvt_pk_bf16_f32 v26, v10, v11
	v_cvt_pk_bf16_f32 v27, v12, v13
	v_cvt_pk_bf16_f32 v28, v14, v15
	v_cvt_pk_bf16_f32 v29, v16, v17
	global_store_dwordx4 v1, v[26:29], s[0:1]
	s_add_u32 s0, s0, 0x4000
	s_addc_u32 s1, s1, 0
	s_waitcnt vmcnt(57)
	v_lshlrev_b32_e32 v18, 16, v64
	v_and_b32_e32 v19, 0xffff0000, v64
	v_lshlrev_b32_e32 v20, 16, v65
	v_and_b32_e32 v21, 0xffff0000, v65
	v_lshlrev_b32_e32 v22, 16, v66
	v_and_b32_e32 v23, 0xffff0000, v66
	v_lshlrev_b32_e32 v24, 16, v67
	v_and_b32_e32 v25, 0xffff0000, v67
	v_fma_f32 v10, v8, v10, v18
	v_fma_f32 v11, v8, v11, v19
	v_fma_f32 v12, v8, v12, v20
	v_fma_f32 v13, v8, v13, v21
	v_fma_f32 v14, v8, v14, v22
	v_fma_f32 v15, v8, v15, v23
	v_fma_f32 v16, v8, v16, v24
	v_fma_f32 v17, v8, v17, v25
	v_cvt_pk_bf16_f32 v34, v10, v11
	v_cvt_pk_bf16_f32 v35, v12, v13
	v_cvt_pk_bf16_f32 v36, v14, v15
	v_cvt_pk_bf16_f32 v37, v16, v17
	global_store_dwordx4 v1, v[34:37], s[0:1]
	s_add_u32 s0, s0, 0x4000
	s_addc_u32 s1, s1, 0
	s_waitcnt vmcnt(56)
	v_lshlrev_b32_e32 v18, 16, v68
	v_and_b32_e32 v19, 0xffff0000, v68
	v_lshlrev_b32_e32 v20, 16, v69
	v_and_b32_e32 v21, 0xffff0000, v69
	v_lshlrev_b32_e32 v22, 16, v70
	v_and_b32_e32 v23, 0xffff0000, v70
	v_lshlrev_b32_e32 v24, 16, v71
	v_and_b32_e32 v25, 0xffff0000, v71
	v_fma_f32 v10, v8, v10, v18
	v_fma_f32 v11, v8, v11, v19
	v_fma_f32 v12, v8, v12, v20
	v_fma_f32 v13, v8, v13, v21
	v_fma_f32 v14, v8, v14, v22
	v_fma_f32 v15, v8, v15, v23
	v_fma_f32 v16, v8, v16, v24
	v_fma_f32 v17, v8, v17, v25
	v_cvt_pk_bf16_f32 v26, v10, v11
	v_cvt_pk_bf16_f32 v27, v12, v13
	v_cvt_pk_bf16_f32 v28, v14, v15
	v_cvt_pk_bf16_f32 v29, v16, v17
	global_store_dwordx4 v1, v[26:29], s[0:1]
	s_add_u32 s0, s0, 0x4000
	s_addc_u32 s1, s1, 0
	s_waitcnt vmcnt(55)
	v_lshlrev_b32_e32 v18, 16, v72
	v_and_b32_e32 v19, 0xffff0000, v72
	v_lshlrev_b32_e32 v20, 16, v73
	v_and_b32_e32 v21, 0xffff0000, v73
	v_lshlrev_b32_e32 v22, 16, v74
	v_and_b32_e32 v23, 0xffff0000, v74
	v_lshlrev_b32_e32 v24, 16, v75
	v_and_b32_e32 v25, 0xffff0000, v75
	v_fma_f32 v10, v8, v10, v18
	v_fma_f32 v11, v8, v11, v19
	v_fma_f32 v12, v8, v12, v20
	v_fma_f32 v13, v8, v13, v21
	v_fma_f32 v14, v8, v14, v22
	v_fma_f32 v15, v8, v15, v23
	v_fma_f32 v16, v8, v16, v24
	v_fma_f32 v17, v8, v17, v25
	v_cvt_pk_bf16_f32 v34, v10, v11
	v_cvt_pk_bf16_f32 v35, v12, v13
	v_cvt_pk_bf16_f32 v36, v14, v15
	v_cvt_pk_bf16_f32 v37, v16, v17
	global_store_dwordx4 v1, v[34:37], s[0:1]
	s_add_u32 s0, s0, 0x4000
	s_addc_u32 s1, s1, 0
	s_waitcnt vmcnt(54)
	v_lshlrev_b32_e32 v18, 16, v76
	v_and_b32_e32 v19, 0xffff0000, v76
	v_lshlrev_b32_e32 v20, 16, v77
	v_and_b32_e32 v21, 0xffff0000, v77
	v_lshlrev_b32_e32 v22, 16, v78
	v_and_b32_e32 v23, 0xffff0000, v78
	v_lshlrev_b32_e32 v24, 16, v79
	v_and_b32_e32 v25, 0xffff0000, v79
	v_fma_f32 v10, v8, v10, v18
	v_fma_f32 v11, v8, v11, v19
	v_fma_f32 v12, v8, v12, v20
	v_fma_f32 v13, v8, v13, v21
	v_fma_f32 v14, v8, v14, v22
	v_fma_f32 v15, v8, v15, v23
	v_fma_f32 v16, v8, v16, v24
	v_fma_f32 v17, v8, v17, v25
	v_cvt_pk_bf16_f32 v26, v10, v11
	v_cvt_pk_bf16_f32 v27, v12, v13
	v_cvt_pk_bf16_f32 v28, v14, v15
	v_cvt_pk_bf16_f32 v29, v16, v17
	global_store_dwordx4 v1, v[26:29], s[0:1]
	s_add_u32 s0, s0, 0x4000
	s_addc_u32 s1, s1, 0
	s_waitcnt vmcnt(53)
	v_lshlrev_b32_e32 v18, 16, v80
	v_and_b32_e32 v19, 0xffff0000, v80
	v_lshlrev_b32_e32 v20, 16, v81
	v_and_b32_e32 v21, 0xffff0000, v81
	v_lshlrev_b32_e32 v22, 16, v82
	v_and_b32_e32 v23, 0xffff0000, v82
	v_lshlrev_b32_e32 v24, 16, v83
	v_and_b32_e32 v25, 0xffff0000, v83
	v_fma_f32 v10, v8, v10, v18
	v_fma_f32 v11, v8, v11, v19
	v_fma_f32 v12, v8, v12, v20
	v_fma_f32 v13, v8, v13, v21
	v_fma_f32 v14, v8, v14, v22
	v_fma_f32 v15, v8, v15, v23
	v_fma_f32 v16, v8, v16, v24
	v_fma_f32 v17, v8, v17, v25
	v_cvt_pk_bf16_f32 v34, v10, v11
	v_cvt_pk_bf16_f32 v35, v12, v13
	v_cvt_pk_bf16_f32 v36, v14, v15
	v_cvt_pk_bf16_f32 v37, v16, v17
	global_store_dwordx4 v1, v[34:37], s[0:1]
	s_add_u32 s0, s0, 0x4000
	s_addc_u32 s1, s1, 0
	s_waitcnt vmcnt(52)
	v_lshlrev_b32_e32 v18, 16, v84
	v_and_b32_e32 v19, 0xffff0000, v84
	v_lshlrev_b32_e32 v20, 16, v85
	v_and_b32_e32 v21, 0xffff0000, v85
	v_lshlrev_b32_e32 v22, 16, v86
	v_and_b32_e32 v23, 0xffff0000, v86
	v_lshlrev_b32_e32 v24, 16, v87
	v_and_b32_e32 v25, 0xffff0000, v87
	v_fma_f32 v10, v8, v10, v18
	v_fma_f32 v11, v8, v11, v19
	v_fma_f32 v12, v8, v12, v20
	v_fma_f32 v13, v8, v13, v21
	v_fma_f32 v14, v8, v14, v22
	v_fma_f32 v15, v8, v15, v23
	v_fma_f32 v16, v8, v16, v24
	v_fma_f32 v17, v8, v17, v25
	v_cvt_pk_bf16_f32 v26, v10, v11
	v_cvt_pk_bf16_f32 v27, v12, v13
	v_cvt_pk_bf16_f32 v28, v14, v15
	v_cvt_pk_bf16_f32 v29, v16, v17
	global_store_dwordx4 v1, v[26:29], s[0:1]
	s_add_u32 s0, s0, 0x4000
	s_addc_u32 s1, s1, 0
	s_waitcnt vmcnt(51)
; __device__ __forceinline__ unsigned cvt_pk_bf16(float lo, float hi) { unsigned r; asm volatile("v_cvt_pk_bf16_f32 %0, %1, %2" : "=v"(r) : "v"(lo), "v"(hi)); return r; }
; __global__ void __launch_bounds__(512, 2) hse_fwd(Params P) {
;     ...
;                     for (int c = 0; c < 128; c += 32) { float vn[32]; const int cn = c + 32 < 128 ? c + 32 : c;
; #pragma unroll
;                         for (int j = 0; j < 32; ++j) vn[j] = __uint_as_float((unsigned)p[(size_t)(cn + j) * 8192] << 16);
; #pragma unroll
;                         for (int j = 0; j < 32; j += 2) {
;                             const float r0 = run; run = g64 * run + v[j]; const float r1 = run; run = g64 * run + v[j + 1];
;                             const bool odd = lane & 1; const float mine = odd ? r1 : r0, send = odd ? r0 : r1;
;                             const float recv = __int_as_float(__builtin_amdgcn_mov_dpp(__float_as_int(send), 0xB1, 0xF, 0xF, false));
;                             const unsigned w = odd ? cvt_pk_bf16(recv, mine) : cvt_pk_bf16(mine, recv);
;                             *(unsigned*)(pb - (lane & 1) + (size_t)(c + j + (odd ? 1 : 0)) * 8192) = w; }
; #pragma unroll
;                         for (int j = 0; j < 32; ++j) v[j] = vn[j]; }
	v_lshlrev_b32_e32 v18, 16, v88
	v_and_b32_e32 v19, 0xffff0000, v88
	v_lshlrev_b32_e32 v20, 16, v89
	v_and_b32_e32 v21, 0xffff0000, v89
	v_lshlrev_b32_e32 v22, 16, v90
	v_and_b32_e32 v23, 0xffff0000, v90
	v_lshlrev_b32_e32 v24, 16, v91
	v_and_b32_e32 v25, 0xffff0000, v91
	v_fma_f32 v10, v8, v10, v18
	v_fma_f32 v11, v8, v11, v19
	v_fma_f32 v12, v8, v12, v20
	v_fma_f32 v13, v8, v13, v21
	v_fma_f32 v14, v8, v14, v22
	v_fma_f32 v15, v8, v15, v23
	v_fma_f32 v16, v8, v16, v24
	v_fma_f32 v17, v8, v17, v25
	v_cvt_pk_bf16_f32 v34, v10, v11
	v_cvt_pk_bf16_f32 v35, v12, v13
	v_cvt_pk_bf16_f32 v36, v14, v15
	v_cvt_pk_bf16_f32 v37, v16, v17
	global_store_dwordx4 v1, v[34:37], s[0:1]
	s_add_u32 s0, s0, 0x4000
	s_addc_u32 s1, s1, 0
	s_waitcnt vmcnt(50)
	v_lshlrev_b32_e32 v18, 16, v92
	v_and_b32_e32 v19, 0xffff0000, v92
	v_lshlrev_b32_e32 v20, 16, v93
	v_and_b32_e32 v21, 0xffff0000, v93
	v_lshlrev_b32_e32 v22, 16, v94
	v_and_b32_e32 v23, 0xffff0000, v94
	v_lshlrev_b32_e32 v24, 16, v95
	v_and_b32_e32 v25, 0xffff0000, v95
	v_fma_f32 v10, v8, v10, v18
	v_fma_f32 v11, v8, v11, v19
	v_fma_f32 v12, v8, v12, v20
	v_fma_f32 v13, v8, v13, v21
	v_fma_f32 v14, v8, v14, v22
	v_fma_f32 v15, v8, v15, v23
	v_fma_f32 v16, v8, v16, v24
	v_fma_f32 v17, v8, v17, v25
	v_cvt_pk_bf16_f32 v26, v10, v11
	v_cvt_pk_bf16_f32 v27, v12, v13
	v_cvt_pk_bf16_f32 v28, v14, v15
	v_cvt_pk_bf16_f32 v29, v16, v17
	global_store_dwordx4 v1, v[26:29], s[0:1]
	s_add_u32 s0, s0, 0x4000
	s_addc_u32 s1, s1, 0
	s_waitcnt vmcnt(49)
	v_lshlrev_b32_e32 v18, 16, v96
	v_and_b32_e32 v19, 0xffff0000, v96
	v_lshlrev_b32_e32 v20, 16, v97
	v_and_b32_e32 v21, 0xffff0000, v97
	v_lshlrev_b32_e32 v22, 16, v98
	v_and_b32_e32 v23, 0xffff0000, v98
	v_lshlrev_b32_e32 v24, 16, v99
	v_and_b32_e32 v25, 0xffff0000, v99
	v_fma_f32 v10, v8, v10, v18
	v_fma_f32 v11, v8, v11, v19
	v_fma_f32 v12, v8, v12, v20
	v_fma_f32 v13, v8, v13, v21
	v_fma_f32 v14, v8, v14, v22
	v_fma_f32 v15, v8, v15, v23
	v_fma_f32 v16, v8, v16, v24
	v_fma_f32 v17, v8, v17, v25
	v_cvt_pk_bf16_f32 v34, v10, v11
	v_cvt_pk_bf16_f32 v35, v12, v13
	v_cvt_pk_bf16_f32 v36, v14, v15
	v_cvt_pk_bf16_f32 v37, v16, v17
	global_store_dwordx4 v1, v[34:37], s[0:1]
	s_add_u32 s0, s0, 0x4000
	s_addc_u32 s1, s1, 0
	s_waitcnt vmcnt(48)
	v_lshlrev_b32_e32 v18, 16, v100
	v_and_b32_e32 v19, 0xffff0000, v100
	v_lshlrev_b32_e32 v20, 16, v101
	v_and_b32_e32 v21, 0xffff0000, v101
	v_lshlrev_b32_e32 v22, 16, v102
	v_and_b32_e32 v23, 0xffff0000, v102
	v_lshlrev_b32_e32 v24, 16, v103
	v_and_b32_e32 v25, 0xffff0000, v103
	v_fma_f32 v10, v8, v10, v18
	v_fma_f32 v11, v8, v11, v19
	v_fma_f32 v12, v8, v12, v20
	v_fma_f32 v13, v8, v13, v21
	v_fma_f32 v14, v8, v14, v22
	v_fma_f32 v15, v8, v15, v23
	v_fma_f32 v16, v8, v16, v24
	v_fma_f32 v17, v8, v17, v25
	v_cvt_pk_bf16_f32 v26, v10, v11
	v_cvt_pk_bf16_f32 v27, v12, v13
	v_cvt_pk_bf16_f32 v28, v14, v15
	v_cvt_pk_bf16_f32 v29, v16, v17
	global_store_dwordx4 v1, v[26:29], s[0:1]
	s_add_u32 s0, s0, 0x4000
	s_addc_u32 s1, s1, 0
	s_waitcnt vmcnt(47)
	v_lshlrev_b32_e32 v18, 16, v104
	v_and_b32_e32 v19, 0xffff0000, v104
	v_lshlrev_b32_e32 v20, 16, v105
	v_and_b32_e32 v21, 0xffff0000, v105
	v_lshlrev_b32_e32 v22, 16, v106
	v_and_b32_e32 v23, 0xffff0000, v106
	v_lshlrev_b32_e32 v24, 16, v107
	v_and_b32_e32 v25, 0xffff0000, v107
	v_fma_f32 v10, v8, v10, v18
	v_fma_f32 v11, v8, v11, v19
	v_fma_f32 v12, v8, v12, v20
	v_fma_f32 v13, v8, v13, v21
	v_fma_f32 v14, v8, v14, v22
	v_fma_f32 v15, v8, v15, v23
	v_fma_f32 v16, v8, v16, v24
	v_fma_f32 v17, v8, v17, v25
	v_cvt_pk_bf16_f32 v34, v10, v11
	v_cvt_pk_bf16_f32 v35, v12, v13
	v_cvt_pk_bf16_f32 v36, v14, v15
	v_cvt_pk_bf16_f32 v37, v16, v17
	global_store_dwordx4 v1, v[34:37], s[0:1]
	s_add_u32 s0, s0, 0x4000
	s_addc_u32 s1, s1, 0
	s_waitcnt vmcnt(46)
	v_lshlrev_b32_e32 v18, 16, v108
	v_and_b32_e32 v19, 0xffff0000, v108
	v_lshlrev_b32_e32 v20, 16, v109
	v_and_b32_e32 v21, 0xffff0000, v109
	v_lshlrev_b32_e32 v22, 16, v110
	v_and_b32_e32 v23, 0xffff0000, v110
	v_lshlrev_b32_e32 v24, 16, v111
	v_and_b32_e32 v25, 0xffff0000, v111
	v_fma_f32 v10, v8, v10, v18
	v_fma_f32 v11, v8, v11, v19
	v_fma_f32 v12, v8, v12, v20
	v_fma_f32 v13, v8, v13, v21
	v_fma_f32 v14, v8, v14, v22
	v_fma_f32 v15, v8, v15, v23
	v_fma_f32 v16, v8, v16, v24
	v_fma_f32 v17, v8, v17, v25
	v_cvt_pk_bf16_f32 v26, v10, v11
	v_cvt_pk_bf16_f32 v27, v12, v13
	v_cvt_pk_bf16_f32 v28, v14, v15
	v_cvt_pk_bf16_f32 v29, v16, v17
	global_store_dwordx4 v1, v[26:29], s[0:1]
	s_add_u32 s0, s0, 0x4000
	s_addc_u32 s1, s1, 0
	s_waitcnt vmcnt(45)
	v_lshlrev_b32_e32 v18, 16, v112
	v_and_b32_e32 v19, 0xffff0000, v112
	v_lshlrev_b32_e32 v20, 16, v113
	v_and_b32_e32 v21, 0xffff0000, v113
	v_lshlrev_b32_e32 v22, 16, v114
	v_and_b32_e32 v23, 0xffff0000, v114
	v_lshlrev_b32_e32 v24, 16, v115
	v_and_b32_e32 v25, 0xffff0000, v115
	v_fma_f32 v10, v8, v10, v18
	v_fma_f32 v11, v8, v11, v19
	v_fma_f32 v12, v8, v12, v20
	v_fma_f32 v13, v8, v13, v21
	v_fma_f32 v14, v8, v14, v22
	v_fma_f32 v15, v8, v15, v23
	v_fma_f32 v16, v8, v16, v24
	v_fma_f32 v17, v8, v17, v25
	v_cvt_pk_bf16_f32 v34, v10, v11
	v_cvt_pk_bf16_f32 v35, v12, v13
	v_cvt_pk_bf16_f32 v36, v14, v15
	v_cvt_pk_bf16_f32 v37, v16, v17
	global_store_dwordx4 v1, v[34:37], s[0:1]
	s_add_u32 s0, s0, 0x4000
	s_addc_u32 s1, s1, 0
	s_waitcnt vmcnt(44)
; __device__ __forceinline__ unsigned cvt_pk_bf16(float lo, float hi) { unsigned r; asm volatile("v_cvt_pk_bf16_f32 %0, %1, %2" : "=v"(r) : "v"(lo), "v"(hi)); return r; }
; __global__ void __launch_bounds__(512, 2) hse_fwd(Params P) {
;     ...
;                     for (int c = 0; c < 128; c += 32) { float vn[32]; const int cn = c + 32 < 128 ? c + 32 : c;
; #pragma unroll
;                         for (int j = 0; j < 32; ++j) vn[j] = __uint_as_float((unsigned)p[(size_t)(cn + j) * 8192] << 16);
; #pragma unroll
;                         for (int j = 0; j < 32; j += 2) {
;                             const float r0 = run; run = g64 * run + v[j]; const float r1 = run; run = g64 * run + v[j + 1];
;                             const bool odd = lane & 1; const float mine = odd ? r1 : r0, send = odd ? r0 : r1;
;                             const float recv = __int_as_float(__builtin_amdgcn_mov_dpp(__float_as_int(send), 0xB1, 0xF, 0xF, false));
;                             const unsigned w = odd ? cvt_pk_bf16(recv, mine) : cvt_pk_bf16(mine, recv);
;                             *(unsigned*)(pb - (lane & 1) + (size_t)(c + j + (odd ? 1 : 0)) * 8192) = w; }
; #pragma unroll
;                         for (int j = 0; j < 32; ++j) v[j] = vn[j]; }
	v_lshlrev_b32_e32 v18, 16, v116
	v_and_b32_e32 v19, 0xffff0000, v116
	v_lshlrev_b32_e32 v20, 16, v117
	v_and_b32_e32 v21, 0xffff0000, v117
	v_lshlrev_b32_e32 v22, 16, v118
	v_and_b32_e32 v23, 0xffff0000, v118
	v_lshlrev_b32_e32 v24, 16, v119
	v_and_b32_e32 v25, 0xffff0000, v119
	v_fma_f32 v10, v8, v10, v18
	v_fma_f32 v11, v8, v11, v19
	v_fma_f32 v12, v8, v12, v20
	v_fma_f32 v13, v8, v13, v21
	v_fma_f32 v14, v8, v14, v22
	v_fma_f32 v15, v8, v15, v23
	v_fma_f32 v16, v8, v16, v24
	v_fma_f32 v17, v8, v17, v25
	v_cvt_pk_bf16_f32 v26, v10, v11
	v_cvt_pk_bf16_f32 v27, v12, v13
	v_cvt_pk_bf16_f32 v28, v14, v15
	v_cvt_pk_bf16_f32 v29, v16, v17
	global_store_dwordx4 v1, v[26:29], s[0:1]
	s_add_u32 s0, s0, 0x4000
	s_addc_u32 s1, s1, 0
	s_waitcnt vmcnt(43)
	v_lshlrev_b32_e32 v18, 16, v120
	v_and_b32_e32 v19, 0xffff0000, v120
	v_lshlrev_b32_e32 v20, 16, v121
	v_and_b32_e32 v21, 0xffff0000, v121
	v_lshlrev_b32_e32 v22, 16, v122
	v_and_b32_e32 v23, 0xffff0000, v122
	v_lshlrev_b32_e32 v24, 16, v123
	v_and_b32_e32 v25, 0xffff0000, v123
	v_fma_f32 v10, v8, v10, v18
	v_fma_f32 v11, v8, v11, v19
	v_fma_f32 v12, v8, v12, v20
	v_fma_f32 v13, v8, v13, v21
	v_fma_f32 v14, v8, v14, v22
	v_fma_f32 v15, v8, v15, v23
	v_fma_f32 v16, v8, v16, v24
	v_fma_f32 v17, v8, v17, v25
	v_cvt_pk_bf16_f32 v34, v10, v11
	v_cvt_pk_bf16_f32 v35, v12, v13
	v_cvt_pk_bf16_f32 v36, v14, v15
	v_cvt_pk_bf16_f32 v37, v16, v17
	global_store_dwordx4 v1, v[34:37], s[0:1]
	s_add_u32 s0, s0, 0x4000
	s_addc_u32 s1, s1, 0
	s_waitcnt vmcnt(42)
	v_lshlrev_b32_e32 v18, 16, v124
	v_and_b32_e32 v19, 0xffff0000, v124
	v_lshlrev_b32_e32 v20, 16, v125
	v_and_b32_e32 v21, 0xffff0000, v125
	v_lshlrev_b32_e32 v22, 16, v126
	v_and_b32_e32 v23, 0xffff0000, v126
	v_lshlrev_b32_e32 v24, 16, v127
	v_and_b32_e32 v25, 0xffff0000, v127
	v_fma_f32 v10, v8, v10, v18
	v_fma_f32 v11, v8, v11, v19
	v_fma_f32 v12, v8, v12, v20
	v_fma_f32 v13, v8, v13, v21
	v_fma_f32 v14, v8, v14, v22
	v_fma_f32 v15, v8, v15, v23
	v_fma_f32 v16, v8, v16, v24
	v_fma_f32 v17, v8, v17, v25
	v_cvt_pk_bf16_f32 v26, v10, v11
	v_cvt_pk_bf16_f32 v27, v12, v13
	v_cvt_pk_bf16_f32 v28, v14, v15
	v_cvt_pk_bf16_f32 v29, v16, v17
	global_store_dwordx4 v1, v[26:29], s[0:1]
	s_add_u32 s0, s0, 0x4000
	s_addc_u32 s1, s1, 0
	s_waitcnt vmcnt(41)
	v_lshlrev_b32_e32 v18, 16, v128
	v_and_b32_e32 v19, 0xffff0000, v128
	v_lshlrev_b32_e32 v20, 16, v129
	v_and_b32_e32 v21, 0xffff0000, v129
	v_lshlrev_b32_e32 v22, 16, v130
	v_and_b32_e32 v23, 0xffff0000, v130
	v_lshlrev_b32_e32 v24, 16, v131
	v_and_b32_e32 v25, 0xffff0000, v131
	v_fma_f32 v10, v8, v10, v18
	v_fma_f32 v11, v8, v11, v19
	v_fma_f32 v12, v8, v12, v20
	v_fma_f32 v13, v8, v13, v21
	v_fma_f32 v14, v8, v14, v22
	v_fma_f32 v15, v8, v15, v23
	v_fma_f32 v16, v8, v16, v24
	v_fma_f32 v17, v8, v17, v25
	v_cvt_pk_bf16_f32 v34, v10, v11
	v_cvt_pk_bf16_f32 v35, v12, v13
	v_cvt_pk_bf16_f32 v36, v14, v15
	v_cvt_pk_bf16_f32 v37, v16, v17
	global_store_dwordx4 v1, v[34:37], s[0:1]
	s_add_u32 s0, s0, 0x4000
	s_addc_u32 s1, s1, 0
	s_waitcnt vmcnt(40)
	v_lshlrev_b32_e32 v18, 16, v132
	v_and_b32_e32 v19, 0xffff0000, v132
	v_lshlrev_b32_e32 v20, 16, v133
	v_and_b32_e32 v21, 0xffff0000, v133
	v_lshlrev_b32_e32 v22, 16, v134
	v_and_b32_e32 v23, 0xffff0000, v134
	v_lshlrev_b32_e32 v24, 16, v135
	v_and_b32_e32 v25, 0xffff0000, v135
	v_fma_f32 v10, v8, v10, v18
	v_fma_f32 v11, v8, v11, v19
	v_fma_f32 v12, v8, v12, v20
	v_fma_f32 v13, v8, v13, v21
	v_fma_f32 v14, v8, v14, v22
	v_fma_f32 v15, v8, v15, v23
	v_fma_f32 v16, v8, v16, v24
	v_fma_f32 v17, v8, v17, v25
	v_cvt_pk_bf16_f32 v26, v10, v11
	v_cvt_pk_bf16_f32 v27, v12, v13
	v_cvt_pk_bf16_f32 v28, v14, v15
	v_cvt_pk_bf16_f32 v29, v16, v17
	global_store_dwordx4 v1, v[26:29], s[0:1]
	s_add_u32 s0, s0, 0x4000
	s_addc_u32 s1, s1, 0
	s_waitcnt vmcnt(39)
	v_lshlrev_b32_e32 v18, 16, v136
	v_and_b32_e32 v19, 0xffff0000, v136
	v_lshlrev_b32_e32 v20, 16, v137
	v_and_b32_e32 v21, 0xffff0000, v137
	v_lshlrev_b32_e32 v22, 16, v138
	v_and_b32_e32 v23, 0xffff0000, v138
	v_lshlrev_b32_e32 v24, 16, v139
	v_and_b32_e32 v25, 0xffff0000, v139
	v_fma_f32 v10, v8, v10, v18
	v_fma_f32 v11, v8, v11, v19
	v_fma_f32 v12, v8, v12, v20
	v_fma_f32 v13, v8, v13, v21
	v_fma_f32 v14, v8, v14, v22
	v_fma_f32 v15, v8, v15, v23
	v_fma_f32 v16, v8, v16, v24
	v_fma_f32 v17, v8, v17, v25
	v_cvt_pk_bf16_f32 v34, v10, v11
	v_cvt_pk_bf16_f32 v35, v12, v13
	v_cvt_pk_bf16_f32 v36, v14, v15
	v_cvt_pk_bf16_f32 v37, v16, v17
	global_store_dwordx4 v1, v[34:37], s[0:1]
	s_add_u32 s0, s0, 0x4000
	s_addc_u32 s1, s1, 0
	s_waitcnt vmcnt(38)
	v_lshlrev_b32_e32 v18, 16, v140
	v_and_b32_e32 v19, 0xffff0000, v140
	v_lshlrev_b32_e32 v20, 16, v141
	v_and_b32_e32 v21, 0xffff0000, v141
	v_lshlrev_b32_e32 v22, 16, v142
	v_and_b32_e32 v23, 0xffff0000, v142
	v_lshlrev_b32_e32 v24, 16, v143
	v_and_b32_e32 v25, 0xffff0000, v143
	v_fma_f32 v10, v8, v10, v18
	v_fma_f32 v11, v8, v11, v19
	v_fma_f32 v12, v8, v12, v20
	v_fma_f32 v13, v8, v13, v21
	v_fma_f32 v14, v8, v14, v22
	v_fma_f32 v15, v8, v15, v23
	v_fma_f32 v16, v8, v16, v24
	v_fma_f32 v17, v8, v17, v25
	v_cvt_pk_bf16_f32 v26, v10, v11
	v_cvt_pk_bf16_f32 v27, v12, v13
	v_cvt_pk_bf16_f32 v28, v14, v15
	v_cvt_pk_bf16_f32 v29, v16, v17
	global_store_dwordx4 v1, v[26:29], s[0:1]
	s_add_u32 s0, s0, 0x4000
	s_addc_u32 s1, s1, 0
	s_waitcnt vmcnt(37)
; __device__ __forceinline__ unsigned cvt_pk_bf16(float lo, float hi) { unsigned r; asm volatile("v_cvt_pk_bf16_f32 %0, %1, %2" : "=v"(r) : "v"(lo), "v"(hi)); return r; }
; __global__ void __launch_bounds__(512, 2) hse_fwd(Params P) {
;     ...
;                         for (int j = 0; j < 32; j += 2) {
;                             const float r0 = run; run = g64 * run + v[j]; const float r1 = run; run = g64 * run + v[j + 1];
;                             const bool odd = lane & 1; const float mine = odd ? r1 : r0, send = odd ? r0 : r1;
;                             const float recv = __int_as_float(__builtin_amdgcn_mov_dpp(__float_as_int(send), 0xB1, 0xF, 0xF, false));
;                             const unsigned w = odd ? cvt_pk_bf16(recv, mine) : cvt_pk_bf16(mine, recv);
;                             *(unsigned*)(pb - (lane & 1) + (size_t)(c + j + (odd ? 1 : 0)) * 8192) = w; }
; #pragma unroll
;                         for (int j = 0; j < 32; ++j) v[j] = vn[j]; }
;                     const int e = idx >> 6, d = idx & 63;
;                     out[O_RET_P + ((((size_t)l * NB + gr.b0 + bl) * 8 + h) * 64 + ((d & 1) * 32 + (d >> 1))) * 128 + e] = run;
	v_lshlrev_b32_e32 v18, 16, v144
	v_and_b32_e32 v19, 0xffff0000, v144
	v_lshlrev_b32_e32 v20, 16, v145
	v_and_b32_e32 v21, 0xffff0000, v145
	v_lshlrev_b32_e32 v22, 16, v146
	v_and_b32_e32 v23, 0xffff0000, v146
	v_lshlrev_b32_e32 v24, 16, v147
	v_and_b32_e32 v25, 0xffff0000, v147
	v_fma_f32 v10, v8, v10, v18
	v_fma_f32 v11, v8, v11, v19
	v_fma_f32 v12, v8, v12, v20
	v_fma_f32 v13, v8, v13, v21
	v_fma_f32 v14, v8, v14, v22
	v_fma_f32 v15, v8, v15, v23
	v_fma_f32 v16, v8, v16, v24
	v_fma_f32 v17, v8, v17, v25
	v_cvt_pk_bf16_f32 v34, v10, v11
	v_cvt_pk_bf16_f32 v35, v12, v13
	v_cvt_pk_bf16_f32 v36, v14, v15
	v_cvt_pk_bf16_f32 v37, v16, v17
	global_store_dwordx4 v1, v[34:37], s[0:1]
	s_add_u32 s0, s0, 0x4000
	s_addc_u32 s1, s1, 0
	s_waitcnt vmcnt(36)
	v_lshlrev_b32_e32 v18, 16, v148
	v_and_b32_e32 v19, 0xffff0000, v148
	v_lshlrev_b32_e32 v20, 16, v149
	v_and_b32_e32 v21, 0xffff0000, v149
	v_lshlrev_b32_e32 v22, 16, v150
	v_and_b32_e32 v23, 0xffff0000, v150
	v_lshlrev_b32_e32 v24, 16, v151
	v_and_b32_e32 v25, 0xffff0000, v151
	v_fma_f32 v10, v8, v10, v18
	v_fma_f32 v11, v8, v11, v19
	v_fma_f32 v12, v8, v12, v20
	v_fma_f32 v13, v8, v13, v21
	v_fma_f32 v14, v8, v14, v22
	v_fma_f32 v15, v8, v15, v23
	v_fma_f32 v16, v8, v16, v24
	v_fma_f32 v17, v8, v17, v25
	v_cvt_pk_bf16_f32 v26, v10, v11
	v_cvt_pk_bf16_f32 v27, v12, v13
	v_cvt_pk_bf16_f32 v28, v14, v15
	v_cvt_pk_bf16_f32 v29, v16, v17
	global_store_dwordx4 v1, v[26:29], s[0:1]
	s_add_u32 s0, s0, 0x4000
	s_addc_u32 s1, s1, 0
	s_waitcnt vmcnt(35)
	v_lshlrev_b32_e32 v18, 16, v152
	v_and_b32_e32 v19, 0xffff0000, v152
	v_lshlrev_b32_e32 v20, 16, v153
	v_and_b32_e32 v21, 0xffff0000, v153
	v_lshlrev_b32_e32 v22, 16, v154
	v_and_b32_e32 v23, 0xffff0000, v154
	v_lshlrev_b32_e32 v24, 16, v155
	v_and_b32_e32 v25, 0xffff0000, v155
	v_fma_f32 v10, v8, v10, v18
	v_fma_f32 v11, v8, v11, v19
	v_fma_f32 v12, v8, v12, v20
	v_fma_f32 v13, v8, v13, v21
	v_fma_f32 v14, v8, v14, v22
	v_fma_f32 v15, v8, v15, v23
	v_fma_f32 v16, v8, v16, v24
	v_fma_f32 v17, v8, v17, v25
	v_cvt_pk_bf16_f32 v34, v10, v11
	v_cvt_pk_bf16_f32 v35, v12, v13
	v_cvt_pk_bf16_f32 v36, v14, v15
	v_cvt_pk_bf16_f32 v37, v16, v17
	global_store_dwordx4 v1, v[34:37], s[0:1]
	s_add_u32 s0, s0, 0x4000
	s_addc_u32 s1, s1, 0
	s_waitcnt vmcnt(34)
	v_lshlrev_b32_e32 v18, 16, v156
	v_and_b32_e32 v19, 0xffff0000, v156
	v_lshlrev_b32_e32 v20, 16, v157
	v_and_b32_e32 v21, 0xffff0000, v157
	v_lshlrev_b32_e32 v22, 16, v158
	v_and_b32_e32 v23, 0xffff0000, v158
	v_lshlrev_b32_e32 v24, 16, v159
	v_and_b32_e32 v25, 0xffff0000, v159
	v_fma_f32 v10, v8, v10, v18
	v_fma_f32 v11, v8, v11, v19
	v_fma_f32 v12, v8, v12, v20
	v_fma_f32 v13, v8, v13, v21
	v_fma_f32 v14, v8, v14, v22
	v_fma_f32 v15, v8, v15, v23
	v_fma_f32 v16, v8, v16, v24
	v_fma_f32 v17, v8, v17, v25
	v_cvt_pk_bf16_f32 v26, v10, v11
	v_cvt_pk_bf16_f32 v27, v12, v13
	v_cvt_pk_bf16_f32 v28, v14, v15
	v_cvt_pk_bf16_f32 v29, v16, v17
	global_store_dwordx4 v1, v[26:29], s[0:1]
	s_add_u32 s0, s0, 0x4000
	s_addc_u32 s1, s1, 0
	s_waitcnt vmcnt(33)
	v_lshlrev_b32_e32 v18, 16, v160
	v_and_b32_e32 v19, 0xffff0000, v160
	v_lshlrev_b32_e32 v20, 16, v161
	v_and_b32_e32 v21, 0xffff0000, v161
	v_lshlrev_b32_e32 v22, 16, v162
	v_and_b32_e32 v23, 0xffff0000, v162
	v_lshlrev_b32_e32 v24, 16, v163
	v_and_b32_e32 v25, 0xffff0000, v163
	v_fma_f32 v10, v8, v10, v18
	v_fma_f32 v11, v8, v11, v19
	v_fma_f32 v12, v8, v12, v20
	v_fma_f32 v13, v8, v13, v21
	v_fma_f32 v14, v8, v14, v22
	v_fma_f32 v15, v8, v15, v23
	v_fma_f32 v16, v8, v16, v24
	v_fma_f32 v17, v8, v17, v25
	v_cvt_pk_bf16_f32 v34, v10, v11
	v_cvt_pk_bf16_f32 v35, v12, v13
	v_cvt_pk_bf16_f32 v36, v14, v15
	v_cvt_pk_bf16_f32 v37, v16, v17
	global_store_dwordx4 v1, v[34:37], s[0:1]
	s_add_u32 s0, s0, 0x4000
	s_addc_u32 s1, s1, 0
	s_waitcnt vmcnt(32)
	v_lshlrev_b32_e32 v18, 16, v164
	v_and_b32_e32 v19, 0xffff0000, v164
	v_lshlrev_b32_e32 v20, 16, v165
	v_and_b32_e32 v21, 0xffff0000, v165
	v_lshlrev_b32_e32 v22, 16, v166
	v_and_b32_e32 v23, 0xffff0000, v166
	v_lshlrev_b32_e32 v24, 16, v167
	v_and_b32_e32 v25, 0xffff0000, v167
	v_fma_f32 v10, v8, v10, v18
	v_fma_f32 v11, v8, v11, v19
	v_fma_f32 v12, v8, v12, v20
	v_fma_f32 v13, v8, v13, v21
	v_fma_f32 v14, v8, v14, v22
	v_fma_f32 v15, v8, v15, v23
	v_fma_f32 v16, v8, v16, v24
	v_fma_f32 v17, v8, v17, v25
	s_add_i32 s26, s74, s17
	s_lshl_b64 s[14:15], s[26:27], 9
	s_lshl_b32 s18, s16, 6
	s_or_b32 s14, s14, s18
	v_bfe_u32 v2, v0, 1, 5
	v_or_b32_e32 v2, s14, v2
	v_mov_b32_e32 v3, s15
	v_lshlrev_b64 v[2:3], 9, v[2:3]
	v_lshl_add_u64 v[2:3], s[6:7], 0, v[2:3]
	v_ashrrev_i32_e32 v26, 6, v0
	v_ashrrev_i32_e32 v27, 31, v26
	v_lshl_add_u64 v[2:3], v[26:27], 2, v[2:3]
	s_mov_b64 s[14:15], 0x17400000
	v_lshl_add_u64 v[2:3], v[2:3], 0, s[14:15]
	s_mov_b64 s[14:15], 0x4000
	v_lshl_add_u64 v[6:7], v[2:3], 0, s[14:15]
	global_store_dword v[2:3], v10, off offset:0
	global_store_dword v[6:7], v11, off offset:0
	global_store_dword v[2:3], v12, off offset:512
	global_store_dword v[6:7], v13, off offset:512
	global_store_dword v[2:3], v14, off offset:1024
	global_store_dword v[6:7], v15, off offset:1024
	global_store_dword v[2:3], v16, off offset:1536
	global_store_dword v[6:7], v17, off offset:1536
.Lscan_idle:
	s_branch .LBB0_4922
.LBB0_5027:
	v_readlane_b32 s0, v255, 45
	s_add_i32 s26, s0, 4
	v_readlane_b32 s0, v253, 6
	v_readlane_b32 s1, v253, 7
	s_cmp_lt_i32 s26, s1
	s_cbranch_scc0 .LBB0_5039
	v_readlane_b32 s0, v255, 2
	s_nop 1
	v_mov_b32_e32 v0, s0
	ds_read_b64 v[0:1], v0
	v_readlane_b32 s0, v253, 8
	s_waitcnt lgkmcnt(0)
	v_readfirstlane_b32 s4, v0
	v_mbcnt_lo_u32_b32 v0, -1, 0
	v_mbcnt_hi_u32_b32 v0, -1, v0
	s_waitcnt vmcnt(0)
	v_readfirstlane_b32 s5, v1
	v_or_b32_e32 v0, s0, v0
	v_cmp_eq_u32_e32 vcc, 0, v0
	s_barrier
	s_and_saveexec_b64 s[0:1], vcc
	v_readlane_b32 s46, v253, 4
	v_readlane_b32 s47, v253, 5
	s_cbranch_execz .LBB0_5077
	v_readlane_b32 s6, v255, 3
	s_waitcnt vmcnt(0) expcnt(0) lgkmcnt(0)
	s_nop 0
	v_mov_b32_e32 v0, s6
	ds_read_b32 v2, v0
	v_readlane_b32 s6, v255, 4
	s_waitcnt lgkmcnt(0)
	v_cmp_ne_u32_e32 vcc, 0, v2
	v_mov_b32_e32 v0, s6
	ds_read_b32 v0, v0
	s_cbranch_vccnz .LBB0_5045
	v_readlane_b32 s6, v253, 2
	v_readlane_b32 s7, v253, 3
	s_load_dwordx2 s[10:11], s[6:7], 0x4
	s_add_u32 s6, s4, 0x1000
	s_addc_u32 s7, s5, 0
	s_add_u32 s8, s4, 0x1100
	s_addc_u32 s9, s5, 0
	v_readlane_b32 s12, v253, 0
	s_waitcnt lgkmcnt(0)
	s_mul_i32 s14, s10, s12
	s_add_u32 s10, s4, 0x1200
	s_mul_i32 s14, s14, s11
	s_addc_u32 s11, s5, 0
	v_readlane_b32 s13, v253, 1
	s_add_u32 s12, s4, 0x1300
	s_addc_u32 s13, s5, 0
	s_mov_b32 s15, 1
	s_branch .LBB0_5032
